# v26 plus: GEMM MFMA blocks reordered so both K-halves of an accumulator issue back to back
# speedup vs baseline: 1.0136x; 1.0028x over previous
.LBB0_185:
	ds_read_b128 v[136:139], v149
	ds_read_b128 v[154:157], v149 offset:1024
	ds_read_b128 v[158:161], v149 offset:2048
	ds_read_b128 v[162:165], v149 offset:3072
	ds_read_b128 v[166:169], v150
	ds_read_b128 v[170:173], v150 offset:1024
	ds_read_b128 v[174:177], v150 offset:2048
	ds_read_b128 v[178:181], v150 offset:3072
	s_cmp_eq_u32 s86, 28
	s_cselect_b32 s54, s80, s84
	s_cselect_b32 s55, s25, s85
	s_cselect_b32 s46, s81, s82
	s_cselect_b32 s47, s19, s83
	s_add_u32 s44, s54, 0x80
	s_addc_u32 s45, s55, 0
	ds_read_b128 v[182:185], v151
	ds_read_b128 v[186:189], v151 offset:1024
	ds_read_b128 v[190:193], v151 offset:2048
	ds_read_b128 v[194:197], v151 offset:3072
	ds_read_b128 v[198:201], v151 offset:4096
	ds_read_b128 v[202:205], v151 offset:5120
	ds_read_b128 v[206:209], v151 offset:6144
	ds_read_b128 v[210:213], v151 offset:7168
	s_mov_b32 m0, s75
	s_nop 0
	global_load_lds_dwordx4 v1, s[40:41] offset:0
	s_nop 0
	s_mov_b32 m0, s76
	s_nop 0
	global_load_lds_dwordx4 v143, s[40:41] offset:0
	s_waitcnt vmcnt(8)
	s_waitcnt lgkmcnt(0)
	s_barrier
	s_setprio 1
	s_waitcnt lgkmcnt(7)
	s_waitcnt lgkmcnt(5)
	s_waitcnt lgkmcnt(3)
	s_waitcnt lgkmcnt(1)
	s_waitcnt lgkmcnt(0)
	v_mfma_f32_16x16x32_bf16 v[126:129], v[136:139], v[182:185], v[126:129]
	v_mfma_f32_16x16x32_bf16 v[126:129], v[154:157], v[186:189], v[126:129]
	v_mfma_f32_16x16x32_bf16 v[122:125], v[158:161], v[182:185], v[122:125]
	v_mfma_f32_16x16x32_bf16 v[122:125], v[162:165], v[186:189], v[122:125]
	v_mfma_f32_16x16x32_bf16 v[114:117], v[136:139], v[190:193], v[114:117]
	v_mfma_f32_16x16x32_bf16 v[114:117], v[154:157], v[194:197], v[114:117]
	v_mfma_f32_16x16x32_bf16 v[106:109], v[158:161], v[190:193], v[106:109]
	v_mfma_f32_16x16x32_bf16 v[106:109], v[162:165], v[194:197], v[106:109]
	v_mfma_f32_16x16x32_bf16 v[98:101], v[136:139], v[198:201], v[98:101]
	v_mfma_f32_16x16x32_bf16 v[98:101], v[154:157], v[202:205], v[98:101]
	v_mfma_f32_16x16x32_bf16 v[90:93], v[158:161], v[198:201], v[90:93]
	v_mfma_f32_16x16x32_bf16 v[90:93], v[162:165], v[202:205], v[90:93]
	v_mfma_f32_16x16x32_bf16 v[82:85], v[136:139], v[206:209], v[82:85]
	v_mfma_f32_16x16x32_bf16 v[82:85], v[154:157], v[210:213], v[82:85]
	v_mfma_f32_16x16x32_bf16 v[74:77], v[158:161], v[206:209], v[74:77]
	v_mfma_f32_16x16x32_bf16 v[74:77], v[162:165], v[210:213], v[74:77]
	s_setprio 0
	s_setprio 1
	v_mfma_f32_16x16x32_bf16 v[118:121], v[166:169], v[182:185], v[118:121]
	v_mfma_f32_16x16x32_bf16 v[118:121], v[170:173], v[186:189], v[118:121]
	v_mfma_f32_16x16x32_bf16 v[110:113], v[174:177], v[182:185], v[110:113]
	v_mfma_f32_16x16x32_bf16 v[110:113], v[178:181], v[186:189], v[110:113]
	v_mfma_f32_16x16x32_bf16 v[102:105], v[166:169], v[190:193], v[102:105]
	v_mfma_f32_16x16x32_bf16 v[102:105], v[170:173], v[194:197], v[102:105]
	v_mfma_f32_16x16x32_bf16 v[94:97], v[174:177], v[190:193], v[94:97]
	v_mfma_f32_16x16x32_bf16 v[94:97], v[178:181], v[194:197], v[94:97]
	v_mfma_f32_16x16x32_bf16 v[86:89], v[166:169], v[198:201], v[86:89]
	v_mfma_f32_16x16x32_bf16 v[86:89], v[170:173], v[202:205], v[86:89]
	v_mfma_f32_16x16x32_bf16 v[78:81], v[174:177], v[198:201], v[78:81]
	v_mfma_f32_16x16x32_bf16 v[78:81], v[178:181], v[202:205], v[78:81]
	v_mfma_f32_16x16x32_bf16 v[70:73], v[166:169], v[206:209], v[70:73]
	v_mfma_f32_16x16x32_bf16 v[70:73], v[170:173], v[210:213], v[70:73]
	v_mfma_f32_16x16x32_bf16 v[66:69], v[174:177], v[206:209], v[66:69]
	v_mfma_f32_16x16x32_bf16 v[66:69], v[178:181], v[210:213], v[66:69]
	s_setprio 0
	s_barrier
	ds_read_b128 v[182:185], v151 offset:16384
	ds_read_b128 v[186:189], v151 offset:17408
	ds_read_b128 v[190:193], v151 offset:18432
	ds_read_b128 v[194:197], v151 offset:19456
	ds_read_b128 v[198:201], v151 offset:20480
	ds_read_b128 v[202:205], v151 offset:21504
	ds_read_b128 v[206:209], v151 offset:22528
	ds_read_b128 v[210:213], v151 offset:23552
	s_mov_b32 m0, s39
	s_nop 0
	global_load_lds_dwordx4 v135, s[46:47] offset:0
	s_add_u32 s30, s46, 0x80000
	s_mov_b32 m0, s58
	s_nop 0
	global_load_lds_dwordx4 v145, s[46:47] offset:0
	s_addc_u32 s31, s47, 0
	s_mov_b32 m0, s59
	s_nop 0
	global_load_lds_dwordx4 v135, s[30:31] offset:0
	s_nop 0
	s_mov_b32 m0, s64
	s_nop 0
	global_load_lds_dwordx4 v145, s[30:31] offset:0
	s_nop 0
	s_mov_b32 m0, s53
	s_nop 0
	global_load_lds_dwordx4 v1, s[54:55] offset:0
	s_nop 0
	s_mov_b32 m0, s65
	s_nop 0
	global_load_lds_dwordx4 v143, s[54:55] offset:0
	s_waitcnt vmcnt(8)
	s_waitcnt lgkmcnt(0)
	s_barrier
	s_setprio 1
	s_waitcnt lgkmcnt(7)
	s_waitcnt lgkmcnt(5)
	s_waitcnt lgkmcnt(3)
	s_waitcnt lgkmcnt(1)
	s_waitcnt lgkmcnt(0)
	v_mfma_f32_16x16x32_bf16 v[62:65], v[136:139], v[182:185], v[62:65]
	v_mfma_f32_16x16x32_bf16 v[62:65], v[154:157], v[186:189], v[62:65]
	v_mfma_f32_16x16x32_bf16 v[58:61], v[158:161], v[182:185], v[58:61]
	v_mfma_f32_16x16x32_bf16 v[58:61], v[162:165], v[186:189], v[58:61]
	v_mfma_f32_16x16x32_bf16 v[50:53], v[136:139], v[190:193], v[50:53]
	v_mfma_f32_16x16x32_bf16 v[50:53], v[154:157], v[194:197], v[50:53]
	v_mfma_f32_16x16x32_bf16 v[42:45], v[158:161], v[190:193], v[42:45]
	v_mfma_f32_16x16x32_bf16 v[42:45], v[162:165], v[194:197], v[42:45]
	v_mfma_f32_16x16x32_bf16 v[34:37], v[136:139], v[198:201], v[34:37]
	v_mfma_f32_16x16x32_bf16 v[34:37], v[154:157], v[202:205], v[34:37]
	v_mfma_f32_16x16x32_bf16 v[26:29], v[158:161], v[198:201], v[26:29]
	v_mfma_f32_16x16x32_bf16 v[26:29], v[162:165], v[202:205], v[26:29]
	v_mfma_f32_16x16x32_bf16 v[18:21], v[136:139], v[206:209], v[18:21]
	v_mfma_f32_16x16x32_bf16 v[18:21], v[154:157], v[210:213], v[18:21]
	v_mfma_f32_16x16x32_bf16 v[10:13], v[158:161], v[206:209], v[10:13]
	v_mfma_f32_16x16x32_bf16 v[10:13], v[162:165], v[210:213], v[10:13]
	s_setprio 0
	s_setprio 1
	v_mfma_f32_16x16x32_bf16 v[54:57], v[166:169], v[182:185], v[54:57]
	v_mfma_f32_16x16x32_bf16 v[54:57], v[170:173], v[186:189], v[54:57]
	v_mfma_f32_16x16x32_bf16 v[46:49], v[174:177], v[182:185], v[46:49]
	v_mfma_f32_16x16x32_bf16 v[46:49], v[178:181], v[186:189], v[46:49]
	v_mfma_f32_16x16x32_bf16 v[38:41], v[166:169], v[190:193], v[38:41]
	v_mfma_f32_16x16x32_bf16 v[38:41], v[170:173], v[194:197], v[38:41]
	v_mfma_f32_16x16x32_bf16 v[30:33], v[174:177], v[190:193], v[30:33]
	v_mfma_f32_16x16x32_bf16 v[30:33], v[178:181], v[194:197], v[30:33]
	v_mfma_f32_16x16x32_bf16 v[22:25], v[166:169], v[198:201], v[22:25]
	v_mfma_f32_16x16x32_bf16 v[22:25], v[170:173], v[202:205], v[22:25]
	v_mfma_f32_16x16x32_bf16 v[14:17], v[174:177], v[198:201], v[14:17]
	v_mfma_f32_16x16x32_bf16 v[14:17], v[178:181], v[202:205], v[14:17]
	v_mfma_f32_16x16x32_bf16 v[6:9], v[166:169], v[206:209], v[6:9]
	v_mfma_f32_16x16x32_bf16 v[6:9], v[170:173], v[210:213], v[6:9]
	v_mfma_f32_16x16x32_bf16 v[2:5], v[174:177], v[206:209], v[2:5]
	v_mfma_f32_16x16x32_bf16 v[2:5], v[178:181], v[210:213], v[2:5]
	s_setprio 0
	s_barrier
; #define PG8_KSETUP() const bool last = (t == nt - 2); const char* a1 = cA + (size_t)(t + 1) * kstep; \
;             const char* a2 = last ? nA : cA + (size_t)(t + 2) * kstep; const char* b2 = last ? nB : cB + (size_t)(t + 2) * kstep; const char* a3 = a2 + kstep; const char* b3 = b2 + kstep; \
;             if (last && has_next) S.a_ready(nxt)
; template <class Epi, class Sched, bool ALIGN_EPI = false, bool SP2 = false>
; __device__ __forceinline__ void gemm_phase(PG8_LAS unsigned char* lds, const Gemm g, const Sched& S, const Epi& E) {
;     ...
;         int t0 = 0;
;         if constexpr (SP2 && Epi::NVM == 16) { if (ui > 0) { const int t = 0; PG8_KSETUP(); PG8_KITER_SP2(24, 24); t0 = 2; } }
;         if constexpr (SP2 && Epi::NVM == 8) { if (ui > 0) { const int t = 0; PG8_KSETUP(); PG8_KITER_SP2(16, 16); t0 = 2; } }
;         for (int t = t0; t < nt; t += 2) {
;             PG8_KSETUP();
;             if constexpr (SP2) {
;             PG8_KITER_SP2(8, 8);
	ds_read_b128 v[136:139], v152
	ds_read_b128 v[154:157], v152 offset:1024
	ds_read_b128 v[158:161], v152 offset:2048
	ds_read_b128 v[162:165], v152 offset:3072
	ds_read_b128 v[166:169], v153
	ds_read_b128 v[170:173], v153 offset:1024
	ds_read_b128 v[174:177], v153 offset:2048
	ds_read_b128 v[178:181], v153 offset:3072
	ds_read_b128 v[182:185], v151 offset:32768
	ds_read_b128 v[186:189], v151 offset:33792
	ds_read_b128 v[190:193], v151 offset:34816
	ds_read_b128 v[194:197], v151 offset:35840
	ds_read_b128 v[198:201], v151 offset:36864
	ds_read_b128 v[202:205], v151 offset:37888
	ds_read_b128 v[206:209], v151 offset:38912
	ds_read_b128 v[210:213], v151 offset:39936
	s_add_u32 s30, s54, 0x80000
	s_addc_u32 s31, s55, 0
	s_mov_b32 m0, s66
	s_nop 0
	global_load_lds_dwordx4 v1, s[30:31] offset:0
	s_nop 0
	s_mov_b32 m0, s67
	s_nop 0
	global_load_lds_dwordx4 v143, s[30:31] offset:0
	s_waitcnt vmcnt(8)
	s_waitcnt lgkmcnt(0)
	s_barrier
	s_setprio 1
	s_waitcnt lgkmcnt(7)
	s_waitcnt lgkmcnt(5)
	s_waitcnt lgkmcnt(3)
	s_waitcnt lgkmcnt(1)
	s_waitcnt lgkmcnt(0)
	v_mfma_f32_16x16x32_bf16 v[126:129], v[136:139], v[182:185], v[126:129]
	v_mfma_f32_16x16x32_bf16 v[126:129], v[154:157], v[186:189], v[126:129]
	v_mfma_f32_16x16x32_bf16 v[122:125], v[158:161], v[182:185], v[122:125]
	v_mfma_f32_16x16x32_bf16 v[122:125], v[162:165], v[186:189], v[122:125]
	v_mfma_f32_16x16x32_bf16 v[114:117], v[136:139], v[190:193], v[114:117]
	v_mfma_f32_16x16x32_bf16 v[114:117], v[154:157], v[194:197], v[114:117]
	v_mfma_f32_16x16x32_bf16 v[106:109], v[158:161], v[190:193], v[106:109]
	v_mfma_f32_16x16x32_bf16 v[106:109], v[162:165], v[194:197], v[106:109]
	v_mfma_f32_16x16x32_bf16 v[98:101], v[136:139], v[198:201], v[98:101]
	v_mfma_f32_16x16x32_bf16 v[98:101], v[154:157], v[202:205], v[98:101]
	v_mfma_f32_16x16x32_bf16 v[90:93], v[158:161], v[198:201], v[90:93]
	v_mfma_f32_16x16x32_bf16 v[90:93], v[162:165], v[202:205], v[90:93]
	v_mfma_f32_16x16x32_bf16 v[82:85], v[136:139], v[206:209], v[82:85]
	v_mfma_f32_16x16x32_bf16 v[82:85], v[154:157], v[210:213], v[82:85]
	v_mfma_f32_16x16x32_bf16 v[74:77], v[158:161], v[206:209], v[74:77]
	v_mfma_f32_16x16x32_bf16 v[74:77], v[162:165], v[210:213], v[74:77]
	s_setprio 0
	s_setprio 1
	v_mfma_f32_16x16x32_bf16 v[118:121], v[166:169], v[182:185], v[118:121]
	v_mfma_f32_16x16x32_bf16 v[118:121], v[170:173], v[186:189], v[118:121]
	v_mfma_f32_16x16x32_bf16 v[110:113], v[174:177], v[182:185], v[110:113]
	v_mfma_f32_16x16x32_bf16 v[110:113], v[178:181], v[186:189], v[110:113]
	v_mfma_f32_16x16x32_bf16 v[102:105], v[166:169], v[190:193], v[102:105]
	v_mfma_f32_16x16x32_bf16 v[102:105], v[170:173], v[194:197], v[102:105]
	v_mfma_f32_16x16x32_bf16 v[94:97], v[174:177], v[190:193], v[94:97]
	v_mfma_f32_16x16x32_bf16 v[94:97], v[178:181], v[194:197], v[94:97]
	v_mfma_f32_16x16x32_bf16 v[86:89], v[166:169], v[198:201], v[86:89]
	v_mfma_f32_16x16x32_bf16 v[86:89], v[170:173], v[202:205], v[86:89]
	v_mfma_f32_16x16x32_bf16 v[78:81], v[174:177], v[198:201], v[78:81]
	v_mfma_f32_16x16x32_bf16 v[78:81], v[178:181], v[202:205], v[78:81]
	v_mfma_f32_16x16x32_bf16 v[70:73], v[166:169], v[206:209], v[70:73]
	v_mfma_f32_16x16x32_bf16 v[70:73], v[170:173], v[210:213], v[70:73]
	v_mfma_f32_16x16x32_bf16 v[66:69], v[174:177], v[206:209], v[66:69]
	v_mfma_f32_16x16x32_bf16 v[66:69], v[178:181], v[210:213], v[66:69]
	s_setprio 0
	s_barrier
	ds_read_b128 v[182:185], v151 offset:49152
	ds_read_b128 v[186:189], v151 offset:50176
	ds_read_b128 v[190:193], v151 offset:51200
	ds_read_b128 v[194:197], v151 offset:52224
	ds_read_b128 v[198:201], v151 offset:53248
	ds_read_b128 v[202:205], v151 offset:54272
	ds_read_b128 v[206:209], v151 offset:55296
	ds_read_b128 v[210:213], v151 offset:56320
	s_add_u32 s30, s46, 0x80
	s_addc_u32 s31, s47, 0
	s_mov_b32 m0, s69
	s_nop 0
	global_load_lds_dwordx4 v135, s[30:31] offset:0
	s_nop 0
	s_mov_b32 m0, s70
	s_nop 0
	global_load_lds_dwordx4 v145, s[30:31] offset:0
	s_add_u32 s30, s46, 0x80080
	s_addc_u32 s31, s47, 0
	s_mov_b32 m0, s73
	s_nop 0
	global_load_lds_dwordx4 v135, s[30:31] offset:0
	s_nop 0
	s_mov_b32 m0, s74
	s_nop 0
	global_load_lds_dwordx4 v145, s[30:31] offset:0
	s_nop 0
	s_mov_b32 m0, s71
	s_nop 0
	global_load_lds_dwordx4 v1, s[44:45] offset:0
	s_nop 0
	s_mov_b32 m0, s72
	s_nop 0
	global_load_lds_dwordx4 v143, s[44:45] offset:0
	s_waitcnt vmcnt(8)
	s_waitcnt lgkmcnt(0)
	s_barrier
	s_setprio 1
	s_waitcnt lgkmcnt(7)
	s_waitcnt lgkmcnt(5)
	s_waitcnt lgkmcnt(3)
	s_waitcnt lgkmcnt(1)
	s_waitcnt lgkmcnt(0)
	v_mfma_f32_16x16x32_bf16 v[62:65], v[136:139], v[182:185], v[62:65]
	v_mfma_f32_16x16x32_bf16 v[62:65], v[154:157], v[186:189], v[62:65]
	v_mfma_f32_16x16x32_bf16 v[58:61], v[158:161], v[182:185], v[58:61]
	v_mfma_f32_16x16x32_bf16 v[58:61], v[162:165], v[186:189], v[58:61]
	v_mfma_f32_16x16x32_bf16 v[50:53], v[136:139], v[190:193], v[50:53]
	v_mfma_f32_16x16x32_bf16 v[50:53], v[154:157], v[194:197], v[50:53]
	v_mfma_f32_16x16x32_bf16 v[42:45], v[158:161], v[190:193], v[42:45]
	v_mfma_f32_16x16x32_bf16 v[42:45], v[162:165], v[194:197], v[42:45]
	v_mfma_f32_16x16x32_bf16 v[34:37], v[136:139], v[198:201], v[34:37]
	v_mfma_f32_16x16x32_bf16 v[34:37], v[154:157], v[202:205], v[34:37]
	v_mfma_f32_16x16x32_bf16 v[26:29], v[158:161], v[198:201], v[26:29]
	v_mfma_f32_16x16x32_bf16 v[26:29], v[162:165], v[202:205], v[26:29]
	v_mfma_f32_16x16x32_bf16 v[18:21], v[136:139], v[206:209], v[18:21]
	v_mfma_f32_16x16x32_bf16 v[18:21], v[154:157], v[210:213], v[18:21]
	v_mfma_f32_16x16x32_bf16 v[10:13], v[158:161], v[206:209], v[10:13]
	v_mfma_f32_16x16x32_bf16 v[10:13], v[162:165], v[210:213], v[10:13]
	s_setprio 0
	s_setprio 1
	v_mfma_f32_16x16x32_bf16 v[54:57], v[166:169], v[182:185], v[54:57]
	v_mfma_f32_16x16x32_bf16 v[54:57], v[170:173], v[186:189], v[54:57]
	v_mfma_f32_16x16x32_bf16 v[46:49], v[174:177], v[182:185], v[46:49]
	v_mfma_f32_16x16x32_bf16 v[46:49], v[178:181], v[186:189], v[46:49]
	v_mfma_f32_16x16x32_bf16 v[38:41], v[166:169], v[190:193], v[38:41]
	v_mfma_f32_16x16x32_bf16 v[38:41], v[170:173], v[194:197], v[38:41]
	v_mfma_f32_16x16x32_bf16 v[30:33], v[174:177], v[190:193], v[30:33]
	v_mfma_f32_16x16x32_bf16 v[30:33], v[178:181], v[194:197], v[30:33]
	v_mfma_f32_16x16x32_bf16 v[22:25], v[166:169], v[198:201], v[22:25]
	v_mfma_f32_16x16x32_bf16 v[22:25], v[170:173], v[202:205], v[22:25]
	v_mfma_f32_16x16x32_bf16 v[14:17], v[174:177], v[198:201], v[14:17]
	v_mfma_f32_16x16x32_bf16 v[14:17], v[178:181], v[202:205], v[14:17]
	v_mfma_f32_16x16x32_bf16 v[6:9], v[166:169], v[206:209], v[6:9]
	v_mfma_f32_16x16x32_bf16 v[6:9], v[170:173], v[210:213], v[6:9]
	v_mfma_f32_16x16x32_bf16 v[2:5], v[174:177], v[206:209], v[2:5]
	v_mfma_f32_16x16x32_bf16 v[2:5], v[178:181], v[210:213], v[2:5]
	s_setprio 0
	s_barrier
	s_add_i32 s86, s86, 2
	s_add_u32 s82, s82, 0x100
	s_addc_u32 s83, s83, 0
	s_add_u32 s84, s84, 0x100
	s_addc_u32 s85, s85, 0
	s_add_u32 s40, s40, 0x100
	s_addc_u32 s41, s41, 0
	s_cmp_gt_u32 s86, 29
	s_cbranch_scc0 .LBB0_185
	s_and_b64 vcc, exec, s[16:17]
	s_cbranch_vccz .LBB0_188
	s_barrier

.LBB0_628:
	ds_read_b128 v[138:141], v147
	ds_read_b128 v[152:155], v147 offset:1024
	ds_read_b128 v[156:159], v147 offset:2048
	ds_read_b128 v[160:163], v147 offset:3072
	ds_read_b128 v[164:167], v148
	ds_read_b128 v[168:171], v148 offset:1024
	ds_read_b128 v[172:175], v148 offset:2048
	ds_read_b128 v[176:179], v148 offset:3072
	s_cmp_eq_u32 s88, 28
	s_cselect_b32 s66, s47, s91
	s_cselect_b32 s67, s39, s92
	s_cselect_b32 s64, s87, s89
	s_cselect_b32 s65, s37, s90
	s_add_u32 s58, s66, 0x80
	s_addc_u32 s59, s67, 0
	ds_read_b128 v[180:183], v149
	ds_read_b128 v[184:187], v149 offset:1024
	ds_read_b128 v[188:191], v149 offset:2048
	ds_read_b128 v[192:195], v149 offset:3072
	ds_read_b128 v[196:199], v149 offset:4096
	ds_read_b128 v[200:203], v149 offset:5120
	ds_read_b128 v[204:207], v149 offset:6144
	ds_read_b128 v[208:211], v149 offset:7168
	s_mov_b32 m0, s81
	s_nop 0
	global_load_lds_dwordx4 v1, s[56:57] offset:0
	s_nop 0
	s_mov_b32 m0, s82
	s_nop 0
	global_load_lds_dwordx4 v143, s[56:57] offset:0
	s_waitcnt vmcnt(8)
	s_waitcnt lgkmcnt(0)
	s_barrier
	s_setprio 1
	s_waitcnt lgkmcnt(7)
	s_waitcnt lgkmcnt(5)
	s_waitcnt lgkmcnt(3)
	s_waitcnt lgkmcnt(1)
	s_waitcnt lgkmcnt(0)
	v_mfma_f32_16x16x32_bf16 v[130:133], v[138:141], v[180:183], v[130:133]
	v_mfma_f32_16x16x32_bf16 v[130:133], v[152:155], v[184:187], v[130:133]
	v_mfma_f32_16x16x32_bf16 v[126:129], v[156:159], v[180:183], v[126:129]
	v_mfma_f32_16x16x32_bf16 v[126:129], v[160:163], v[184:187], v[126:129]
	v_mfma_f32_16x16x32_bf16 v[114:117], v[138:141], v[188:191], v[114:117]
	v_mfma_f32_16x16x32_bf16 v[114:117], v[152:155], v[192:195], v[114:117]
	v_mfma_f32_16x16x32_bf16 v[110:113], v[156:159], v[188:191], v[110:113]
	v_mfma_f32_16x16x32_bf16 v[110:113], v[160:163], v[192:195], v[110:113]
	v_mfma_f32_16x16x32_bf16 v[98:101], v[138:141], v[196:199], v[98:101]
	v_mfma_f32_16x16x32_bf16 v[98:101], v[152:155], v[200:203], v[98:101]
	v_mfma_f32_16x16x32_bf16 v[94:97], v[156:159], v[196:199], v[94:97]
	v_mfma_f32_16x16x32_bf16 v[94:97], v[160:163], v[200:203], v[94:97]
	v_mfma_f32_16x16x32_bf16 v[82:85], v[138:141], v[204:207], v[82:85]
	v_mfma_f32_16x16x32_bf16 v[82:85], v[152:155], v[208:211], v[82:85]
	v_mfma_f32_16x16x32_bf16 v[78:81], v[156:159], v[204:207], v[78:81]
	v_mfma_f32_16x16x32_bf16 v[78:81], v[160:163], v[208:211], v[78:81]
	s_setprio 0
	s_setprio 1
	v_mfma_f32_16x16x32_bf16 v[122:125], v[164:167], v[180:183], v[122:125]
	v_mfma_f32_16x16x32_bf16 v[122:125], v[168:171], v[184:187], v[122:125]
	v_mfma_f32_16x16x32_bf16 v[118:121], v[172:175], v[180:183], v[118:121]
	v_mfma_f32_16x16x32_bf16 v[118:121], v[176:179], v[184:187], v[118:121]
	v_mfma_f32_16x16x32_bf16 v[106:109], v[164:167], v[188:191], v[106:109]
	v_mfma_f32_16x16x32_bf16 v[106:109], v[168:171], v[192:195], v[106:109]
	v_mfma_f32_16x16x32_bf16 v[102:105], v[172:175], v[188:191], v[102:105]
	v_mfma_f32_16x16x32_bf16 v[102:105], v[176:179], v[192:195], v[102:105]
	v_mfma_f32_16x16x32_bf16 v[90:93], v[164:167], v[196:199], v[90:93]
	v_mfma_f32_16x16x32_bf16 v[90:93], v[168:171], v[200:203], v[90:93]
	v_mfma_f32_16x16x32_bf16 v[86:89], v[172:175], v[196:199], v[86:89]
	v_mfma_f32_16x16x32_bf16 v[86:89], v[176:179], v[200:203], v[86:89]
	v_mfma_f32_16x16x32_bf16 v[74:77], v[164:167], v[204:207], v[74:77]
	v_mfma_f32_16x16x32_bf16 v[74:77], v[168:171], v[208:211], v[74:77]
	v_mfma_f32_16x16x32_bf16 v[70:73], v[172:175], v[204:207], v[70:73]
	v_mfma_f32_16x16x32_bf16 v[70:73], v[176:179], v[208:211], v[70:73]
	s_setprio 0
	s_barrier
	ds_read_b128 v[180:183], v149 offset:16384
	ds_read_b128 v[184:187], v149 offset:17408
	ds_read_b128 v[188:191], v149 offset:18432
	ds_read_b128 v[192:195], v149 offset:19456
	ds_read_b128 v[196:199], v149 offset:20480
	ds_read_b128 v[200:203], v149 offset:21504
	ds_read_b128 v[204:207], v149 offset:22528
	ds_read_b128 v[208:211], v149 offset:23552
	s_mov_b32 m0, s52
	s_nop 0
	global_load_lds_dwordx4 v142, s[64:65] offset:0
	s_add_u32 s30, s64, 0x80000
	s_mov_b32 m0, s53
	s_nop 0
	global_load_lds_dwordx4 v144, s[64:65] offset:0
	s_addc_u32 s31, s65, 0
	s_mov_b32 m0, s55
	s_nop 0
	global_load_lds_dwordx4 v142, s[30:31] offset:0
	s_nop 0
	s_mov_b32 m0, s68
	s_nop 0
	global_load_lds_dwordx4 v144, s[30:31] offset:0
	s_nop 0
	s_mov_b32 m0, s33
	s_nop 0
	global_load_lds_dwordx4 v1, s[66:67] offset:0
	s_nop 0
	s_mov_b32 m0, s69
	s_nop 0
	global_load_lds_dwordx4 v143, s[66:67] offset:0
	s_waitcnt vmcnt(8)
	s_waitcnt lgkmcnt(0)
	s_barrier
	s_setprio 1
	s_waitcnt lgkmcnt(7)
	s_waitcnt lgkmcnt(5)
	s_waitcnt lgkmcnt(3)
	s_waitcnt lgkmcnt(1)
	s_waitcnt lgkmcnt(0)
	v_mfma_f32_16x16x32_bf16 v[66:69], v[138:141], v[180:183], v[66:69]
	v_mfma_f32_16x16x32_bf16 v[66:69], v[152:155], v[184:187], v[66:69]
	v_mfma_f32_16x16x32_bf16 v[62:65], v[156:159], v[180:183], v[62:65]
	v_mfma_f32_16x16x32_bf16 v[62:65], v[160:163], v[184:187], v[62:65]
	v_mfma_f32_16x16x32_bf16 v[50:53], v[138:141], v[188:191], v[50:53]
	v_mfma_f32_16x16x32_bf16 v[50:53], v[152:155], v[192:195], v[50:53]
	v_mfma_f32_16x16x32_bf16 v[46:49], v[156:159], v[188:191], v[46:49]
	v_mfma_f32_16x16x32_bf16 v[46:49], v[160:163], v[192:195], v[46:49]
	v_mfma_f32_16x16x32_bf16 v[34:37], v[138:141], v[196:199], v[34:37]
	v_mfma_f32_16x16x32_bf16 v[34:37], v[152:155], v[200:203], v[34:37]
	v_mfma_f32_16x16x32_bf16 v[30:33], v[156:159], v[196:199], v[30:33]
	v_mfma_f32_16x16x32_bf16 v[30:33], v[160:163], v[200:203], v[30:33]
	v_mfma_f32_16x16x32_bf16 v[18:21], v[138:141], v[204:207], v[18:21]
	v_mfma_f32_16x16x32_bf16 v[18:21], v[152:155], v[208:211], v[18:21]
	v_mfma_f32_16x16x32_bf16 v[14:17], v[156:159], v[204:207], v[14:17]
	v_mfma_f32_16x16x32_bf16 v[14:17], v[160:163], v[208:211], v[14:17]
	s_setprio 0
	s_setprio 1
	v_mfma_f32_16x16x32_bf16 v[58:61], v[164:167], v[180:183], v[58:61]
	v_mfma_f32_16x16x32_bf16 v[54:57], v[172:175], v[180:183], v[54:57]
	v_mfma_f32_16x16x32_bf16 v[42:45], v[164:167], v[188:191], v[42:45]
	v_mfma_f32_16x16x32_bf16 v[38:41], v[172:175], v[188:191], v[38:41]
	v_mfma_f32_16x16x32_bf16 v[26:29], v[164:167], v[196:199], v[26:29]
	v_mfma_f32_16x16x32_bf16 v[22:25], v[172:175], v[196:199], v[22:25]
	v_mfma_f32_16x16x32_bf16 v[10:13], v[164:167], v[204:207], v[10:13]
	v_mfma_f32_16x16x32_bf16 v[4:7], v[172:175], v[204:207], v[6:9]
	v_mfma_f32_16x16x32_bf16 v[58:61], v[168:171], v[184:187], v[58:61]
	v_mfma_f32_16x16x32_bf16 v[54:57], v[176:179], v[184:187], v[54:57]
	v_mfma_f32_16x16x32_bf16 v[42:45], v[168:171], v[192:195], v[42:45]
	v_mfma_f32_16x16x32_bf16 v[38:41], v[176:179], v[192:195], v[38:41]
	v_mfma_f32_16x16x32_bf16 v[26:29], v[168:171], v[200:203], v[26:29]
	v_mfma_f32_16x16x32_bf16 v[22:25], v[176:179], v[200:203], v[22:25]
	v_mfma_f32_16x16x32_bf16 v[10:13], v[168:171], v[208:211], v[10:13]
	v_mfma_f32_16x16x32_bf16 v[4:7], v[176:179], v[208:211], v[4:7]
	s_setprio 0
	s_barrier
	ds_read_b128 v[138:141], v150
	ds_read_b128 v[152:155], v150 offset:1024
	ds_read_b128 v[156:159], v150 offset:2048
	ds_read_b128 v[160:163], v150 offset:3072
	ds_read_b128 v[164:167], v151
	ds_read_b128 v[168:171], v151 offset:1024
	ds_read_b128 v[172:175], v151 offset:2048
	ds_read_b128 v[176:179], v151 offset:3072
	ds_read_b128 v[180:183], v149 offset:32768
	ds_read_b128 v[184:187], v149 offset:33792
	ds_read_b128 v[188:191], v149 offset:34816
	ds_read_b128 v[192:195], v149 offset:35840
	ds_read_b128 v[196:199], v149 offset:36864
	ds_read_b128 v[200:203], v149 offset:37888
	ds_read_b128 v[204:207], v149 offset:38912
	ds_read_b128 v[208:211], v149 offset:39936
	s_add_u32 s30, s66, 0x80000
	s_addc_u32 s31, s67, 0
	s_mov_b32 m0, s70
	s_nop 0
	global_load_lds_dwordx4 v1, s[30:31] offset:0
	s_nop 0
	s_mov_b32 m0, s71
	s_nop 0
	global_load_lds_dwordx4 v143, s[30:31] offset:0
	s_waitcnt vmcnt(8)
	s_waitcnt lgkmcnt(0)
	s_barrier
	s_setprio 1
	s_waitcnt lgkmcnt(7)
	s_waitcnt lgkmcnt(5)
	s_waitcnt lgkmcnt(3)
	s_waitcnt lgkmcnt(1)
	s_waitcnt lgkmcnt(0)
	v_mfma_f32_16x16x32_bf16 v[130:133], v[138:141], v[180:183], v[130:133]
	v_mfma_f32_16x16x32_bf16 v[130:133], v[152:155], v[184:187], v[130:133]
	v_mfma_f32_16x16x32_bf16 v[126:129], v[156:159], v[180:183], v[126:129]
	v_mfma_f32_16x16x32_bf16 v[126:129], v[160:163], v[184:187], v[126:129]
	v_mfma_f32_16x16x32_bf16 v[114:117], v[138:141], v[188:191], v[114:117]
	v_mfma_f32_16x16x32_bf16 v[114:117], v[152:155], v[192:195], v[114:117]
	v_mfma_f32_16x16x32_bf16 v[110:113], v[156:159], v[188:191], v[110:113]
	v_mfma_f32_16x16x32_bf16 v[110:113], v[160:163], v[192:195], v[110:113]
	v_mfma_f32_16x16x32_bf16 v[98:101], v[138:141], v[196:199], v[98:101]
	v_mfma_f32_16x16x32_bf16 v[98:101], v[152:155], v[200:203], v[98:101]
	v_mfma_f32_16x16x32_bf16 v[94:97], v[156:159], v[196:199], v[94:97]
	v_mfma_f32_16x16x32_bf16 v[94:97], v[160:163], v[200:203], v[94:97]
	v_mfma_f32_16x16x32_bf16 v[82:85], v[138:141], v[204:207], v[82:85]
	v_mfma_f32_16x16x32_bf16 v[82:85], v[152:155], v[208:211], v[82:85]
	v_mfma_f32_16x16x32_bf16 v[78:81], v[156:159], v[204:207], v[78:81]
	v_mfma_f32_16x16x32_bf16 v[78:81], v[160:163], v[208:211], v[78:81]
	s_setprio 0
	s_setprio 1
	v_mfma_f32_16x16x32_bf16 v[122:125], v[164:167], v[180:183], v[122:125]
	v_mfma_f32_16x16x32_bf16 v[122:125], v[168:171], v[184:187], v[122:125]
	v_mfma_f32_16x16x32_bf16 v[118:121], v[172:175], v[180:183], v[118:121]
	v_mfma_f32_16x16x32_bf16 v[118:121], v[176:179], v[184:187], v[118:121]
	v_mfma_f32_16x16x32_bf16 v[106:109], v[164:167], v[188:191], v[106:109]
	v_mfma_f32_16x16x32_bf16 v[106:109], v[168:171], v[192:195], v[106:109]
	v_mfma_f32_16x16x32_bf16 v[102:105], v[172:175], v[188:191], v[102:105]
	v_mfma_f32_16x16x32_bf16 v[102:105], v[176:179], v[192:195], v[102:105]
	v_mfma_f32_16x16x32_bf16 v[90:93], v[164:167], v[196:199], v[90:93]
	v_mfma_f32_16x16x32_bf16 v[90:93], v[168:171], v[200:203], v[90:93]
	v_mfma_f32_16x16x32_bf16 v[86:89], v[172:175], v[196:199], v[86:89]
	v_mfma_f32_16x16x32_bf16 v[86:89], v[176:179], v[200:203], v[86:89]
	v_mfma_f32_16x16x32_bf16 v[74:77], v[164:167], v[204:207], v[74:77]
	v_mfma_f32_16x16x32_bf16 v[74:77], v[168:171], v[208:211], v[74:77]
	v_mfma_f32_16x16x32_bf16 v[70:73], v[172:175], v[204:207], v[70:73]
	v_mfma_f32_16x16x32_bf16 v[70:73], v[176:179], v[208:211], v[70:73]
	s_setprio 0
	s_barrier
; #define PG8_KSETUP() const bool last = (t == nt - 2); const char* a1 = cA + (size_t)(t + 1) * kstep; \
;             const char* a2 = last ? nA : cA + (size_t)(t + 2) * kstep; const char* b2 = last ? nB : cB + (size_t)(t + 2) * kstep; const char* a3 = a2 + kstep; const char* b3 = b2 + kstep; \
;             if (last && has_next) S.a_ready(nxt)
; template <class Epi, class Sched, bool ALIGN_EPI = false, bool SP2 = false>
; __device__ __forceinline__ void gemm_phase(PG8_LAS unsigned char* lds, const Gemm g, const Sched& S, const Epi& E) {
;     ...
;         int t0 = 0;
;         if constexpr (SP2 && Epi::NVM == 16) { if (ui > 0) { const int t = 0; PG8_KSETUP(); PG8_KITER_SP2(24, 24); t0 = 2; } }
;         if constexpr (SP2 && Epi::NVM == 8) { if (ui > 0) { const int t = 0; PG8_KSETUP(); PG8_KITER_SP2(16, 16); t0 = 2; } }
;         for (int t = t0; t < nt; t += 2) {
;             PG8_KSETUP();
;             if constexpr (SP2) {
;             PG8_KITER_SP2(8, 8);
	ds_read_b128 v[180:183], v149 offset:49152
	ds_read_b128 v[184:187], v149 offset:50176
	ds_read_b128 v[188:191], v149 offset:51200
	ds_read_b128 v[192:195], v149 offset:52224
	ds_read_b128 v[196:199], v149 offset:53248
	ds_read_b128 v[200:203], v149 offset:54272
	ds_read_b128 v[204:207], v149 offset:55296
	ds_read_b128 v[208:211], v149 offset:56320
	s_add_u32 s30, s64, 0x80
	s_addc_u32 s31, s65, 0
	s_mov_b32 m0, s75
	s_nop 0
	global_load_lds_dwordx4 v142, s[30:31] offset:0
	s_nop 0
	s_mov_b32 m0, s76
	s_nop 0
	global_load_lds_dwordx4 v144, s[30:31] offset:0
	s_add_u32 s30, s64, 0x80080
	s_addc_u32 s31, s65, 0
	s_mov_b32 m0, s79
	s_nop 0
	global_load_lds_dwordx4 v142, s[30:31] offset:0
	s_nop 0
	s_mov_b32 m0, s80
	s_nop 0
	global_load_lds_dwordx4 v144, s[30:31] offset:0
	s_nop 0
	s_mov_b32 m0, s77
	s_nop 0
	global_load_lds_dwordx4 v1, s[58:59] offset:0
	s_nop 0
	s_mov_b32 m0, s78
	s_nop 0
	global_load_lds_dwordx4 v143, s[58:59] offset:0
	s_waitcnt vmcnt(8)
	s_waitcnt lgkmcnt(0)
	s_barrier
	s_setprio 1
	s_waitcnt lgkmcnt(7)
	s_waitcnt lgkmcnt(5)
	s_waitcnt lgkmcnt(3)
	s_waitcnt lgkmcnt(1)
	s_waitcnt lgkmcnt(0)
	v_mfma_f32_16x16x32_bf16 v[66:69], v[138:141], v[180:183], v[66:69]
	v_mfma_f32_16x16x32_bf16 v[66:69], v[152:155], v[184:187], v[66:69]
	v_mfma_f32_16x16x32_bf16 v[62:65], v[156:159], v[180:183], v[62:65]
	v_mfma_f32_16x16x32_bf16 v[62:65], v[160:163], v[184:187], v[62:65]
	v_mfma_f32_16x16x32_bf16 v[50:53], v[138:141], v[188:191], v[50:53]
	v_mfma_f32_16x16x32_bf16 v[50:53], v[152:155], v[192:195], v[50:53]
	v_mfma_f32_16x16x32_bf16 v[46:49], v[156:159], v[188:191], v[46:49]
	v_mfma_f32_16x16x32_bf16 v[46:49], v[160:163], v[192:195], v[46:49]
	v_mfma_f32_16x16x32_bf16 v[34:37], v[138:141], v[196:199], v[34:37]
	v_mfma_f32_16x16x32_bf16 v[34:37], v[152:155], v[200:203], v[34:37]
	v_mfma_f32_16x16x32_bf16 v[30:33], v[156:159], v[196:199], v[30:33]
	v_mfma_f32_16x16x32_bf16 v[30:33], v[160:163], v[200:203], v[30:33]
	v_mfma_f32_16x16x32_bf16 v[18:21], v[138:141], v[204:207], v[18:21]
	v_mfma_f32_16x16x32_bf16 v[18:21], v[152:155], v[208:211], v[18:21]
	v_mfma_f32_16x16x32_bf16 v[14:17], v[156:159], v[204:207], v[14:17]
	v_mfma_f32_16x16x32_bf16 v[14:17], v[160:163], v[208:211], v[14:17]
	s_setprio 0
	s_setprio 1
	v_mfma_f32_16x16x32_bf16 v[58:61], v[164:167], v[180:183], v[58:61]
	v_mfma_f32_16x16x32_bf16 v[54:57], v[172:175], v[180:183], v[54:57]
	v_mfma_f32_16x16x32_bf16 v[42:45], v[164:167], v[188:191], v[42:45]
	v_mfma_f32_16x16x32_bf16 v[38:41], v[172:175], v[188:191], v[38:41]
	v_mfma_f32_16x16x32_bf16 v[26:29], v[164:167], v[196:199], v[26:29]
	v_mfma_f32_16x16x32_bf16 v[22:25], v[172:175], v[196:199], v[22:25]
	v_mfma_f32_16x16x32_bf16 v[8:11], v[164:167], v[204:207], v[10:13]
	v_mfma_f32_16x16x32_bf16 v[4:7], v[172:175], v[204:207], v[4:7]
	v_mfma_f32_16x16x32_bf16 v[58:61], v[168:171], v[184:187], v[58:61]
	v_mfma_f32_16x16x32_bf16 v[54:57], v[176:179], v[184:187], v[54:57]
	v_mfma_f32_16x16x32_bf16 v[42:45], v[168:171], v[192:195], v[42:45]
	v_mfma_f32_16x16x32_bf16 v[38:41], v[176:179], v[192:195], v[38:41]
	v_mfma_f32_16x16x32_bf16 v[26:29], v[168:171], v[200:203], v[26:29]
	v_mfma_f32_16x16x32_bf16 v[22:25], v[176:179], v[200:203], v[22:25]
	v_mfma_f32_16x16x32_bf16 v[10:13], v[168:171], v[208:211], v[8:11]
	v_mfma_f32_16x16x32_bf16 v[6:9], v[176:179], v[208:211], v[4:7]
	s_setprio 0
	s_barrier
	s_add_i32 s88, s88, 2
	s_add_u32 s89, s89, 0x100
	s_addc_u32 s90, s90, 0
	s_add_u32 s91, s91, 0x100
	s_addc_u32 s92, s92, 0
	s_add_u32 s56, s56, 0x100
	s_addc_u32 s57, s57, 0
	s_cmp_gt_u32 s88, 29
	s_cbranch_scc0 .LBB0_628
	s_and_b64 vcc, exec, s[20:21]
	s_cbranch_vccz .LBB0_631
	s_barrier

.LBB0_787:
	ds_read_b128 v[138:141], v152
	ds_read_b128 v[142:145], v152 offset:1024
	ds_read_b128 v[158:161], v152 offset:2048
	ds_read_b128 v[162:165], v152 offset:3072
	ds_read_b128 v[166:169], v153
	ds_read_b128 v[170:173], v153 offset:1024
	ds_read_b128 v[174:177], v153 offset:2048
	ds_read_b128 v[178:181], v153 offset:3072
	s_cmp_eq_u32 s80, 28
	s_cselect_b32 s44, s78, s83
	s_cselect_b32 s45, s21, s84
	s_cselect_b32 s40, s79, s81
	s_cselect_b32 s41, s19, s82
	s_add_u32 s38, s44, 0x80
	s_addc_u32 s39, s45, 0
	ds_read_b128 v[182:185], v154
	ds_read_b128 v[186:189], v154 offset:1024
	ds_read_b128 v[190:193], v154 offset:2048
	ds_read_b128 v[194:197], v154 offset:3072
	ds_read_b128 v[198:201], v154 offset:4096
	ds_read_b128 v[202:205], v154 offset:5120
	ds_read_b128 v[206:209], v154 offset:6144
	ds_read_b128 v[210:213], v154 offset:7168
	s_add_u32 s30, s83, 0x7ff80
	s_addc_u32 s31, s84, 0
	s_mov_b32 m0, s68
	s_nop 0
	global_load_lds_dwordx4 v1, s[30:31] offset:0
	s_nop 0
	s_mov_b32 m0, s69
	s_nop 0
	global_load_lds_dwordx4 v147, s[30:31] offset:0
	s_waitcnt vmcnt(8)
	s_waitcnt lgkmcnt(0)
	s_barrier
	s_setprio 1
	s_waitcnt lgkmcnt(0)
	v_mfma_f32_16x16x32_bf16 v[130:133], v[138:141], v[182:185], v[130:133]
	v_mfma_f32_16x16x32_bf16 v[130:133], v[142:145], v[186:189], v[130:133]
	v_mfma_f32_16x16x32_bf16 v[126:129], v[158:161], v[182:185], v[126:129]
	v_mfma_f32_16x16x32_bf16 v[126:129], v[162:165], v[186:189], v[126:129]
	v_mfma_f32_16x16x32_bf16 v[114:117], v[138:141], v[190:193], v[114:117]
	v_mfma_f32_16x16x32_bf16 v[114:117], v[142:145], v[194:197], v[114:117]
	v_mfma_f32_16x16x32_bf16 v[110:113], v[158:161], v[190:193], v[110:113]
	v_mfma_f32_16x16x32_bf16 v[110:113], v[162:165], v[194:197], v[110:113]
	v_mfma_f32_16x16x32_bf16 v[98:101], v[138:141], v[198:201], v[98:101]
	v_mfma_f32_16x16x32_bf16 v[98:101], v[142:145], v[202:205], v[98:101]
	v_mfma_f32_16x16x32_bf16 v[94:97], v[158:161], v[198:201], v[94:97]
	v_mfma_f32_16x16x32_bf16 v[94:97], v[162:165], v[202:205], v[94:97]
	v_mfma_f32_16x16x32_bf16 v[82:85], v[138:141], v[206:209], v[82:85]
	v_mfma_f32_16x16x32_bf16 v[82:85], v[142:145], v[210:213], v[82:85]
	v_mfma_f32_16x16x32_bf16 v[78:81], v[158:161], v[206:209], v[78:81]
	v_mfma_f32_16x16x32_bf16 v[78:81], v[162:165], v[210:213], v[78:81]
	s_setprio 0
	s_setprio 1
	v_mfma_f32_16x16x32_bf16 v[122:125], v[166:169], v[182:185], v[122:125]
	v_mfma_f32_16x16x32_bf16 v[122:125], v[170:173], v[186:189], v[122:125]
	v_mfma_f32_16x16x32_bf16 v[118:121], v[174:177], v[182:185], v[118:121]
	v_mfma_f32_16x16x32_bf16 v[118:121], v[178:181], v[186:189], v[118:121]
	v_mfma_f32_16x16x32_bf16 v[106:109], v[166:169], v[190:193], v[106:109]
	v_mfma_f32_16x16x32_bf16 v[106:109], v[170:173], v[194:197], v[106:109]
	v_mfma_f32_16x16x32_bf16 v[102:105], v[174:177], v[190:193], v[102:105]
	v_mfma_f32_16x16x32_bf16 v[102:105], v[178:181], v[194:197], v[102:105]
	v_mfma_f32_16x16x32_bf16 v[90:93], v[166:169], v[198:201], v[90:93]
	v_mfma_f32_16x16x32_bf16 v[90:93], v[170:173], v[202:205], v[90:93]
	v_mfma_f32_16x16x32_bf16 v[86:89], v[174:177], v[198:201], v[86:89]
	v_mfma_f32_16x16x32_bf16 v[86:89], v[178:181], v[202:205], v[86:89]
	v_mfma_f32_16x16x32_bf16 v[74:77], v[166:169], v[206:209], v[74:77]
	v_mfma_f32_16x16x32_bf16 v[74:77], v[170:173], v[210:213], v[74:77]
	v_mfma_f32_16x16x32_bf16 v[66:69], v[174:177], v[206:209], v[66:69]
	v_mfma_f32_16x16x32_bf16 v[66:69], v[178:181], v[210:213], v[66:69]
	s_setprio 0
	s_barrier
	ds_read_b128 v[182:185], v154 offset:16384
	ds_read_b128 v[186:189], v154 offset:17408
	ds_read_b128 v[190:193], v154 offset:18432
	ds_read_b128 v[194:197], v154 offset:19456
	ds_read_b128 v[198:201], v154 offset:20480
	ds_read_b128 v[202:205], v154 offset:21504
	ds_read_b128 v[206:209], v154 offset:22528
	ds_read_b128 v[210:213], v154 offset:23552
	s_mov_b32 m0, s37
	s_nop 0
	global_load_lds_dwordx4 v146, s[40:41] offset:0
	s_add_u32 s30, s40, 0x80000
	s_mov_b32 m0, s52
	s_nop 0
	global_load_lds_dwordx4 v148, s[40:41] offset:0
	s_addc_u32 s31, s41, 0
	s_mov_b32 m0, s53
	s_nop 0
	global_load_lds_dwordx4 v146, s[30:31] offset:0
	s_nop 0
	s_mov_b32 m0, s54
	s_nop 0
	global_load_lds_dwordx4 v148, s[30:31] offset:0
	s_nop 0
	s_mov_b32 m0, s23
	s_nop 0
	global_load_lds_dwordx4 v1, s[44:45] offset:0
	s_nop 0
	s_mov_b32 m0, s55
	s_nop 0
	global_load_lds_dwordx4 v147, s[44:45] offset:0
	s_waitcnt vmcnt(8)
	s_waitcnt lgkmcnt(0)
	s_barrier
	s_setprio 1
	s_waitcnt lgkmcnt(0)
	s_waitcnt lgkmcnt(5)
	s_waitcnt lgkmcnt(3)
	s_waitcnt lgkmcnt(1)
	s_waitcnt lgkmcnt(0)
	v_mfma_f32_16x16x32_bf16 v[70:73], v[138:141], v[182:185], v[70:73]
	v_mfma_f32_16x16x32_bf16 v[70:73], v[142:145], v[186:189], v[70:73]
	v_mfma_f32_16x16x32_bf16 v[62:65], v[158:161], v[182:185], v[62:65]
	v_mfma_f32_16x16x32_bf16 v[62:65], v[162:165], v[186:189], v[62:65]
	v_mfma_f32_16x16x32_bf16 v[50:53], v[138:141], v[190:193], v[50:53]
	v_mfma_f32_16x16x32_bf16 v[50:53], v[142:145], v[194:197], v[50:53]
	v_mfma_f32_16x16x32_bf16 v[46:49], v[158:161], v[190:193], v[46:49]
	v_mfma_f32_16x16x32_bf16 v[46:49], v[162:165], v[194:197], v[46:49]
	v_mfma_f32_16x16x32_bf16 v[34:37], v[138:141], v[198:201], v[34:37]
	v_mfma_f32_16x16x32_bf16 v[34:37], v[142:145], v[202:205], v[34:37]
	v_mfma_f32_16x16x32_bf16 v[30:33], v[158:161], v[198:201], v[30:33]
	v_mfma_f32_16x16x32_bf16 v[30:33], v[162:165], v[202:205], v[30:33]
	v_mfma_f32_16x16x32_bf16 v[18:21], v[138:141], v[206:209], v[18:21]
	v_mfma_f32_16x16x32_bf16 v[18:21], v[142:145], v[210:213], v[18:21]
	v_mfma_f32_16x16x32_bf16 v[14:17], v[158:161], v[206:209], v[14:17]
	v_mfma_f32_16x16x32_bf16 v[14:17], v[162:165], v[210:213], v[14:17]
	s_setprio 0
	s_setprio 1
	v_mfma_f32_16x16x32_bf16 v[58:61], v[166:169], v[182:185], v[58:61]
	v_mfma_f32_16x16x32_bf16 v[54:57], v[174:177], v[182:185], v[54:57]
	v_mfma_f32_16x16x32_bf16 v[42:45], v[166:169], v[190:193], v[42:45]
	v_mfma_f32_16x16x32_bf16 v[38:41], v[174:177], v[190:193], v[38:41]
	v_mfma_f32_16x16x32_bf16 v[26:29], v[166:169], v[198:201], v[26:29]
	v_mfma_f32_16x16x32_bf16 v[22:25], v[174:177], v[198:201], v[22:25]
	v_mfma_f32_16x16x32_bf16 v[10:13], v[166:169], v[206:209], v[10:13]
	v_mfma_f32_16x16x32_bf16 v[4:7], v[174:177], v[206:209], v[6:9]
	v_mfma_f32_16x16x32_bf16 v[58:61], v[170:173], v[186:189], v[58:61]
	v_mfma_f32_16x16x32_bf16 v[54:57], v[178:181], v[186:189], v[54:57]
	v_mfma_f32_16x16x32_bf16 v[42:45], v[170:173], v[194:197], v[42:45]
	v_mfma_f32_16x16x32_bf16 v[38:41], v[178:181], v[194:197], v[38:41]
	v_mfma_f32_16x16x32_bf16 v[26:29], v[170:173], v[202:205], v[26:29]
	v_mfma_f32_16x16x32_bf16 v[22:25], v[178:181], v[202:205], v[22:25]
	v_mfma_f32_16x16x32_bf16 v[10:13], v[170:173], v[210:213], v[10:13]
	v_mfma_f32_16x16x32_bf16 v[4:7], v[178:181], v[210:213], v[4:7]
	s_setprio 0
	s_barrier
; #define PG8_KSETUP() const bool last = (t == nt - 2); const char* a1 = cA + (size_t)(t + 1) * kstep; \
;             const char* a2 = last ? nA : cA + (size_t)(t + 2) * kstep; const char* b2 = last ? nB : cB + (size_t)(t + 2) * kstep; const char* a3 = a2 + kstep; const char* b3 = b2 + kstep; \
;             if (last && has_next) S.a_ready(nxt)
; template <class Epi, class Sched, bool ALIGN_EPI = false, bool SP2 = false>
; __device__ __forceinline__ void gemm_phase(PG8_LAS unsigned char* lds, const Gemm g, const Sched& S, const Epi& E) {
;     ...
;         int t0 = 0;
;         if constexpr (SP2 && Epi::NVM == 16) { if (ui > 0) { const int t = 0; PG8_KSETUP(); PG8_KITER_SP2(24, 24); t0 = 2; } }
;         if constexpr (SP2 && Epi::NVM == 8) { if (ui > 0) { const int t = 0; PG8_KSETUP(); PG8_KITER_SP2(16, 16); t0 = 2; } }
;         for (int t = t0; t < nt; t += 2) {
;             PG8_KSETUP();
;             if constexpr (SP2) {
;             PG8_KITER_SP2(8, 8);
	ds_read_b128 v[138:141], v155
	ds_read_b128 v[142:145], v155 offset:1024
	ds_read_b128 v[158:161], v155 offset:2048
	ds_read_b128 v[162:165], v155 offset:3072
	ds_read_b128 v[166:169], v156
	ds_read_b128 v[170:173], v156 offset:1024
	ds_read_b128 v[174:177], v156 offset:2048
	ds_read_b128 v[178:181], v156 offset:3072
	ds_read_b128 v[182:185], v154 offset:32768
	ds_read_b128 v[186:189], v154 offset:33792
	ds_read_b128 v[190:193], v154 offset:34816
	ds_read_b128 v[194:197], v154 offset:35840
	ds_read_b128 v[198:201], v154 offset:36864
	ds_read_b128 v[202:205], v154 offset:37888
	ds_read_b128 v[206:209], v154 offset:38912
	ds_read_b128 v[210:213], v154 offset:39936
	s_add_u32 s30, s44, 0x80000
	s_addc_u32 s31, s45, 0
	s_mov_b32 m0, s56
	s_nop 0
	global_load_lds_dwordx4 v1, s[30:31] offset:0
	s_nop 0
	s_mov_b32 m0, s57
	s_nop 0
	global_load_lds_dwordx4 v147, s[30:31] offset:0
	s_waitcnt vmcnt(8)
	s_waitcnt lgkmcnt(0)
	s_barrier
	s_setprio 1
	s_waitcnt lgkmcnt(0)
	s_waitcnt lgkmcnt(5)
	s_waitcnt lgkmcnt(3)
	s_waitcnt lgkmcnt(1)
	s_waitcnt lgkmcnt(0)
	v_mfma_f32_16x16x32_bf16 v[130:133], v[138:141], v[182:185], v[130:133]
	v_mfma_f32_16x16x32_bf16 v[130:133], v[142:145], v[186:189], v[130:133]
	v_mfma_f32_16x16x32_bf16 v[126:129], v[158:161], v[182:185], v[126:129]
	v_mfma_f32_16x16x32_bf16 v[126:129], v[162:165], v[186:189], v[126:129]
	v_mfma_f32_16x16x32_bf16 v[114:117], v[138:141], v[190:193], v[114:117]
	v_mfma_f32_16x16x32_bf16 v[114:117], v[142:145], v[194:197], v[114:117]
	v_mfma_f32_16x16x32_bf16 v[110:113], v[158:161], v[190:193], v[110:113]
	v_mfma_f32_16x16x32_bf16 v[110:113], v[162:165], v[194:197], v[110:113]
	v_mfma_f32_16x16x32_bf16 v[98:101], v[138:141], v[198:201], v[98:101]
	v_mfma_f32_16x16x32_bf16 v[98:101], v[142:145], v[202:205], v[98:101]
	v_mfma_f32_16x16x32_bf16 v[94:97], v[158:161], v[198:201], v[94:97]
	v_mfma_f32_16x16x32_bf16 v[94:97], v[162:165], v[202:205], v[94:97]
	v_mfma_f32_16x16x32_bf16 v[82:85], v[138:141], v[206:209], v[82:85]
	v_mfma_f32_16x16x32_bf16 v[82:85], v[142:145], v[210:213], v[82:85]
	v_mfma_f32_16x16x32_bf16 v[78:81], v[158:161], v[206:209], v[78:81]
	v_mfma_f32_16x16x32_bf16 v[78:81], v[162:165], v[210:213], v[78:81]
	s_setprio 0
	s_setprio 1
	v_mfma_f32_16x16x32_bf16 v[122:125], v[166:169], v[182:185], v[122:125]
	v_mfma_f32_16x16x32_bf16 v[122:125], v[170:173], v[186:189], v[122:125]
	v_mfma_f32_16x16x32_bf16 v[118:121], v[174:177], v[182:185], v[118:121]
	v_mfma_f32_16x16x32_bf16 v[118:121], v[178:181], v[186:189], v[118:121]
	v_mfma_f32_16x16x32_bf16 v[106:109], v[166:169], v[190:193], v[106:109]
	v_mfma_f32_16x16x32_bf16 v[106:109], v[170:173], v[194:197], v[106:109]
	v_mfma_f32_16x16x32_bf16 v[102:105], v[174:177], v[190:193], v[102:105]
	v_mfma_f32_16x16x32_bf16 v[102:105], v[178:181], v[194:197], v[102:105]
	v_mfma_f32_16x16x32_bf16 v[90:93], v[166:169], v[198:201], v[90:93]
	v_mfma_f32_16x16x32_bf16 v[90:93], v[170:173], v[202:205], v[90:93]
	v_mfma_f32_16x16x32_bf16 v[86:89], v[174:177], v[198:201], v[86:89]
	v_mfma_f32_16x16x32_bf16 v[86:89], v[178:181], v[202:205], v[86:89]
	v_mfma_f32_16x16x32_bf16 v[74:77], v[166:169], v[206:209], v[74:77]
	v_mfma_f32_16x16x32_bf16 v[74:77], v[170:173], v[210:213], v[74:77]
	v_mfma_f32_16x16x32_bf16 v[66:69], v[174:177], v[206:209], v[66:69]
	v_mfma_f32_16x16x32_bf16 v[66:69], v[178:181], v[210:213], v[66:69]
	s_setprio 0
	s_barrier
	ds_read_b128 v[182:185], v154 offset:49152
	ds_read_b128 v[186:189], v154 offset:50176
	ds_read_b128 v[190:193], v154 offset:51200
	ds_read_b128 v[194:197], v154 offset:52224
	ds_read_b128 v[198:201], v154 offset:53248
	ds_read_b128 v[202:205], v154 offset:54272
	ds_read_b128 v[206:209], v154 offset:55296
	ds_read_b128 v[210:213], v154 offset:56320
	s_add_u32 s30, s40, 0x80
	s_addc_u32 s31, s41, 0
	s_mov_b32 m0, s58
	s_nop 0
	global_load_lds_dwordx4 v146, s[30:31] offset:0
	s_nop 0
	s_mov_b32 m0, s59
	s_nop 0
	global_load_lds_dwordx4 v148, s[30:31] offset:0
	s_add_u32 s30, s40, 0x80080
	s_addc_u32 s31, s41, 0
	s_mov_b32 m0, s66
	s_nop 0
	global_load_lds_dwordx4 v146, s[30:31] offset:0
	s_nop 0
	s_mov_b32 m0, s67
	s_nop 0
	global_load_lds_dwordx4 v148, s[30:31] offset:0
	s_nop 0
	s_mov_b32 m0, s64
	s_nop 0
	global_load_lds_dwordx4 v1, s[38:39] offset:0
	s_nop 0
	s_mov_b32 m0, s65
	s_nop 0
	global_load_lds_dwordx4 v147, s[38:39] offset:0
	s_waitcnt vmcnt(8)
	s_waitcnt lgkmcnt(0)
	s_barrier
	s_setprio 1
	s_waitcnt lgkmcnt(0)
	s_waitcnt lgkmcnt(5)
	s_waitcnt lgkmcnt(3)
	s_waitcnt lgkmcnt(1)
	s_waitcnt lgkmcnt(0)
	v_mfma_f32_16x16x32_bf16 v[70:73], v[138:141], v[182:185], v[70:73]
	v_mfma_f32_16x16x32_bf16 v[70:73], v[142:145], v[186:189], v[70:73]
	v_mfma_f32_16x16x32_bf16 v[62:65], v[158:161], v[182:185], v[62:65]
	v_mfma_f32_16x16x32_bf16 v[62:65], v[162:165], v[186:189], v[62:65]
	v_mfma_f32_16x16x32_bf16 v[50:53], v[138:141], v[190:193], v[50:53]
	v_mfma_f32_16x16x32_bf16 v[50:53], v[142:145], v[194:197], v[50:53]
	v_mfma_f32_16x16x32_bf16 v[46:49], v[158:161], v[190:193], v[46:49]
	v_mfma_f32_16x16x32_bf16 v[46:49], v[162:165], v[194:197], v[46:49]
	v_mfma_f32_16x16x32_bf16 v[34:37], v[138:141], v[198:201], v[34:37]
	v_mfma_f32_16x16x32_bf16 v[34:37], v[142:145], v[202:205], v[34:37]
	v_mfma_f32_16x16x32_bf16 v[30:33], v[158:161], v[198:201], v[30:33]
	v_mfma_f32_16x16x32_bf16 v[30:33], v[162:165], v[202:205], v[30:33]
	v_mfma_f32_16x16x32_bf16 v[18:21], v[138:141], v[206:209], v[18:21]
	v_mfma_f32_16x16x32_bf16 v[18:21], v[142:145], v[210:213], v[18:21]
	v_mfma_f32_16x16x32_bf16 v[14:17], v[158:161], v[206:209], v[14:17]
	v_mfma_f32_16x16x32_bf16 v[14:17], v[162:165], v[210:213], v[14:17]
	s_setprio 0
	s_setprio 1
	v_mfma_f32_16x16x32_bf16 v[58:61], v[166:169], v[182:185], v[58:61]
	v_mfma_f32_16x16x32_bf16 v[54:57], v[174:177], v[182:185], v[54:57]
	v_mfma_f32_16x16x32_bf16 v[42:45], v[166:169], v[190:193], v[42:45]
	v_mfma_f32_16x16x32_bf16 v[38:41], v[174:177], v[190:193], v[38:41]
	v_mfma_f32_16x16x32_bf16 v[26:29], v[166:169], v[198:201], v[26:29]
	v_mfma_f32_16x16x32_bf16 v[22:25], v[174:177], v[198:201], v[22:25]
	v_mfma_f32_16x16x32_bf16 v[8:11], v[166:169], v[206:209], v[10:13]
	v_mfma_f32_16x16x32_bf16 v[4:7], v[174:177], v[206:209], v[4:7]
	v_mfma_f32_16x16x32_bf16 v[58:61], v[170:173], v[186:189], v[58:61]
	v_mfma_f32_16x16x32_bf16 v[54:57], v[178:181], v[186:189], v[54:57]
	v_mfma_f32_16x16x32_bf16 v[42:45], v[170:173], v[194:197], v[42:45]
	v_mfma_f32_16x16x32_bf16 v[38:41], v[178:181], v[194:197], v[38:41]
	v_mfma_f32_16x16x32_bf16 v[26:29], v[170:173], v[202:205], v[26:29]
	v_mfma_f32_16x16x32_bf16 v[22:25], v[178:181], v[202:205], v[22:25]
	v_mfma_f32_16x16x32_bf16 v[10:13], v[170:173], v[210:213], v[8:11]
	v_mfma_f32_16x16x32_bf16 v[6:9], v[178:181], v[210:213], v[4:7]
	s_setprio 0
	s_barrier
	s_add_i32 s80, s80, 2
	s_add_u32 s81, s81, 0x100
	s_addc_u32 s82, s82, 0
	s_add_u32 s83, s83, 0x100
	s_addc_u32 s84, s84, 0
	s_cmp_gt_u32 s80, 29
	s_cbranch_scc0 .LBB0_787
	s_and_b64 vcc, exec, s[16:17]
	s_cbranch_vccz .LBB0_790
	s_barrier

.LBB0_872:
	ds_read_b128 v[148:151], v143
	ds_read_b128 v[152:155], v143 offset:1024
	ds_read_b128 v[156:159], v143 offset:2048
	ds_read_b128 v[160:163], v143 offset:3072
	ds_read_b128 v[164:167], v144
	ds_read_b128 v[168:171], v144 offset:1024
	ds_read_b128 v[172:175], v144 offset:2048
	ds_read_b128 v[176:179], v144 offset:3072
	s_cmpk_eq_i32 s79, 0x54
	s_cselect_b32 s44, s6, s82
	s_cselect_b32 s45, s7, s83
	s_cselect_b32 s40, s28, s80
	s_cselect_b32 s41, s29, s81
	s_add_u32 s38, s44, 0x80
	s_addc_u32 s39, s45, 0
	ds_read_b128 v[180:183], v145
	ds_read_b128 v[184:187], v145 offset:1024
	ds_read_b128 v[188:191], v145 offset:2048
	ds_read_b128 v[192:195], v145 offset:3072
	ds_read_b128 v[196:199], v145 offset:4096
	ds_read_b128 v[200:203], v145 offset:5120
	ds_read_b128 v[204:207], v145 offset:6144
	ds_read_b128 v[208:211], v145 offset:7168
	s_mov_b32 m0, s71
	s_nop 0
	global_load_lds_dwordx4 v1, s[36:37] offset:0
	s_nop 0
	s_mov_b32 m0, s72
	s_nop 0
	global_load_lds_dwordx4 v139, s[36:37] offset:0
	s_waitcnt vmcnt(8)
	s_waitcnt lgkmcnt(0)
	s_barrier
	s_setprio 1
	s_waitcnt lgkmcnt(7)
	s_waitcnt lgkmcnt(5)
	s_waitcnt lgkmcnt(3)
	s_waitcnt lgkmcnt(1)
	s_waitcnt lgkmcnt(0)
	v_mfma_f32_16x16x32_bf16 v[130:133], v[148:151], v[180:183], v[130:133]
	v_mfma_f32_16x16x32_bf16 v[130:133], v[152:155], v[184:187], v[130:133]
	v_mfma_f32_16x16x32_bf16 v[126:129], v[156:159], v[180:183], v[126:129]
	v_mfma_f32_16x16x32_bf16 v[126:129], v[160:163], v[184:187], v[126:129]
	v_mfma_f32_16x16x32_bf16 v[114:117], v[148:151], v[188:191], v[114:117]
	v_mfma_f32_16x16x32_bf16 v[114:117], v[152:155], v[192:195], v[114:117]
	v_mfma_f32_16x16x32_bf16 v[110:113], v[156:159], v[188:191], v[110:113]
	v_mfma_f32_16x16x32_bf16 v[110:113], v[160:163], v[192:195], v[110:113]
	v_mfma_f32_16x16x32_bf16 v[98:101], v[148:151], v[196:199], v[98:101]
	v_mfma_f32_16x16x32_bf16 v[98:101], v[152:155], v[200:203], v[98:101]
	v_mfma_f32_16x16x32_bf16 v[94:97], v[156:159], v[196:199], v[94:97]
	v_mfma_f32_16x16x32_bf16 v[94:97], v[160:163], v[200:203], v[94:97]
	v_mfma_f32_16x16x32_bf16 v[82:85], v[148:151], v[204:207], v[82:85]
	v_mfma_f32_16x16x32_bf16 v[82:85], v[152:155], v[208:211], v[82:85]
	v_mfma_f32_16x16x32_bf16 v[78:81], v[156:159], v[204:207], v[78:81]
	v_mfma_f32_16x16x32_bf16 v[78:81], v[160:163], v[208:211], v[78:81]
	s_setprio 0
	s_setprio 1
	v_mfma_f32_16x16x32_bf16 v[122:125], v[164:167], v[180:183], v[122:125]
	v_mfma_f32_16x16x32_bf16 v[122:125], v[168:171], v[184:187], v[122:125]
	v_mfma_f32_16x16x32_bf16 v[118:121], v[172:175], v[180:183], v[118:121]
	v_mfma_f32_16x16x32_bf16 v[118:121], v[176:179], v[184:187], v[118:121]
	v_mfma_f32_16x16x32_bf16 v[106:109], v[164:167], v[188:191], v[106:109]
	v_mfma_f32_16x16x32_bf16 v[106:109], v[168:171], v[192:195], v[106:109]
	v_mfma_f32_16x16x32_bf16 v[102:105], v[172:175], v[188:191], v[102:105]
	v_mfma_f32_16x16x32_bf16 v[102:105], v[176:179], v[192:195], v[102:105]
	v_mfma_f32_16x16x32_bf16 v[90:93], v[164:167], v[196:199], v[90:93]
	v_mfma_f32_16x16x32_bf16 v[90:93], v[168:171], v[200:203], v[90:93]
	v_mfma_f32_16x16x32_bf16 v[86:89], v[172:175], v[196:199], v[86:89]
	v_mfma_f32_16x16x32_bf16 v[86:89], v[176:179], v[200:203], v[86:89]
	v_mfma_f32_16x16x32_bf16 v[70:73], v[164:167], v[204:207], v[70:73]
	v_mfma_f32_16x16x32_bf16 v[70:73], v[168:171], v[208:211], v[70:73]
	v_mfma_f32_16x16x32_bf16 v[62:65], v[172:175], v[204:207], v[62:65]
	v_mfma_f32_16x16x32_bf16 v[62:65], v[176:179], v[208:211], v[62:65]
	s_setprio 0
	s_barrier
	ds_read_b128 v[180:183], v145 offset:16384
	ds_read_b128 v[184:187], v145 offset:17408
	ds_read_b128 v[188:191], v145 offset:18432
	ds_read_b128 v[192:195], v145 offset:19456
	ds_read_b128 v[196:199], v145 offset:20480
	ds_read_b128 v[200:203], v145 offset:21504
	ds_read_b128 v[204:207], v145 offset:22528
	ds_read_b128 v[208:211], v145 offset:23552
	s_mov_b32 m0, s54
	s_nop 0
	global_load_lds_dwordx4 v138, s[40:41] offset:0
	s_add_u32 s30, s40, 0x160000
	s_mov_b32 m0, s55
	s_nop 0
	global_load_lds_dwordx4 v140, s[40:41] offset:0
	s_addc_u32 s31, s41, 0
	s_mov_b32 m0, s56
	s_nop 0
	global_load_lds_dwordx4 v138, s[30:31] offset:0
	s_nop 0
	s_mov_b32 m0, s57
	s_nop 0
	global_load_lds_dwordx4 v140, s[30:31] offset:0
	s_nop 0
	s_mov_b32 m0, s47
	s_nop 0
	global_load_lds_dwordx4 v1, s[44:45] offset:0
	s_nop 0
	s_mov_b32 m0, s58
	s_nop 0
	global_load_lds_dwordx4 v139, s[44:45] offset:0
	s_waitcnt vmcnt(8)
	s_waitcnt lgkmcnt(0)
	s_barrier
	s_setprio 1
	s_waitcnt lgkmcnt(7)
	s_waitcnt lgkmcnt(5)
	s_waitcnt lgkmcnt(3)
	s_waitcnt lgkmcnt(1)
	s_waitcnt lgkmcnt(0)
	v_mfma_f32_16x16x32_bf16 v[74:77], v[148:151], v[180:183], v[74:77]
	v_mfma_f32_16x16x32_bf16 v[74:77], v[152:155], v[184:187], v[74:77]
	v_mfma_f32_16x16x32_bf16 v[66:69], v[156:159], v[180:183], v[66:69]
	v_mfma_f32_16x16x32_bf16 v[66:69], v[160:163], v[184:187], v[66:69]
	v_mfma_f32_16x16x32_bf16 v[50:53], v[148:151], v[188:191], v[50:53]
	v_mfma_f32_16x16x32_bf16 v[50:53], v[152:155], v[192:195], v[50:53]
	v_mfma_f32_16x16x32_bf16 v[46:49], v[156:159], v[188:191], v[46:49]
	v_mfma_f32_16x16x32_bf16 v[46:49], v[160:163], v[192:195], v[46:49]
	v_mfma_f32_16x16x32_bf16 v[34:37], v[148:151], v[196:199], v[34:37]
	v_mfma_f32_16x16x32_bf16 v[34:37], v[152:155], v[200:203], v[34:37]
	v_mfma_f32_16x16x32_bf16 v[30:33], v[156:159], v[196:199], v[30:33]
	v_mfma_f32_16x16x32_bf16 v[30:33], v[160:163], v[200:203], v[30:33]
	v_mfma_f32_16x16x32_bf16 v[18:21], v[148:151], v[204:207], v[18:21]
	v_mfma_f32_16x16x32_bf16 v[18:21], v[152:155], v[208:211], v[18:21]
	v_mfma_f32_16x16x32_bf16 v[14:17], v[156:159], v[204:207], v[14:17]
	v_mfma_f32_16x16x32_bf16 v[14:17], v[160:163], v[208:211], v[14:17]
	s_setprio 0
	s_setprio 1
	v_mfma_f32_16x16x32_bf16 v[58:61], v[164:167], v[180:183], v[58:61]
	v_mfma_f32_16x16x32_bf16 v[54:57], v[172:175], v[180:183], v[54:57]
	v_mfma_f32_16x16x32_bf16 v[42:45], v[164:167], v[188:191], v[42:45]
	v_mfma_f32_16x16x32_bf16 v[38:41], v[172:175], v[188:191], v[38:41]
	v_mfma_f32_16x16x32_bf16 v[26:29], v[164:167], v[196:199], v[26:29]
	v_mfma_f32_16x16x32_bf16 v[22:25], v[172:175], v[196:199], v[22:25]
	v_mfma_f32_16x16x32_bf16 v[10:13], v[164:167], v[204:207], v[10:13]
	v_mfma_f32_16x16x32_bf16 v[4:7], v[172:175], v[204:207], v[6:9]
	v_mfma_f32_16x16x32_bf16 v[58:61], v[168:171], v[184:187], v[58:61]
	v_mfma_f32_16x16x32_bf16 v[54:57], v[176:179], v[184:187], v[54:57]
	v_mfma_f32_16x16x32_bf16 v[42:45], v[168:171], v[192:195], v[42:45]
	v_mfma_f32_16x16x32_bf16 v[38:41], v[176:179], v[192:195], v[38:41]
	v_mfma_f32_16x16x32_bf16 v[26:29], v[168:171], v[200:203], v[26:29]
	v_mfma_f32_16x16x32_bf16 v[22:25], v[176:179], v[200:203], v[22:25]
	v_mfma_f32_16x16x32_bf16 v[10:13], v[168:171], v[208:211], v[10:13]
	v_mfma_f32_16x16x32_bf16 v[4:7], v[176:179], v[208:211], v[4:7]
	s_setprio 0
	s_barrier
	ds_read_b128 v[148:151], v146
	ds_read_b128 v[152:155], v146 offset:1024
	ds_read_b128 v[156:159], v146 offset:2048
	ds_read_b128 v[160:163], v146 offset:3072
	ds_read_b128 v[164:167], v147
	ds_read_b128 v[168:171], v147 offset:1024
	ds_read_b128 v[172:175], v147 offset:2048
	ds_read_b128 v[176:179], v147 offset:3072
	ds_read_b128 v[180:183], v145 offset:32768
	ds_read_b128 v[184:187], v145 offset:33792
	ds_read_b128 v[188:191], v145 offset:34816
	ds_read_b128 v[192:195], v145 offset:35840
	ds_read_b128 v[196:199], v145 offset:36864
	ds_read_b128 v[200:203], v145 offset:37888
	ds_read_b128 v[204:207], v145 offset:38912
	ds_read_b128 v[208:211], v145 offset:39936
	s_add_u32 s30, s44, 0x160000
	s_addc_u32 s31, s45, 0
	s_mov_b32 m0, s59
	s_nop 0
	global_load_lds_dwordx4 v1, s[30:31] offset:0
	s_nop 0
	s_mov_b32 m0, s64
	s_nop 0
	global_load_lds_dwordx4 v139, s[30:31] offset:0
	s_waitcnt vmcnt(8)
	s_waitcnt lgkmcnt(0)
	s_barrier
	s_setprio 1
	s_waitcnt lgkmcnt(7)
	s_waitcnt lgkmcnt(5)
	s_waitcnt lgkmcnt(3)
	s_waitcnt lgkmcnt(1)
	s_waitcnt lgkmcnt(0)
	v_mfma_f32_16x16x32_bf16 v[130:133], v[148:151], v[180:183], v[130:133]
	v_mfma_f32_16x16x32_bf16 v[130:133], v[152:155], v[184:187], v[130:133]
	v_mfma_f32_16x16x32_bf16 v[126:129], v[156:159], v[180:183], v[126:129]
	v_mfma_f32_16x16x32_bf16 v[126:129], v[160:163], v[184:187], v[126:129]
	v_mfma_f32_16x16x32_bf16 v[114:117], v[148:151], v[188:191], v[114:117]
	v_mfma_f32_16x16x32_bf16 v[114:117], v[152:155], v[192:195], v[114:117]
	v_mfma_f32_16x16x32_bf16 v[110:113], v[156:159], v[188:191], v[110:113]
	v_mfma_f32_16x16x32_bf16 v[110:113], v[160:163], v[192:195], v[110:113]
	v_mfma_f32_16x16x32_bf16 v[98:101], v[148:151], v[196:199], v[98:101]
	v_mfma_f32_16x16x32_bf16 v[98:101], v[152:155], v[200:203], v[98:101]
	v_mfma_f32_16x16x32_bf16 v[94:97], v[156:159], v[196:199], v[94:97]
	v_mfma_f32_16x16x32_bf16 v[94:97], v[160:163], v[200:203], v[94:97]
	v_mfma_f32_16x16x32_bf16 v[82:85], v[148:151], v[204:207], v[82:85]
	v_mfma_f32_16x16x32_bf16 v[82:85], v[152:155], v[208:211], v[82:85]
	v_mfma_f32_16x16x32_bf16 v[78:81], v[156:159], v[204:207], v[78:81]
	v_mfma_f32_16x16x32_bf16 v[78:81], v[160:163], v[208:211], v[78:81]
	s_setprio 0
	s_setprio 1
	v_mfma_f32_16x16x32_bf16 v[122:125], v[164:167], v[180:183], v[122:125]
	v_mfma_f32_16x16x32_bf16 v[122:125], v[168:171], v[184:187], v[122:125]
	v_mfma_f32_16x16x32_bf16 v[118:121], v[172:175], v[180:183], v[118:121]
	v_mfma_f32_16x16x32_bf16 v[118:121], v[176:179], v[184:187], v[118:121]
	v_mfma_f32_16x16x32_bf16 v[106:109], v[164:167], v[188:191], v[106:109]
	v_mfma_f32_16x16x32_bf16 v[106:109], v[168:171], v[192:195], v[106:109]
	v_mfma_f32_16x16x32_bf16 v[102:105], v[172:175], v[188:191], v[102:105]
	v_mfma_f32_16x16x32_bf16 v[102:105], v[176:179], v[192:195], v[102:105]
	v_mfma_f32_16x16x32_bf16 v[90:93], v[164:167], v[196:199], v[90:93]
	v_mfma_f32_16x16x32_bf16 v[90:93], v[168:171], v[200:203], v[90:93]
	v_mfma_f32_16x16x32_bf16 v[86:89], v[172:175], v[196:199], v[86:89]
	v_mfma_f32_16x16x32_bf16 v[86:89], v[176:179], v[200:203], v[86:89]
	v_mfma_f32_16x16x32_bf16 v[70:73], v[164:167], v[204:207], v[70:73]
	v_mfma_f32_16x16x32_bf16 v[70:73], v[168:171], v[208:211], v[70:73]
	v_mfma_f32_16x16x32_bf16 v[62:65], v[172:175], v[204:207], v[62:65]
	v_mfma_f32_16x16x32_bf16 v[62:65], v[176:179], v[208:211], v[62:65]
	s_setprio 0
	s_barrier
; #define PG8_KSETUP() const bool last = (t == nt - 2); const char* a1 = cA + (size_t)(t + 1) * kstep; \
;             const char* a2 = last ? nA : cA + (size_t)(t + 2) * kstep; const char* b2 = last ? nB : cB + (size_t)(t + 2) * kstep; const char* a3 = a2 + kstep; const char* b3 = b2 + kstep; \
;             if (last && has_next) S.a_ready(nxt)
; template <class Epi, class Sched, bool ALIGN_EPI = false, bool SP2 = false>
; __device__ __forceinline__ void gemm_phase(PG8_LAS unsigned char* lds, const Gemm g, const Sched& S, const Epi& E) {
;     ...
;         int t0 = 0;
;         if constexpr (SP2 && Epi::NVM == 16) { if (ui > 0) { const int t = 0; PG8_KSETUP(); PG8_KITER_SP2(24, 24); t0 = 2; } }
;         if constexpr (SP2 && Epi::NVM == 8) { if (ui > 0) { const int t = 0; PG8_KSETUP(); PG8_KITER_SP2(16, 16); t0 = 2; } }
;         for (int t = t0; t < nt; t += 2) {
;             PG8_KSETUP();
;             if constexpr (SP2) {
;             PG8_KITER_SP2(8, 8);
	ds_read_b128 v[180:183], v145 offset:49152
	ds_read_b128 v[184:187], v145 offset:50176
	ds_read_b128 v[188:191], v145 offset:51200
	ds_read_b128 v[192:195], v145 offset:52224
	ds_read_b128 v[196:199], v145 offset:53248
	ds_read_b128 v[200:203], v145 offset:54272
	ds_read_b128 v[204:207], v145 offset:55296
	ds_read_b128 v[208:211], v145 offset:56320
	s_add_u32 s30, s40, 0x80
	s_addc_u32 s31, s41, 0
	s_mov_b32 m0, s65
	s_nop 0
	global_load_lds_dwordx4 v138, s[30:31] offset:0
	s_nop 0
	s_mov_b32 m0, s66
	s_nop 0
	global_load_lds_dwordx4 v140, s[30:31] offset:0
	s_add_u32 s30, s40, 0x160080
	s_addc_u32 s31, s41, 0
	s_mov_b32 m0, s69
	s_nop 0
	global_load_lds_dwordx4 v138, s[30:31] offset:0
	s_nop 0
	s_mov_b32 m0, s70
	s_nop 0
	global_load_lds_dwordx4 v140, s[30:31] offset:0
	s_nop 0
	s_mov_b32 m0, s67
	s_nop 0
	global_load_lds_dwordx4 v1, s[38:39] offset:0
	s_nop 0
	s_mov_b32 m0, s68
	s_nop 0
	global_load_lds_dwordx4 v139, s[38:39] offset:0
	s_waitcnt vmcnt(8)
	s_waitcnt lgkmcnt(0)
	s_barrier
	s_setprio 1
	s_waitcnt lgkmcnt(7)
	s_waitcnt lgkmcnt(5)
	s_waitcnt lgkmcnt(3)
	s_waitcnt lgkmcnt(1)
	s_waitcnt lgkmcnt(0)
	v_mfma_f32_16x16x32_bf16 v[74:77], v[148:151], v[180:183], v[74:77]
	v_mfma_f32_16x16x32_bf16 v[74:77], v[152:155], v[184:187], v[74:77]
	v_mfma_f32_16x16x32_bf16 v[66:69], v[156:159], v[180:183], v[66:69]
	v_mfma_f32_16x16x32_bf16 v[66:69], v[160:163], v[184:187], v[66:69]
	v_mfma_f32_16x16x32_bf16 v[50:53], v[148:151], v[188:191], v[50:53]
	v_mfma_f32_16x16x32_bf16 v[50:53], v[152:155], v[192:195], v[50:53]
	v_mfma_f32_16x16x32_bf16 v[46:49], v[156:159], v[188:191], v[46:49]
	v_mfma_f32_16x16x32_bf16 v[46:49], v[160:163], v[192:195], v[46:49]
	v_mfma_f32_16x16x32_bf16 v[34:37], v[148:151], v[196:199], v[34:37]
	v_mfma_f32_16x16x32_bf16 v[34:37], v[152:155], v[200:203], v[34:37]
	v_mfma_f32_16x16x32_bf16 v[30:33], v[156:159], v[196:199], v[30:33]
	v_mfma_f32_16x16x32_bf16 v[30:33], v[160:163], v[200:203], v[30:33]
	v_mfma_f32_16x16x32_bf16 v[18:21], v[148:151], v[204:207], v[18:21]
	v_mfma_f32_16x16x32_bf16 v[18:21], v[152:155], v[208:211], v[18:21]
	v_mfma_f32_16x16x32_bf16 v[14:17], v[156:159], v[204:207], v[14:17]
	v_mfma_f32_16x16x32_bf16 v[14:17], v[160:163], v[208:211], v[14:17]
	s_setprio 0
	s_setprio 1
	v_mfma_f32_16x16x32_bf16 v[58:61], v[164:167], v[180:183], v[58:61]
	v_mfma_f32_16x16x32_bf16 v[54:57], v[172:175], v[180:183], v[54:57]
	v_mfma_f32_16x16x32_bf16 v[42:45], v[164:167], v[188:191], v[42:45]
	v_mfma_f32_16x16x32_bf16 v[38:41], v[172:175], v[188:191], v[38:41]
	v_mfma_f32_16x16x32_bf16 v[26:29], v[164:167], v[196:199], v[26:29]
	v_mfma_f32_16x16x32_bf16 v[22:25], v[172:175], v[196:199], v[22:25]
	v_mfma_f32_16x16x32_bf16 v[8:11], v[164:167], v[204:207], v[10:13]
	v_mfma_f32_16x16x32_bf16 v[4:7], v[172:175], v[204:207], v[4:7]
	v_mfma_f32_16x16x32_bf16 v[58:61], v[168:171], v[184:187], v[58:61]
	v_mfma_f32_16x16x32_bf16 v[54:57], v[176:179], v[184:187], v[54:57]
	v_mfma_f32_16x16x32_bf16 v[42:45], v[168:171], v[192:195], v[42:45]
	v_mfma_f32_16x16x32_bf16 v[38:41], v[176:179], v[192:195], v[38:41]
	v_mfma_f32_16x16x32_bf16 v[26:29], v[168:171], v[200:203], v[26:29]
	v_mfma_f32_16x16x32_bf16 v[22:25], v[176:179], v[200:203], v[22:25]
	v_mfma_f32_16x16x32_bf16 v[10:13], v[168:171], v[208:211], v[8:11]
	v_mfma_f32_16x16x32_bf16 v[6:9], v[176:179], v[208:211], v[4:7]
	s_setprio 0
	s_barrier
	s_add_i32 s79, s79, 2
	s_add_u32 s80, s80, 0x100
	s_addc_u32 s81, s81, 0
	s_add_u32 s82, s82, 0x100
	s_addc_u32 s83, s83, 0
	s_add_u32 s36, s36, 0x100
	s_addc_u32 s37, s37, 0
	s_cmpk_gt_u32 s79, 0x55
	s_cbranch_scc0 .LBB0_872
	s_and_b64 vcc, exec, s[16:17]
	s_cbranch_vccz .LBB0_875
	s_barrier

.LBB0_1013:
	s_add_u32 s30, s40, s58
	s_addc_u32 s31, s41, 0
	s_add_u32 s42, s30, 0x100
	s_addc_u32 s43, s31, 0
	s_and_b64 s[30:31], s[54:55], exec
	s_cselect_b32 s67, s25, s43
	s_cselect_b32 s66, s94, s42
	s_add_u32 s30, s44, s58
	s_addc_u32 s31, s45, 0
	s_add_u32 s42, s30, 0x100
	s_addc_u32 s43, s31, 0
	s_add_u32 s56, s66, 0x80
	s_addc_u32 s57, s67, 0
	s_and_b64 s[30:31], s[54:55], exec
	s_cselect_b32 s69, s23, s43
	s_cselect_b32 s68, s95, s42
	s_add_u32 s30, s96, s58
	s_addc_u32 s31, s97, 0
	ds_read_b128 v[146:149], v141
	ds_read_b128 v[150:153], v141 offset:1024
	ds_read_b128 v[154:157], v141 offset:2048
	ds_read_b128 v[158:161], v141 offset:3072
	ds_read_b128 v[162:165], v142
	ds_read_b128 v[166:169], v142 offset:1024
	ds_read_b128 v[170:173], v142 offset:2048
	ds_read_b128 v[174:177], v142 offset:3072
	s_add_u32 s72, s30, 0x80
	s_addc_u32 s73, s31, 0
	s_add_u32 s70, s68, 0x10000
	s_addc_u32 s71, s69, 0
	s_add_u32 s64, s66, 0x10000
	s_addc_u32 s65, s67, 0
	s_add_u32 s58, s68, 0x80
	s_addc_u32 s59, s69, 0
	s_add_u32 s54, s68, 0x10080
	s_addc_u32 s55, s69, 0
	ds_read_b128 v[178:181], v143
	ds_read_b128 v[182:185], v143 offset:1024
	ds_read_b128 v[186:189], v143 offset:2048
	ds_read_b128 v[190:193], v143 offset:3072
	ds_read_b128 v[194:197], v143 offset:4096
	ds_read_b128 v[198:201], v143 offset:5120
	ds_read_b128 v[202:205], v143 offset:6144
	ds_read_b128 v[206:209], v143 offset:7168
	s_mov_b32 m0, s86
	s_nop 0
	global_load_lds_dwordx4 v1, s[72:73] offset:0
	s_nop 0
	s_mov_b32 m0, s87
	s_nop 0
	global_load_lds_dwordx4 v137, s[72:73] offset:0
	s_waitcnt vmcnt(8)
	s_waitcnt lgkmcnt(0)
	s_barrier
	s_setprio 1
	s_waitcnt lgkmcnt(7)
	s_waitcnt lgkmcnt(5)
	s_waitcnt lgkmcnt(3)
	s_waitcnt lgkmcnt(1)
	s_waitcnt lgkmcnt(0)
	v_mfma_f32_16x16x32_bf16 v[126:129], v[146:149], v[178:181], v[126:129]
	v_mfma_f32_16x16x32_bf16 v[126:129], v[150:153], v[182:185], v[126:129]
	v_mfma_f32_16x16x32_bf16 v[122:125], v[154:157], v[178:181], v[122:125]
	v_mfma_f32_16x16x32_bf16 v[122:125], v[158:161], v[182:185], v[122:125]
	v_mfma_f32_16x16x32_bf16 v[118:121], v[146:149], v[186:189], v[118:121]
	v_mfma_f32_16x16x32_bf16 v[118:121], v[150:153], v[190:193], v[118:121]
	v_mfma_f32_16x16x32_bf16 v[110:113], v[154:157], v[186:189], v[110:113]
	v_mfma_f32_16x16x32_bf16 v[110:113], v[158:161], v[190:193], v[110:113]
	v_mfma_f32_16x16x32_bf16 v[102:105], v[146:149], v[194:197], v[102:105]
	v_mfma_f32_16x16x32_bf16 v[102:105], v[150:153], v[198:201], v[102:105]
	v_mfma_f32_16x16x32_bf16 v[94:97], v[154:157], v[194:197], v[94:97]
	v_mfma_f32_16x16x32_bf16 v[94:97], v[158:161], v[198:201], v[94:97]
	v_mfma_f32_16x16x32_bf16 v[86:89], v[146:149], v[202:205], v[86:89]
	v_mfma_f32_16x16x32_bf16 v[86:89], v[150:153], v[206:209], v[86:89]
	v_mfma_f32_16x16x32_bf16 v[78:81], v[154:157], v[202:205], v[78:81]
	v_mfma_f32_16x16x32_bf16 v[78:81], v[158:161], v[206:209], v[78:81]
	s_setprio 0
	s_setprio 1
	v_mfma_f32_16x16x32_bf16 v[114:117], v[162:165], v[178:181], v[114:117]
	v_mfma_f32_16x16x32_bf16 v[114:117], v[166:169], v[182:185], v[114:117]
	v_mfma_f32_16x16x32_bf16 v[106:109], v[170:173], v[178:181], v[106:109]
	v_mfma_f32_16x16x32_bf16 v[106:109], v[174:177], v[182:185], v[106:109]
	v_mfma_f32_16x16x32_bf16 v[98:101], v[162:165], v[186:189], v[98:101]
	v_mfma_f32_16x16x32_bf16 v[98:101], v[166:169], v[190:193], v[98:101]
	v_mfma_f32_16x16x32_bf16 v[90:93], v[170:173], v[186:189], v[90:93]
	v_mfma_f32_16x16x32_bf16 v[90:93], v[174:177], v[190:193], v[90:93]
	v_mfma_f32_16x16x32_bf16 v[82:85], v[162:165], v[194:197], v[82:85]
	v_mfma_f32_16x16x32_bf16 v[82:85], v[166:169], v[198:201], v[82:85]
	v_mfma_f32_16x16x32_bf16 v[74:77], v[170:173], v[194:197], v[74:77]
	v_mfma_f32_16x16x32_bf16 v[74:77], v[174:177], v[198:201], v[74:77]
	v_mfma_f32_16x16x32_bf16 v[70:73], v[162:165], v[202:205], v[70:73]
	v_mfma_f32_16x16x32_bf16 v[70:73], v[166:169], v[206:209], v[70:73]
	v_mfma_f32_16x16x32_bf16 v[66:69], v[170:173], v[202:205], v[66:69]
	v_mfma_f32_16x16x32_bf16 v[66:69], v[174:177], v[206:209], v[66:69]
	s_setprio 0
	s_barrier
	ds_read_b128 v[178:181], v143 offset:16384
	ds_read_b128 v[182:185], v143 offset:17408
	ds_read_b128 v[186:189], v143 offset:18432
	ds_read_b128 v[190:193], v143 offset:19456
	ds_read_b128 v[194:197], v143 offset:20480
	ds_read_b128 v[198:201], v143 offset:21504
	ds_read_b128 v[202:205], v143 offset:22528
	ds_read_b128 v[206:209], v143 offset:23552
	s_mov_b32 m0, s39
	s_nop 0
	global_load_lds_dwordx4 v136, s[68:69] offset:0
	s_nop 0
	s_mov_b32 m0, s74
	s_nop 0
	global_load_lds_dwordx4 v138, s[68:69] offset:0
	s_nop 0
	s_mov_b32 m0, s75
	s_nop 0
	global_load_lds_dwordx4 v136, s[70:71] offset:0
	s_nop 0
	s_mov_b32 m0, s76
	s_nop 0
	global_load_lds_dwordx4 v138, s[70:71] offset:0
	s_nop 0
	s_mov_b32 m0, s53
	s_nop 0
	global_load_lds_dwordx4 v1, s[66:67] offset:0
	s_nop 0
	s_mov_b32 m0, s77
	s_nop 0
	global_load_lds_dwordx4 v137, s[66:67] offset:0
	s_waitcnt vmcnt(8)
	s_waitcnt lgkmcnt(0)
	s_barrier
	s_setprio 1
	s_waitcnt lgkmcnt(7)
	s_waitcnt lgkmcnt(5)
	s_waitcnt lgkmcnt(3)
	s_waitcnt lgkmcnt(1)
	s_waitcnt lgkmcnt(0)
	v_mfma_f32_16x16x32_bf16 v[62:65], v[146:149], v[178:181], v[62:65]
	v_mfma_f32_16x16x32_bf16 v[62:65], v[150:153], v[182:185], v[62:65]
	v_mfma_f32_16x16x32_bf16 v[58:61], v[154:157], v[178:181], v[58:61]
	v_mfma_f32_16x16x32_bf16 v[58:61], v[158:161], v[182:185], v[58:61]
	v_mfma_f32_16x16x32_bf16 v[54:57], v[146:149], v[186:189], v[54:57]
	v_mfma_f32_16x16x32_bf16 v[54:57], v[150:153], v[190:193], v[54:57]
	v_mfma_f32_16x16x32_bf16 v[46:49], v[154:157], v[186:189], v[46:49]
	v_mfma_f32_16x16x32_bf16 v[46:49], v[158:161], v[190:193], v[46:49]
	v_mfma_f32_16x16x32_bf16 v[38:41], v[146:149], v[194:197], v[38:41]
	v_mfma_f32_16x16x32_bf16 v[38:41], v[150:153], v[198:201], v[38:41]
	v_mfma_f32_16x16x32_bf16 v[30:33], v[154:157], v[194:197], v[30:33]
	v_mfma_f32_16x16x32_bf16 v[30:33], v[158:161], v[198:201], v[30:33]
	v_mfma_f32_16x16x32_bf16 v[22:25], v[146:149], v[202:205], v[22:25]
	v_mfma_f32_16x16x32_bf16 v[22:25], v[150:153], v[206:209], v[22:25]
	v_mfma_f32_16x16x32_bf16 v[14:17], v[154:157], v[202:205], v[14:17]
	v_mfma_f32_16x16x32_bf16 v[14:17], v[158:161], v[206:209], v[14:17]
	s_setprio 0
	s_setprio 1
	v_mfma_f32_16x16x32_bf16 v[50:53], v[162:165], v[178:181], v[50:53]
	v_mfma_f32_16x16x32_bf16 v[50:53], v[166:169], v[182:185], v[50:53]
	v_mfma_f32_16x16x32_bf16 v[42:45], v[170:173], v[178:181], v[42:45]
	v_mfma_f32_16x16x32_bf16 v[42:45], v[174:177], v[182:185], v[42:45]
	v_mfma_f32_16x16x32_bf16 v[34:37], v[162:165], v[186:189], v[34:37]
	v_mfma_f32_16x16x32_bf16 v[34:37], v[166:169], v[190:193], v[34:37]
	v_mfma_f32_16x16x32_bf16 v[26:29], v[170:173], v[186:189], v[26:29]
	v_mfma_f32_16x16x32_bf16 v[26:29], v[174:177], v[190:193], v[26:29]
	v_mfma_f32_16x16x32_bf16 v[18:21], v[162:165], v[194:197], v[18:21]
	v_mfma_f32_16x16x32_bf16 v[18:21], v[166:169], v[198:201], v[18:21]
	v_mfma_f32_16x16x32_bf16 v[10:13], v[170:173], v[194:197], v[10:13]
	v_mfma_f32_16x16x32_bf16 v[10:13], v[174:177], v[198:201], v[10:13]
	v_mfma_f32_16x16x32_bf16 v[6:9], v[162:165], v[202:205], v[6:9]
	v_mfma_f32_16x16x32_bf16 v[6:9], v[166:169], v[206:209], v[6:9]
	v_mfma_f32_16x16x32_bf16 v[2:5], v[170:173], v[202:205], v[2:5]
	v_mfma_f32_16x16x32_bf16 v[2:5], v[174:177], v[206:209], v[2:5]
	s_setprio 0
	s_barrier
	ds_read_b128 v[146:149], v144
	ds_read_b128 v[150:153], v144 offset:1024
	ds_read_b128 v[154:157], v144 offset:2048
	ds_read_b128 v[158:161], v144 offset:3072
	ds_read_b128 v[162:165], v145
	ds_read_b128 v[166:169], v145 offset:1024
	ds_read_b128 v[170:173], v145 offset:2048
	ds_read_b128 v[174:177], v145 offset:3072
	ds_read_b128 v[178:181], v143 offset:32768
	ds_read_b128 v[182:185], v143 offset:33792
	ds_read_b128 v[186:189], v143 offset:34816
	ds_read_b128 v[190:193], v143 offset:35840
	ds_read_b128 v[194:197], v143 offset:36864
	ds_read_b128 v[198:201], v143 offset:37888
	ds_read_b128 v[202:205], v143 offset:38912
	ds_read_b128 v[206:209], v143 offset:39936
	s_mov_b32 m0, s78
	s_nop 0
	global_load_lds_dwordx4 v1, s[64:65] offset:0
	s_nop 0
	s_mov_b32 m0, s79
	s_nop 0
	global_load_lds_dwordx4 v137, s[64:65] offset:0
	s_waitcnt vmcnt(8)
	s_waitcnt lgkmcnt(0)
	s_barrier
	s_setprio 1
	s_waitcnt lgkmcnt(7)
	s_waitcnt lgkmcnt(5)
	s_waitcnt lgkmcnt(3)
	s_waitcnt lgkmcnt(1)
	s_waitcnt lgkmcnt(0)
	v_mfma_f32_16x16x32_bf16 v[126:129], v[146:149], v[178:181], v[126:129]
	v_mfma_f32_16x16x32_bf16 v[126:129], v[150:153], v[182:185], v[126:129]
	v_mfma_f32_16x16x32_bf16 v[122:125], v[154:157], v[178:181], v[122:125]
	v_mfma_f32_16x16x32_bf16 v[122:125], v[158:161], v[182:185], v[122:125]
	v_mfma_f32_16x16x32_bf16 v[118:121], v[146:149], v[186:189], v[118:121]
	v_mfma_f32_16x16x32_bf16 v[118:121], v[150:153], v[190:193], v[118:121]
	v_mfma_f32_16x16x32_bf16 v[110:113], v[154:157], v[186:189], v[110:113]
	v_mfma_f32_16x16x32_bf16 v[110:113], v[158:161], v[190:193], v[110:113]
	v_mfma_f32_16x16x32_bf16 v[102:105], v[146:149], v[194:197], v[102:105]
	v_mfma_f32_16x16x32_bf16 v[102:105], v[150:153], v[198:201], v[102:105]
	v_mfma_f32_16x16x32_bf16 v[94:97], v[154:157], v[194:197], v[94:97]
	v_mfma_f32_16x16x32_bf16 v[94:97], v[158:161], v[198:201], v[94:97]
	v_mfma_f32_16x16x32_bf16 v[86:89], v[146:149], v[202:205], v[86:89]
	v_mfma_f32_16x16x32_bf16 v[86:89], v[150:153], v[206:209], v[86:89]
	v_mfma_f32_16x16x32_bf16 v[78:81], v[154:157], v[202:205], v[78:81]
	v_mfma_f32_16x16x32_bf16 v[78:81], v[158:161], v[206:209], v[78:81]
	s_setprio 0
	s_setprio 1
	v_mfma_f32_16x16x32_bf16 v[114:117], v[162:165], v[178:181], v[114:117]
	v_mfma_f32_16x16x32_bf16 v[114:117], v[166:169], v[182:185], v[114:117]
	v_mfma_f32_16x16x32_bf16 v[106:109], v[170:173], v[178:181], v[106:109]
	v_mfma_f32_16x16x32_bf16 v[106:109], v[174:177], v[182:185], v[106:109]
	v_mfma_f32_16x16x32_bf16 v[98:101], v[162:165], v[186:189], v[98:101]
	v_mfma_f32_16x16x32_bf16 v[98:101], v[166:169], v[190:193], v[98:101]
	v_mfma_f32_16x16x32_bf16 v[90:93], v[170:173], v[186:189], v[90:93]
	v_mfma_f32_16x16x32_bf16 v[90:93], v[174:177], v[190:193], v[90:93]
	v_mfma_f32_16x16x32_bf16 v[82:85], v[162:165], v[194:197], v[82:85]
	v_mfma_f32_16x16x32_bf16 v[82:85], v[166:169], v[198:201], v[82:85]
	v_mfma_f32_16x16x32_bf16 v[74:77], v[170:173], v[194:197], v[74:77]
	v_mfma_f32_16x16x32_bf16 v[74:77], v[174:177], v[198:201], v[74:77]
	v_mfma_f32_16x16x32_bf16 v[70:73], v[162:165], v[202:205], v[70:73]
	v_mfma_f32_16x16x32_bf16 v[70:73], v[166:169], v[206:209], v[70:73]
	v_mfma_f32_16x16x32_bf16 v[66:69], v[170:173], v[202:205], v[66:69]
	v_mfma_f32_16x16x32_bf16 v[66:69], v[174:177], v[206:209], v[66:69]
	s_setprio 0
	s_barrier
; #define PG8_KSETUP() const bool last = (t == nt - 2); const char* a1 = cA + (size_t)(t + 1) * kstep; \
;             const char* a2 = last ? nA : cA + (size_t)(t + 2) * kstep; const char* b2 = last ? nB : cB + (size_t)(t + 2) * kstep; const char* a3 = a2 + kstep; const char* b3 = b2 + kstep; \
;             if (last && has_next) S.a_ready(nxt)
; template <class Epi, class Sched, bool ALIGN_EPI = false, bool SP2 = false>
; __device__ __forceinline__ void gemm_phase(PG8_LAS unsigned char* lds, const Gemm g, const Sched& S, const Epi& E) {
;     ...
;         int t0 = 0;
;         if constexpr (SP2 && Epi::NVM == 16) { if (ui > 0) { const int t = 0; PG8_KSETUP(); PG8_KITER_SP2(24, 24); t0 = 2; } }
;         if constexpr (SP2 && Epi::NVM == 8) { if (ui > 0) { const int t = 0; PG8_KSETUP(); PG8_KITER_SP2(16, 16); t0 = 2; } }
;         for (int t = t0; t < nt; t += 2) {
;             PG8_KSETUP();
;             if constexpr (SP2) {
;             PG8_KITER_SP2(8, 8);
	ds_read_b128 v[178:181], v143 offset:49152
	ds_read_b128 v[182:185], v143 offset:50176
	ds_read_b128 v[186:189], v143 offset:51200
	ds_read_b128 v[190:193], v143 offset:52224
	ds_read_b128 v[194:197], v143 offset:53248
	ds_read_b128 v[198:201], v143 offset:54272
	ds_read_b128 v[202:205], v143 offset:55296
	ds_read_b128 v[206:209], v143 offset:56320
	s_mov_b32 m0, s80
	s_nop 0
	global_load_lds_dwordx4 v136, s[58:59] offset:0
	s_nop 0
	s_mov_b32 m0, s81
	s_nop 0
	global_load_lds_dwordx4 v138, s[58:59] offset:0
	s_nop 0
	s_mov_b32 m0, s84
	s_nop 0
	global_load_lds_dwordx4 v136, s[54:55] offset:0
	s_nop 0
	s_mov_b32 m0, s85
	s_nop 0
	global_load_lds_dwordx4 v138, s[54:55] offset:0
	s_nop 0
	s_mov_b32 m0, s82
	s_nop 0
	global_load_lds_dwordx4 v1, s[56:57] offset:0
	s_nop 0
	s_mov_b32 m0, s83
	s_nop 0
	global_load_lds_dwordx4 v137, s[56:57] offset:0
	s_waitcnt vmcnt(8)
	s_waitcnt lgkmcnt(0)
	s_barrier
	s_setprio 1
	s_waitcnt lgkmcnt(7)
	s_waitcnt lgkmcnt(5)
	s_waitcnt lgkmcnt(3)
	s_waitcnt lgkmcnt(1)
	s_waitcnt lgkmcnt(0)
	v_mfma_f32_16x16x32_bf16 v[62:65], v[146:149], v[178:181], v[62:65]
	v_mfma_f32_16x16x32_bf16 v[62:65], v[150:153], v[182:185], v[62:65]
	v_mfma_f32_16x16x32_bf16 v[58:61], v[154:157], v[178:181], v[58:61]
	v_mfma_f32_16x16x32_bf16 v[58:61], v[158:161], v[182:185], v[58:61]
	v_mfma_f32_16x16x32_bf16 v[54:57], v[146:149], v[186:189], v[54:57]
	v_mfma_f32_16x16x32_bf16 v[54:57], v[150:153], v[190:193], v[54:57]
	v_mfma_f32_16x16x32_bf16 v[46:49], v[154:157], v[186:189], v[46:49]
	v_mfma_f32_16x16x32_bf16 v[46:49], v[158:161], v[190:193], v[46:49]
	v_mfma_f32_16x16x32_bf16 v[38:41], v[146:149], v[194:197], v[38:41]
	v_mfma_f32_16x16x32_bf16 v[38:41], v[150:153], v[198:201], v[38:41]
	v_mfma_f32_16x16x32_bf16 v[30:33], v[154:157], v[194:197], v[30:33]
	v_mfma_f32_16x16x32_bf16 v[30:33], v[158:161], v[198:201], v[30:33]
	v_mfma_f32_16x16x32_bf16 v[22:25], v[146:149], v[202:205], v[22:25]
	v_mfma_f32_16x16x32_bf16 v[22:25], v[150:153], v[206:209], v[22:25]
	v_mfma_f32_16x16x32_bf16 v[14:17], v[154:157], v[202:205], v[14:17]
	v_mfma_f32_16x16x32_bf16 v[14:17], v[158:161], v[206:209], v[14:17]
	s_setprio 0
	s_setprio 1
	v_mfma_f32_16x16x32_bf16 v[50:53], v[162:165], v[178:181], v[50:53]
	v_mfma_f32_16x16x32_bf16 v[50:53], v[166:169], v[182:185], v[50:53]
	v_mfma_f32_16x16x32_bf16 v[42:45], v[170:173], v[178:181], v[42:45]
	v_mfma_f32_16x16x32_bf16 v[42:45], v[174:177], v[182:185], v[42:45]
	v_mfma_f32_16x16x32_bf16 v[34:37], v[162:165], v[186:189], v[34:37]
	v_mfma_f32_16x16x32_bf16 v[34:37], v[166:169], v[190:193], v[34:37]
	v_mfma_f32_16x16x32_bf16 v[26:29], v[170:173], v[186:189], v[26:29]
	v_mfma_f32_16x16x32_bf16 v[26:29], v[174:177], v[190:193], v[26:29]
	v_mfma_f32_16x16x32_bf16 v[18:21], v[162:165], v[194:197], v[18:21]
	v_mfma_f32_16x16x32_bf16 v[18:21], v[166:169], v[198:201], v[18:21]
	v_mfma_f32_16x16x32_bf16 v[10:13], v[170:173], v[194:197], v[10:13]
	v_mfma_f32_16x16x32_bf16 v[10:13], v[174:177], v[198:201], v[10:13]
	v_mfma_f32_16x16x32_bf16 v[6:9], v[162:165], v[202:205], v[6:9]
	v_mfma_f32_16x16x32_bf16 v[6:9], v[166:169], v[206:209], v[6:9]
	v_mfma_f32_16x16x32_bf16 v[2:5], v[170:173], v[202:205], v[2:5]
	v_mfma_f32_16x16x32_bf16 v[2:5], v[174:177], v[206:209], v[2:5]
	s_setprio 0
	s_barrier
	s_movk_i32 s58, 0x100
	s_andn2_b64 vcc, exec, s[46:47]
	s_mov_b64 s[54:55], -1
	s_mov_b64 s[46:47], 0
	s_cbranch_vccz .LBB0_1013
	s_and_b64 vcc, exec, s[14:15]
	s_cbranch_vccz .LBB0_1016
	s_barrier

.LBB0_2132:
	ds_read_b128 v[138:141], v147
	ds_read_b128 v[152:155], v147 offset:1024
	ds_read_b128 v[156:159], v147 offset:2048
	ds_read_b128 v[160:163], v147 offset:3072
	ds_read_b128 v[164:167], v148
	ds_read_b128 v[168:171], v148 offset:1024
	ds_read_b128 v[172:175], v148 offset:2048
	ds_read_b128 v[176:179], v148 offset:3072
	s_cmp_eq_u32 s86, 28
	s_cselect_b32 s64, s45, s89
	s_cselect_b32 s65, s37, s90
	s_cselect_b32 s58, s85, s87
	s_cselect_b32 s59, s29, s88
	s_add_u32 s56, s64, 0x80
	s_addc_u32 s57, s65, 0
	ds_read_b128 v[180:183], v149
	ds_read_b128 v[184:187], v149 offset:1024
	ds_read_b128 v[188:191], v149 offset:2048
	ds_read_b128 v[192:195], v149 offset:3072
	ds_read_b128 v[196:199], v149 offset:4096
	ds_read_b128 v[200:203], v149 offset:5120
	ds_read_b128 v[204:207], v149 offset:6144
	ds_read_b128 v[208:211], v149 offset:7168
	s_mov_b32 m0, s79
	s_nop 0
	global_load_lds_dwordx4 v1, s[54:55] offset:0
	s_nop 0
	s_mov_b32 m0, s80
	s_nop 0
	global_load_lds_dwordx4 v143, s[54:55] offset:0
	s_waitcnt vmcnt(8)
	s_waitcnt lgkmcnt(0)
	s_barrier
	s_setprio 1
	s_waitcnt lgkmcnt(7)
	s_waitcnt lgkmcnt(5)
	s_waitcnt lgkmcnt(3)
	s_waitcnt lgkmcnt(1)
	s_waitcnt lgkmcnt(0)
	v_mfma_f32_16x16x32_bf16 v[130:133], v[138:141], v[180:183], v[130:133]
	v_mfma_f32_16x16x32_bf16 v[130:133], v[152:155], v[184:187], v[130:133]
	v_mfma_f32_16x16x32_bf16 v[126:129], v[156:159], v[180:183], v[126:129]
	v_mfma_f32_16x16x32_bf16 v[126:129], v[160:163], v[184:187], v[126:129]
	v_mfma_f32_16x16x32_bf16 v[114:117], v[138:141], v[188:191], v[114:117]
	v_mfma_f32_16x16x32_bf16 v[114:117], v[152:155], v[192:195], v[114:117]
	v_mfma_f32_16x16x32_bf16 v[110:113], v[156:159], v[188:191], v[110:113]
	v_mfma_f32_16x16x32_bf16 v[110:113], v[160:163], v[192:195], v[110:113]
	v_mfma_f32_16x16x32_bf16 v[98:101], v[138:141], v[196:199], v[98:101]
	v_mfma_f32_16x16x32_bf16 v[98:101], v[152:155], v[200:203], v[98:101]
	v_mfma_f32_16x16x32_bf16 v[94:97], v[156:159], v[196:199], v[94:97]
	v_mfma_f32_16x16x32_bf16 v[94:97], v[160:163], v[200:203], v[94:97]
	v_mfma_f32_16x16x32_bf16 v[82:85], v[138:141], v[204:207], v[82:85]
	v_mfma_f32_16x16x32_bf16 v[82:85], v[152:155], v[208:211], v[82:85]
	v_mfma_f32_16x16x32_bf16 v[78:81], v[156:159], v[204:207], v[78:81]
	v_mfma_f32_16x16x32_bf16 v[78:81], v[160:163], v[208:211], v[78:81]
	s_setprio 0
	s_setprio 1
	v_mfma_f32_16x16x32_bf16 v[122:125], v[164:167], v[180:183], v[122:125]
	v_mfma_f32_16x16x32_bf16 v[122:125], v[168:171], v[184:187], v[122:125]
	v_mfma_f32_16x16x32_bf16 v[118:121], v[172:175], v[180:183], v[118:121]
	v_mfma_f32_16x16x32_bf16 v[118:121], v[176:179], v[184:187], v[118:121]
	v_mfma_f32_16x16x32_bf16 v[106:109], v[164:167], v[188:191], v[106:109]
	v_mfma_f32_16x16x32_bf16 v[106:109], v[168:171], v[192:195], v[106:109]
	v_mfma_f32_16x16x32_bf16 v[102:105], v[172:175], v[188:191], v[102:105]
	v_mfma_f32_16x16x32_bf16 v[102:105], v[176:179], v[192:195], v[102:105]
	v_mfma_f32_16x16x32_bf16 v[90:93], v[164:167], v[196:199], v[90:93]
	v_mfma_f32_16x16x32_bf16 v[90:93], v[168:171], v[200:203], v[90:93]
	v_mfma_f32_16x16x32_bf16 v[86:89], v[172:175], v[196:199], v[86:89]
	v_mfma_f32_16x16x32_bf16 v[86:89], v[176:179], v[200:203], v[86:89]
	v_mfma_f32_16x16x32_bf16 v[74:77], v[164:167], v[204:207], v[74:77]
	v_mfma_f32_16x16x32_bf16 v[74:77], v[168:171], v[208:211], v[74:77]
	v_mfma_f32_16x16x32_bf16 v[70:73], v[172:175], v[204:207], v[70:73]
	v_mfma_f32_16x16x32_bf16 v[70:73], v[176:179], v[208:211], v[70:73]
	s_setprio 0
	s_barrier
	ds_read_b128 v[180:183], v149 offset:16384
	ds_read_b128 v[184:187], v149 offset:17408
	ds_read_b128 v[188:191], v149 offset:18432
	ds_read_b128 v[192:195], v149 offset:19456
	ds_read_b128 v[196:199], v149 offset:20480
	ds_read_b128 v[200:203], v149 offset:21504
	ds_read_b128 v[204:207], v149 offset:22528
	ds_read_b128 v[208:211], v149 offset:23552
	s_mov_b32 m0, s47
	s_nop 0
	global_load_lds_dwordx4 v142, s[58:59] offset:0
	s_add_u32 s30, s58, 0x80000
	s_mov_b32 m0, s52
	s_nop 0
	global_load_lds_dwordx4 v144, s[58:59] offset:0
	s_addc_u32 s31, s59, 0
	s_mov_b32 m0, s53
	s_nop 0
	global_load_lds_dwordx4 v142, s[30:31] offset:0
	s_nop 0
	s_mov_b32 m0, s66
	s_nop 0
	global_load_lds_dwordx4 v144, s[30:31] offset:0
	s_nop 0
	s_mov_b32 m0, s33
	s_nop 0
	global_load_lds_dwordx4 v1, s[64:65] offset:0
	s_nop 0
	s_mov_b32 m0, s67
	s_nop 0
	global_load_lds_dwordx4 v143, s[64:65] offset:0
	s_waitcnt vmcnt(8)
	s_waitcnt lgkmcnt(0)
	s_barrier
	s_setprio 1
	s_waitcnt lgkmcnt(7)
	s_waitcnt lgkmcnt(5)
	s_waitcnt lgkmcnt(3)
	s_waitcnt lgkmcnt(1)
	s_waitcnt lgkmcnt(0)
	v_mfma_f32_16x16x32_bf16 v[66:69], v[138:141], v[180:183], v[66:69]
	v_mfma_f32_16x16x32_bf16 v[66:69], v[152:155], v[184:187], v[66:69]
	v_mfma_f32_16x16x32_bf16 v[62:65], v[156:159], v[180:183], v[62:65]
	v_mfma_f32_16x16x32_bf16 v[62:65], v[160:163], v[184:187], v[62:65]
	v_mfma_f32_16x16x32_bf16 v[50:53], v[138:141], v[188:191], v[50:53]
	v_mfma_f32_16x16x32_bf16 v[50:53], v[152:155], v[192:195], v[50:53]
	v_mfma_f32_16x16x32_bf16 v[46:49], v[156:159], v[188:191], v[46:49]
	v_mfma_f32_16x16x32_bf16 v[46:49], v[160:163], v[192:195], v[46:49]
	v_mfma_f32_16x16x32_bf16 v[34:37], v[138:141], v[196:199], v[34:37]
	v_mfma_f32_16x16x32_bf16 v[34:37], v[152:155], v[200:203], v[34:37]
	v_mfma_f32_16x16x32_bf16 v[30:33], v[156:159], v[196:199], v[30:33]
	v_mfma_f32_16x16x32_bf16 v[30:33], v[160:163], v[200:203], v[30:33]
	v_mfma_f32_16x16x32_bf16 v[18:21], v[138:141], v[204:207], v[18:21]
	v_mfma_f32_16x16x32_bf16 v[18:21], v[152:155], v[208:211], v[18:21]
	v_mfma_f32_16x16x32_bf16 v[14:17], v[156:159], v[204:207], v[14:17]
	v_mfma_f32_16x16x32_bf16 v[14:17], v[160:163], v[208:211], v[14:17]
	s_setprio 0
	s_setprio 1
	v_mfma_f32_16x16x32_bf16 v[58:61], v[164:167], v[180:183], v[58:61]
	v_mfma_f32_16x16x32_bf16 v[54:57], v[172:175], v[180:183], v[54:57]
	v_mfma_f32_16x16x32_bf16 v[42:45], v[164:167], v[188:191], v[42:45]
	v_mfma_f32_16x16x32_bf16 v[38:41], v[172:175], v[188:191], v[38:41]
	v_mfma_f32_16x16x32_bf16 v[26:29], v[164:167], v[196:199], v[26:29]
	v_mfma_f32_16x16x32_bf16 v[22:25], v[172:175], v[196:199], v[22:25]
	v_mfma_f32_16x16x32_bf16 v[10:13], v[164:167], v[204:207], v[10:13]
	v_mfma_f32_16x16x32_bf16 v[4:7], v[172:175], v[204:207], v[6:9]
	v_mfma_f32_16x16x32_bf16 v[58:61], v[168:171], v[184:187], v[58:61]
	v_mfma_f32_16x16x32_bf16 v[54:57], v[176:179], v[184:187], v[54:57]
	v_mfma_f32_16x16x32_bf16 v[42:45], v[168:171], v[192:195], v[42:45]
	v_mfma_f32_16x16x32_bf16 v[38:41], v[176:179], v[192:195], v[38:41]
	v_mfma_f32_16x16x32_bf16 v[26:29], v[168:171], v[200:203], v[26:29]
	v_mfma_f32_16x16x32_bf16 v[22:25], v[176:179], v[200:203], v[22:25]
	v_mfma_f32_16x16x32_bf16 v[10:13], v[168:171], v[208:211], v[10:13]
	v_mfma_f32_16x16x32_bf16 v[4:7], v[176:179], v[208:211], v[4:7]
	s_setprio 0
	s_barrier
	ds_read_b128 v[138:141], v150
	ds_read_b128 v[152:155], v150 offset:1024
	ds_read_b128 v[156:159], v150 offset:2048
	ds_read_b128 v[160:163], v150 offset:3072
	ds_read_b128 v[164:167], v151
	ds_read_b128 v[168:171], v151 offset:1024
	ds_read_b128 v[172:175], v151 offset:2048
	ds_read_b128 v[176:179], v151 offset:3072
	ds_read_b128 v[180:183], v149 offset:32768
	ds_read_b128 v[184:187], v149 offset:33792
	ds_read_b128 v[188:191], v149 offset:34816
	ds_read_b128 v[192:195], v149 offset:35840
	ds_read_b128 v[196:199], v149 offset:36864
	ds_read_b128 v[200:203], v149 offset:37888
	ds_read_b128 v[204:207], v149 offset:38912
	ds_read_b128 v[208:211], v149 offset:39936
	s_add_u32 s30, s64, 0x80000
	s_addc_u32 s31, s65, 0
	s_mov_b32 m0, s68
	s_nop 0
	global_load_lds_dwordx4 v1, s[30:31] offset:0
	s_nop 0
	s_mov_b32 m0, s69
	s_nop 0
	global_load_lds_dwordx4 v143, s[30:31] offset:0
	s_waitcnt vmcnt(8)
	s_waitcnt lgkmcnt(0)
	s_barrier
	s_setprio 1
	s_waitcnt lgkmcnt(7)
	s_waitcnt lgkmcnt(5)
	s_waitcnt lgkmcnt(3)
	s_waitcnt lgkmcnt(1)
	s_waitcnt lgkmcnt(0)
	v_mfma_f32_16x16x32_bf16 v[130:133], v[138:141], v[180:183], v[130:133]
	v_mfma_f32_16x16x32_bf16 v[130:133], v[152:155], v[184:187], v[130:133]
	v_mfma_f32_16x16x32_bf16 v[126:129], v[156:159], v[180:183], v[126:129]
	v_mfma_f32_16x16x32_bf16 v[126:129], v[160:163], v[184:187], v[126:129]
	v_mfma_f32_16x16x32_bf16 v[114:117], v[138:141], v[188:191], v[114:117]
	v_mfma_f32_16x16x32_bf16 v[114:117], v[152:155], v[192:195], v[114:117]
	v_mfma_f32_16x16x32_bf16 v[110:113], v[156:159], v[188:191], v[110:113]
	v_mfma_f32_16x16x32_bf16 v[110:113], v[160:163], v[192:195], v[110:113]
	v_mfma_f32_16x16x32_bf16 v[98:101], v[138:141], v[196:199], v[98:101]
	v_mfma_f32_16x16x32_bf16 v[98:101], v[152:155], v[200:203], v[98:101]
	v_mfma_f32_16x16x32_bf16 v[94:97], v[156:159], v[196:199], v[94:97]
	v_mfma_f32_16x16x32_bf16 v[94:97], v[160:163], v[200:203], v[94:97]
	v_mfma_f32_16x16x32_bf16 v[82:85], v[138:141], v[204:207], v[82:85]
	v_mfma_f32_16x16x32_bf16 v[82:85], v[152:155], v[208:211], v[82:85]
	v_mfma_f32_16x16x32_bf16 v[78:81], v[156:159], v[204:207], v[78:81]
	v_mfma_f32_16x16x32_bf16 v[78:81], v[160:163], v[208:211], v[78:81]
	s_setprio 0
	s_setprio 1
	v_mfma_f32_16x16x32_bf16 v[122:125], v[164:167], v[180:183], v[122:125]
	v_mfma_f32_16x16x32_bf16 v[122:125], v[168:171], v[184:187], v[122:125]
	v_mfma_f32_16x16x32_bf16 v[118:121], v[172:175], v[180:183], v[118:121]
	v_mfma_f32_16x16x32_bf16 v[118:121], v[176:179], v[184:187], v[118:121]
	v_mfma_f32_16x16x32_bf16 v[106:109], v[164:167], v[188:191], v[106:109]
	v_mfma_f32_16x16x32_bf16 v[106:109], v[168:171], v[192:195], v[106:109]
	v_mfma_f32_16x16x32_bf16 v[102:105], v[172:175], v[188:191], v[102:105]
	v_mfma_f32_16x16x32_bf16 v[102:105], v[176:179], v[192:195], v[102:105]
	v_mfma_f32_16x16x32_bf16 v[90:93], v[164:167], v[196:199], v[90:93]
	v_mfma_f32_16x16x32_bf16 v[90:93], v[168:171], v[200:203], v[90:93]
	v_mfma_f32_16x16x32_bf16 v[86:89], v[172:175], v[196:199], v[86:89]
	v_mfma_f32_16x16x32_bf16 v[86:89], v[176:179], v[200:203], v[86:89]
	v_mfma_f32_16x16x32_bf16 v[74:77], v[164:167], v[204:207], v[74:77]
	v_mfma_f32_16x16x32_bf16 v[74:77], v[168:171], v[208:211], v[74:77]
	v_mfma_f32_16x16x32_bf16 v[70:73], v[172:175], v[204:207], v[70:73]
	v_mfma_f32_16x16x32_bf16 v[70:73], v[176:179], v[208:211], v[70:73]
	s_setprio 0
	s_barrier
; #define PG8_KSETUP() const bool last = (t == nt - 2); const char* a1 = cA + (size_t)(t + 1) * kstep; \
;             const char* a2 = last ? nA : cA + (size_t)(t + 2) * kstep; const char* b2 = last ? nB : cB + (size_t)(t + 2) * kstep; const char* a3 = a2 + kstep; const char* b3 = b2 + kstep; \
;             if (last && has_next) S.a_ready(nxt)
; template <class Epi, class Sched, bool ALIGN_EPI = false, bool SP2 = false>
; __device__ __forceinline__ void gemm_phase(PG8_LAS unsigned char* lds, const Gemm g, const Sched& S, const Epi& E) {
;     ...
;         int t0 = 0;
;         if constexpr (SP2 && Epi::NVM == 16) { if (ui > 0) { const int t = 0; PG8_KSETUP(); PG8_KITER_SP2(24, 24); t0 = 2; } }
;         if constexpr (SP2 && Epi::NVM == 8) { if (ui > 0) { const int t = 0; PG8_KSETUP(); PG8_KITER_SP2(16, 16); t0 = 2; } }
;         for (int t = t0; t < nt; t += 2) {
;             PG8_KSETUP();
;             if constexpr (SP2) {
;             PG8_KITER_SP2(8, 8);
	ds_read_b128 v[180:183], v149 offset:49152
	ds_read_b128 v[184:187], v149 offset:50176
	ds_read_b128 v[188:191], v149 offset:51200
	ds_read_b128 v[192:195], v149 offset:52224
	ds_read_b128 v[196:199], v149 offset:53248
	ds_read_b128 v[200:203], v149 offset:54272
	ds_read_b128 v[204:207], v149 offset:55296
	ds_read_b128 v[208:211], v149 offset:56320
	s_add_u32 s30, s58, 0x80
	s_addc_u32 s31, s59, 0
	s_mov_b32 m0, s73
	s_nop 0
	global_load_lds_dwordx4 v142, s[30:31] offset:0
	s_nop 0
	s_mov_b32 m0, s74
	s_nop 0
	global_load_lds_dwordx4 v144, s[30:31] offset:0
	s_add_u32 s30, s58, 0x80080
	s_addc_u32 s31, s59, 0
	s_mov_b32 m0, s77
	s_nop 0
	global_load_lds_dwordx4 v142, s[30:31] offset:0
	s_nop 0
	s_mov_b32 m0, s78
	s_nop 0
	global_load_lds_dwordx4 v144, s[30:31] offset:0
	s_nop 0
	s_mov_b32 m0, s75
	s_nop 0
	global_load_lds_dwordx4 v1, s[56:57] offset:0
	s_nop 0
	s_mov_b32 m0, s76
	s_nop 0
	global_load_lds_dwordx4 v143, s[56:57] offset:0
	s_waitcnt vmcnt(8)
	s_waitcnt lgkmcnt(0)
	s_barrier
	s_setprio 1
	s_waitcnt lgkmcnt(7)
	s_waitcnt lgkmcnt(5)
	s_waitcnt lgkmcnt(3)
	s_waitcnt lgkmcnt(1)
	s_waitcnt lgkmcnt(0)
	v_mfma_f32_16x16x32_bf16 v[66:69], v[138:141], v[180:183], v[66:69]
	v_mfma_f32_16x16x32_bf16 v[66:69], v[152:155], v[184:187], v[66:69]
	v_mfma_f32_16x16x32_bf16 v[62:65], v[156:159], v[180:183], v[62:65]
	v_mfma_f32_16x16x32_bf16 v[62:65], v[160:163], v[184:187], v[62:65]
	v_mfma_f32_16x16x32_bf16 v[50:53], v[138:141], v[188:191], v[50:53]
	v_mfma_f32_16x16x32_bf16 v[50:53], v[152:155], v[192:195], v[50:53]
	v_mfma_f32_16x16x32_bf16 v[46:49], v[156:159], v[188:191], v[46:49]
	v_mfma_f32_16x16x32_bf16 v[46:49], v[160:163], v[192:195], v[46:49]
	v_mfma_f32_16x16x32_bf16 v[34:37], v[138:141], v[196:199], v[34:37]
	v_mfma_f32_16x16x32_bf16 v[34:37], v[152:155], v[200:203], v[34:37]
	v_mfma_f32_16x16x32_bf16 v[30:33], v[156:159], v[196:199], v[30:33]
	v_mfma_f32_16x16x32_bf16 v[30:33], v[160:163], v[200:203], v[30:33]
	v_mfma_f32_16x16x32_bf16 v[18:21], v[138:141], v[204:207], v[18:21]
	v_mfma_f32_16x16x32_bf16 v[18:21], v[152:155], v[208:211], v[18:21]
	v_mfma_f32_16x16x32_bf16 v[14:17], v[156:159], v[204:207], v[14:17]
	v_mfma_f32_16x16x32_bf16 v[14:17], v[160:163], v[208:211], v[14:17]
	s_setprio 0
	s_setprio 1
	v_mfma_f32_16x16x32_bf16 v[58:61], v[164:167], v[180:183], v[58:61]
	v_mfma_f32_16x16x32_bf16 v[54:57], v[172:175], v[180:183], v[54:57]
	v_mfma_f32_16x16x32_bf16 v[42:45], v[164:167], v[188:191], v[42:45]
	v_mfma_f32_16x16x32_bf16 v[38:41], v[172:175], v[188:191], v[38:41]
	v_mfma_f32_16x16x32_bf16 v[26:29], v[164:167], v[196:199], v[26:29]
	v_mfma_f32_16x16x32_bf16 v[22:25], v[172:175], v[196:199], v[22:25]
	v_mfma_f32_16x16x32_bf16 v[8:11], v[164:167], v[204:207], v[10:13]
	v_mfma_f32_16x16x32_bf16 v[4:7], v[172:175], v[204:207], v[4:7]
	v_mfma_f32_16x16x32_bf16 v[58:61], v[168:171], v[184:187], v[58:61]
	v_mfma_f32_16x16x32_bf16 v[54:57], v[176:179], v[184:187], v[54:57]
	v_mfma_f32_16x16x32_bf16 v[42:45], v[168:171], v[192:195], v[42:45]
	v_mfma_f32_16x16x32_bf16 v[38:41], v[176:179], v[192:195], v[38:41]
	v_mfma_f32_16x16x32_bf16 v[26:29], v[168:171], v[200:203], v[26:29]
	v_mfma_f32_16x16x32_bf16 v[22:25], v[176:179], v[200:203], v[22:25]
	v_mfma_f32_16x16x32_bf16 v[10:13], v[168:171], v[208:211], v[8:11]
	v_mfma_f32_16x16x32_bf16 v[6:9], v[176:179], v[208:211], v[4:7]
	s_setprio 0
	s_barrier
	s_add_i32 s86, s86, 2
	s_add_u32 s87, s87, 0x100
	s_addc_u32 s88, s88, 0
	s_add_u32 s89, s89, 0x100
	s_addc_u32 s90, s90, 0
	s_add_u32 s54, s54, 0x100
	s_addc_u32 s55, s55, 0
	s_cmp_gt_u32 s86, 29
	s_cbranch_scc0 .LBB0_2132
	s_and_b64 vcc, exec, s[18:19]
	s_cbranch_vccz .LBB0_2135
	s_barrier

.LBB0_2291:
	ds_read_b128 v[138:141], v152
	ds_read_b128 v[142:145], v152 offset:1024
	ds_read_b128 v[158:161], v152 offset:2048
	ds_read_b128 v[162:165], v152 offset:3072
	ds_read_b128 v[166:169], v153
	ds_read_b128 v[170:173], v153 offset:1024
	ds_read_b128 v[174:177], v153 offset:2048
	ds_read_b128 v[178:181], v153 offset:3072
	s_cmp_eq_u32 s78, 28
	s_cselect_b32 s40, s76, s81
	s_cselect_b32 s41, s19, s82
	s_cselect_b32 s38, s77, s79
	s_cselect_b32 s39, s17, s80
	s_add_u32 s36, s40, 0x80
	s_addc_u32 s37, s41, 0
	ds_read_b128 v[182:185], v154
	ds_read_b128 v[186:189], v154 offset:1024
	ds_read_b128 v[190:193], v154 offset:2048
	ds_read_b128 v[194:197], v154 offset:3072
	ds_read_b128 v[198:201], v154 offset:4096
	ds_read_b128 v[202:205], v154 offset:5120
	ds_read_b128 v[206:209], v154 offset:6144
	ds_read_b128 v[210:213], v154 offset:7168
	s_add_u32 s30, s81, 0x7ff80
	s_addc_u32 s31, s82, 0
	s_mov_b32 m0, s66
	s_nop 0
	global_load_lds_dwordx4 v1, s[30:31] offset:0
	s_nop 0
	s_mov_b32 m0, s67
	s_nop 0
	global_load_lds_dwordx4 v147, s[30:31] offset:0
	s_waitcnt vmcnt(8)
	s_waitcnt lgkmcnt(0)
	s_barrier
	s_setprio 1
	s_waitcnt lgkmcnt(0)
	v_mfma_f32_16x16x32_bf16 v[130:133], v[138:141], v[182:185], v[130:133]
	v_mfma_f32_16x16x32_bf16 v[130:133], v[142:145], v[186:189], v[130:133]
	v_mfma_f32_16x16x32_bf16 v[126:129], v[158:161], v[182:185], v[126:129]
	v_mfma_f32_16x16x32_bf16 v[126:129], v[162:165], v[186:189], v[126:129]
	v_mfma_f32_16x16x32_bf16 v[114:117], v[138:141], v[190:193], v[114:117]
	v_mfma_f32_16x16x32_bf16 v[114:117], v[142:145], v[194:197], v[114:117]
	v_mfma_f32_16x16x32_bf16 v[110:113], v[158:161], v[190:193], v[110:113]
	v_mfma_f32_16x16x32_bf16 v[110:113], v[162:165], v[194:197], v[110:113]
	v_mfma_f32_16x16x32_bf16 v[98:101], v[138:141], v[198:201], v[98:101]
	v_mfma_f32_16x16x32_bf16 v[98:101], v[142:145], v[202:205], v[98:101]
	v_mfma_f32_16x16x32_bf16 v[94:97], v[158:161], v[198:201], v[94:97]
	v_mfma_f32_16x16x32_bf16 v[94:97], v[162:165], v[202:205], v[94:97]
	v_mfma_f32_16x16x32_bf16 v[82:85], v[138:141], v[206:209], v[82:85]
	v_mfma_f32_16x16x32_bf16 v[82:85], v[142:145], v[210:213], v[82:85]
	v_mfma_f32_16x16x32_bf16 v[78:81], v[158:161], v[206:209], v[78:81]
	v_mfma_f32_16x16x32_bf16 v[78:81], v[162:165], v[210:213], v[78:81]
	s_setprio 0
	s_setprio 1
	v_mfma_f32_16x16x32_bf16 v[122:125], v[166:169], v[182:185], v[122:125]
	v_mfma_f32_16x16x32_bf16 v[122:125], v[170:173], v[186:189], v[122:125]
	v_mfma_f32_16x16x32_bf16 v[118:121], v[174:177], v[182:185], v[118:121]
	v_mfma_f32_16x16x32_bf16 v[118:121], v[178:181], v[186:189], v[118:121]
	v_mfma_f32_16x16x32_bf16 v[106:109], v[166:169], v[190:193], v[106:109]
	v_mfma_f32_16x16x32_bf16 v[106:109], v[170:173], v[194:197], v[106:109]
	v_mfma_f32_16x16x32_bf16 v[102:105], v[174:177], v[190:193], v[102:105]
	v_mfma_f32_16x16x32_bf16 v[102:105], v[178:181], v[194:197], v[102:105]
	v_mfma_f32_16x16x32_bf16 v[90:93], v[166:169], v[198:201], v[90:93]
	v_mfma_f32_16x16x32_bf16 v[90:93], v[170:173], v[202:205], v[90:93]
	v_mfma_f32_16x16x32_bf16 v[86:89], v[174:177], v[198:201], v[86:89]
	v_mfma_f32_16x16x32_bf16 v[86:89], v[178:181], v[202:205], v[86:89]
	v_mfma_f32_16x16x32_bf16 v[74:77], v[166:169], v[206:209], v[74:77]
	v_mfma_f32_16x16x32_bf16 v[74:77], v[170:173], v[210:213], v[74:77]
	v_mfma_f32_16x16x32_bf16 v[66:69], v[174:177], v[206:209], v[66:69]
	v_mfma_f32_16x16x32_bf16 v[66:69], v[178:181], v[210:213], v[66:69]
	s_setprio 0
	s_barrier
	ds_read_b128 v[182:185], v154 offset:16384
	ds_read_b128 v[186:189], v154 offset:17408
	ds_read_b128 v[190:193], v154 offset:18432
	ds_read_b128 v[194:197], v154 offset:19456
	ds_read_b128 v[198:201], v154 offset:20480
	ds_read_b128 v[202:205], v154 offset:21504
	ds_read_b128 v[206:209], v154 offset:22528
	ds_read_b128 v[210:213], v154 offset:23552
	s_mov_b32 m0, s29
	s_nop 0
	global_load_lds_dwordx4 v146, s[38:39] offset:0
	s_add_u32 s30, s38, 0x80000
	s_mov_b32 m0, s46
	s_nop 0
	global_load_lds_dwordx4 v148, s[38:39] offset:0
	s_addc_u32 s31, s39, 0
	s_mov_b32 m0, s47
	s_nop 0
	global_load_lds_dwordx4 v146, s[30:31] offset:0
	s_nop 0
	s_mov_b32 m0, s52
	s_nop 0
	global_load_lds_dwordx4 v148, s[30:31] offset:0
	s_nop 0
	s_mov_b32 m0, s21
	s_nop 0
	global_load_lds_dwordx4 v1, s[40:41] offset:0
	s_nop 0
	s_mov_b32 m0, s53
	s_nop 0
	global_load_lds_dwordx4 v147, s[40:41] offset:0
	s_waitcnt vmcnt(8)
	s_waitcnt lgkmcnt(0)
	s_barrier
	s_setprio 1
	s_waitcnt lgkmcnt(0)
	v_mfma_f32_16x16x32_bf16 v[70:73], v[138:141], v[182:185], v[70:73]
	v_mfma_f32_16x16x32_bf16 v[70:73], v[142:145], v[186:189], v[70:73]
	v_mfma_f32_16x16x32_bf16 v[62:65], v[158:161], v[182:185], v[62:65]
	v_mfma_f32_16x16x32_bf16 v[62:65], v[162:165], v[186:189], v[62:65]
	v_mfma_f32_16x16x32_bf16 v[50:53], v[138:141], v[190:193], v[50:53]
	v_mfma_f32_16x16x32_bf16 v[50:53], v[142:145], v[194:197], v[50:53]
	v_mfma_f32_16x16x32_bf16 v[46:49], v[158:161], v[190:193], v[46:49]
	v_mfma_f32_16x16x32_bf16 v[46:49], v[162:165], v[194:197], v[46:49]
	v_mfma_f32_16x16x32_bf16 v[34:37], v[138:141], v[198:201], v[34:37]
	v_mfma_f32_16x16x32_bf16 v[34:37], v[142:145], v[202:205], v[34:37]
	v_mfma_f32_16x16x32_bf16 v[30:33], v[158:161], v[198:201], v[30:33]
	v_mfma_f32_16x16x32_bf16 v[30:33], v[162:165], v[202:205], v[30:33]
	v_mfma_f32_16x16x32_bf16 v[18:21], v[138:141], v[206:209], v[18:21]
	v_mfma_f32_16x16x32_bf16 v[18:21], v[142:145], v[210:213], v[18:21]
	v_mfma_f32_16x16x32_bf16 v[14:17], v[158:161], v[206:209], v[14:17]
	v_mfma_f32_16x16x32_bf16 v[14:17], v[162:165], v[210:213], v[14:17]
	s_setprio 0
	s_setprio 1
	v_mfma_f32_16x16x32_bf16 v[58:61], v[166:169], v[182:185], v[58:61]
	v_mfma_f32_16x16x32_bf16 v[54:57], v[174:177], v[182:185], v[54:57]
	v_mfma_f32_16x16x32_bf16 v[42:45], v[166:169], v[190:193], v[42:45]
	v_mfma_f32_16x16x32_bf16 v[38:41], v[174:177], v[190:193], v[38:41]
	v_mfma_f32_16x16x32_bf16 v[26:29], v[166:169], v[198:201], v[26:29]
	v_mfma_f32_16x16x32_bf16 v[22:25], v[174:177], v[198:201], v[22:25]
	v_mfma_f32_16x16x32_bf16 v[10:13], v[166:169], v[206:209], v[10:13]
	v_mfma_f32_16x16x32_bf16 v[4:7], v[174:177], v[206:209], v[6:9]
	v_mfma_f32_16x16x32_bf16 v[58:61], v[170:173], v[186:189], v[58:61]
	v_mfma_f32_16x16x32_bf16 v[54:57], v[178:181], v[186:189], v[54:57]
	v_mfma_f32_16x16x32_bf16 v[42:45], v[170:173], v[194:197], v[42:45]
	v_mfma_f32_16x16x32_bf16 v[38:41], v[178:181], v[194:197], v[38:41]
	v_mfma_f32_16x16x32_bf16 v[26:29], v[170:173], v[202:205], v[26:29]
	v_mfma_f32_16x16x32_bf16 v[22:25], v[178:181], v[202:205], v[22:25]
	v_mfma_f32_16x16x32_bf16 v[10:13], v[170:173], v[210:213], v[10:13]
	v_mfma_f32_16x16x32_bf16 v[4:7], v[178:181], v[210:213], v[4:7]
	s_setprio 0
	s_barrier
; #define PG8_KSETUP() const bool last = (t == nt - 2); const char* a1 = cA + (size_t)(t + 1) * kstep; \
;             const char* a2 = last ? nA : cA + (size_t)(t + 2) * kstep; const char* b2 = last ? nB : cB + (size_t)(t + 2) * kstep; const char* a3 = a2 + kstep; const char* b3 = b2 + kstep; \
;             if (last && has_next) S.a_ready(nxt)
; template <class Epi, class Sched, bool ALIGN_EPI = false, bool SP2 = false>
; __device__ __forceinline__ void gemm_phase(PG8_LAS unsigned char* lds, const Gemm g, const Sched& S, const Epi& E) {
;     ...
;         int t0 = 0;
;         if constexpr (SP2 && Epi::NVM == 16) { if (ui > 0) { const int t = 0; PG8_KSETUP(); PG8_KITER_SP2(24, 24); t0 = 2; } }
;         if constexpr (SP2 && Epi::NVM == 8) { if (ui > 0) { const int t = 0; PG8_KSETUP(); PG8_KITER_SP2(16, 16); t0 = 2; } }
;         for (int t = t0; t < nt; t += 2) {
	ds_read_b128 v[138:141], v155
	ds_read_b128 v[142:145], v155 offset:1024
	ds_read_b128 v[158:161], v155 offset:2048
	ds_read_b128 v[162:165], v155 offset:3072
	ds_read_b128 v[166:169], v156
	ds_read_b128 v[170:173], v156 offset:1024
	ds_read_b128 v[174:177], v156 offset:2048
	ds_read_b128 v[178:181], v156 offset:3072
	ds_read_b128 v[182:185], v154 offset:32768
	ds_read_b128 v[186:189], v154 offset:33792
	ds_read_b128 v[190:193], v154 offset:34816
	ds_read_b128 v[194:197], v154 offset:35840
	ds_read_b128 v[198:201], v154 offset:36864
	ds_read_b128 v[202:205], v154 offset:37888
	ds_read_b128 v[206:209], v154 offset:38912
	ds_read_b128 v[210:213], v154 offset:39936
	s_add_u32 s30, s40, 0x80000
	s_addc_u32 s31, s41, 0
	s_mov_b32 m0, s54
	s_nop 0
	global_load_lds_dwordx4 v1, s[30:31] offset:0
	s_nop 0
	s_mov_b32 m0, s55
	s_nop 0
	global_load_lds_dwordx4 v147, s[30:31] offset:0
	s_waitcnt vmcnt(8)
	s_waitcnt lgkmcnt(0)
	s_barrier
	s_setprio 1
	s_waitcnt lgkmcnt(0)
	v_mfma_f32_16x16x32_bf16 v[130:133], v[138:141], v[182:185], v[130:133]
	v_mfma_f32_16x16x32_bf16 v[130:133], v[142:145], v[186:189], v[130:133]
	v_mfma_f32_16x16x32_bf16 v[126:129], v[158:161], v[182:185], v[126:129]
	v_mfma_f32_16x16x32_bf16 v[126:129], v[162:165], v[186:189], v[126:129]
	v_mfma_f32_16x16x32_bf16 v[114:117], v[138:141], v[190:193], v[114:117]
	v_mfma_f32_16x16x32_bf16 v[114:117], v[142:145], v[194:197], v[114:117]
	v_mfma_f32_16x16x32_bf16 v[110:113], v[158:161], v[190:193], v[110:113]
	v_mfma_f32_16x16x32_bf16 v[110:113], v[162:165], v[194:197], v[110:113]
	v_mfma_f32_16x16x32_bf16 v[98:101], v[138:141], v[198:201], v[98:101]
	v_mfma_f32_16x16x32_bf16 v[98:101], v[142:145], v[202:205], v[98:101]
	v_mfma_f32_16x16x32_bf16 v[94:97], v[158:161], v[198:201], v[94:97]
	v_mfma_f32_16x16x32_bf16 v[94:97], v[162:165], v[202:205], v[94:97]
	v_mfma_f32_16x16x32_bf16 v[82:85], v[138:141], v[206:209], v[82:85]
	v_mfma_f32_16x16x32_bf16 v[82:85], v[142:145], v[210:213], v[82:85]
	v_mfma_f32_16x16x32_bf16 v[78:81], v[158:161], v[206:209], v[78:81]
	v_mfma_f32_16x16x32_bf16 v[78:81], v[162:165], v[210:213], v[78:81]
	s_setprio 0
	s_setprio 1
	v_mfma_f32_16x16x32_bf16 v[122:125], v[166:169], v[182:185], v[122:125]
	v_mfma_f32_16x16x32_bf16 v[122:125], v[170:173], v[186:189], v[122:125]
	v_mfma_f32_16x16x32_bf16 v[118:121], v[174:177], v[182:185], v[118:121]
	v_mfma_f32_16x16x32_bf16 v[118:121], v[178:181], v[186:189], v[118:121]
	v_mfma_f32_16x16x32_bf16 v[106:109], v[166:169], v[190:193], v[106:109]
	v_mfma_f32_16x16x32_bf16 v[106:109], v[170:173], v[194:197], v[106:109]
	v_mfma_f32_16x16x32_bf16 v[102:105], v[174:177], v[190:193], v[102:105]
	v_mfma_f32_16x16x32_bf16 v[102:105], v[178:181], v[194:197], v[102:105]
	v_mfma_f32_16x16x32_bf16 v[90:93], v[166:169], v[198:201], v[90:93]
	v_mfma_f32_16x16x32_bf16 v[90:93], v[170:173], v[202:205], v[90:93]
	v_mfma_f32_16x16x32_bf16 v[86:89], v[174:177], v[198:201], v[86:89]
	v_mfma_f32_16x16x32_bf16 v[86:89], v[178:181], v[202:205], v[86:89]
	v_mfma_f32_16x16x32_bf16 v[74:77], v[166:169], v[206:209], v[74:77]
	v_mfma_f32_16x16x32_bf16 v[74:77], v[170:173], v[210:213], v[74:77]
	v_mfma_f32_16x16x32_bf16 v[66:69], v[174:177], v[206:209], v[66:69]
	v_mfma_f32_16x16x32_bf16 v[66:69], v[178:181], v[210:213], v[66:69]
	s_setprio 0
	s_barrier
	ds_read_b128 v[182:185], v154 offset:49152
	ds_read_b128 v[186:189], v154 offset:50176
	ds_read_b128 v[190:193], v154 offset:51200
	ds_read_b128 v[194:197], v154 offset:52224
	ds_read_b128 v[198:201], v154 offset:53248
	ds_read_b128 v[202:205], v154 offset:54272
	ds_read_b128 v[206:209], v154 offset:55296
	ds_read_b128 v[210:213], v154 offset:56320
	s_add_u32 s30, s38, 0x80
	s_addc_u32 s31, s39, 0
	s_mov_b32 m0, s56
	s_nop 0
	global_load_lds_dwordx4 v146, s[30:31] offset:0
	s_nop 0
	s_mov_b32 m0, s57
	s_nop 0
	global_load_lds_dwordx4 v148, s[30:31] offset:0
	s_add_u32 s30, s38, 0x80080
	s_addc_u32 s31, s39, 0
	s_mov_b32 m0, s64
	s_nop 0
	global_load_lds_dwordx4 v146, s[30:31] offset:0
	s_nop 0
	s_mov_b32 m0, s65
	s_nop 0
	global_load_lds_dwordx4 v148, s[30:31] offset:0
	s_nop 0
	s_mov_b32 m0, s58
	s_nop 0
	global_load_lds_dwordx4 v1, s[36:37] offset:0
	s_nop 0
	s_mov_b32 m0, s59
	s_nop 0
	global_load_lds_dwordx4 v147, s[36:37] offset:0
	s_waitcnt vmcnt(8)
	s_waitcnt lgkmcnt(0)
	s_barrier
	s_setprio 1
	s_waitcnt lgkmcnt(0)
	v_mfma_f32_16x16x32_bf16 v[70:73], v[138:141], v[182:185], v[70:73]
	v_mfma_f32_16x16x32_bf16 v[70:73], v[142:145], v[186:189], v[70:73]
	v_mfma_f32_16x16x32_bf16 v[62:65], v[158:161], v[182:185], v[62:65]
	v_mfma_f32_16x16x32_bf16 v[62:65], v[162:165], v[186:189], v[62:65]
	v_mfma_f32_16x16x32_bf16 v[50:53], v[138:141], v[190:193], v[50:53]
	v_mfma_f32_16x16x32_bf16 v[50:53], v[142:145], v[194:197], v[50:53]
	v_mfma_f32_16x16x32_bf16 v[46:49], v[158:161], v[190:193], v[46:49]
	v_mfma_f32_16x16x32_bf16 v[46:49], v[162:165], v[194:197], v[46:49]
	v_mfma_f32_16x16x32_bf16 v[34:37], v[138:141], v[198:201], v[34:37]
	v_mfma_f32_16x16x32_bf16 v[34:37], v[142:145], v[202:205], v[34:37]
	v_mfma_f32_16x16x32_bf16 v[30:33], v[158:161], v[198:201], v[30:33]
	v_mfma_f32_16x16x32_bf16 v[30:33], v[162:165], v[202:205], v[30:33]
	v_mfma_f32_16x16x32_bf16 v[18:21], v[138:141], v[206:209], v[18:21]
	v_mfma_f32_16x16x32_bf16 v[18:21], v[142:145], v[210:213], v[18:21]
	v_mfma_f32_16x16x32_bf16 v[14:17], v[158:161], v[206:209], v[14:17]
	v_mfma_f32_16x16x32_bf16 v[14:17], v[162:165], v[210:213], v[14:17]
	s_setprio 0
	s_setprio 1
	v_mfma_f32_16x16x32_bf16 v[58:61], v[166:169], v[182:185], v[58:61]
	v_mfma_f32_16x16x32_bf16 v[54:57], v[174:177], v[182:185], v[54:57]
	v_mfma_f32_16x16x32_bf16 v[42:45], v[166:169], v[190:193], v[42:45]
	v_mfma_f32_16x16x32_bf16 v[38:41], v[174:177], v[190:193], v[38:41]
	v_mfma_f32_16x16x32_bf16 v[26:29], v[166:169], v[198:201], v[26:29]
	v_mfma_f32_16x16x32_bf16 v[22:25], v[174:177], v[198:201], v[22:25]
	v_mfma_f32_16x16x32_bf16 v[8:11], v[166:169], v[206:209], v[10:13]
	v_mfma_f32_16x16x32_bf16 v[4:7], v[174:177], v[206:209], v[4:7]
	v_mfma_f32_16x16x32_bf16 v[58:61], v[170:173], v[186:189], v[58:61]
	v_mfma_f32_16x16x32_bf16 v[54:57], v[178:181], v[186:189], v[54:57]
	v_mfma_f32_16x16x32_bf16 v[42:45], v[170:173], v[194:197], v[42:45]
	v_mfma_f32_16x16x32_bf16 v[38:41], v[178:181], v[194:197], v[38:41]
	v_mfma_f32_16x16x32_bf16 v[26:29], v[170:173], v[202:205], v[26:29]
	v_mfma_f32_16x16x32_bf16 v[22:25], v[178:181], v[202:205], v[22:25]
	v_mfma_f32_16x16x32_bf16 v[10:13], v[170:173], v[210:213], v[8:11]
	v_mfma_f32_16x16x32_bf16 v[6:9], v[178:181], v[210:213], v[4:7]
	s_setprio 0
	s_barrier
	s_add_i32 s78, s78, 2
	s_add_u32 s79, s79, 0x100
	s_addc_u32 s80, s80, 0
	s_add_u32 s81, s81, 0x100
	s_addc_u32 s82, s82, 0
	s_cmp_gt_u32 s78, 29
	s_cbranch_scc0 .LBB0_2291
	s_and_b64 vcc, exec, s[14:15]
	s_cbranch_vccz .LBB0_2294
	s_barrier

.LBB0_2378:
	ds_read_b128 v[138:141], v147
	ds_read_b128 v[152:155], v147 offset:1024
	ds_read_b128 v[156:159], v147 offset:2048
	ds_read_b128 v[160:163], v147 offset:3072
	ds_read_b128 v[164:167], v148
	ds_read_b128 v[168:171], v148 offset:1024
	ds_read_b128 v[172:175], v148 offset:2048
	ds_read_b128 v[176:179], v148 offset:3072
	s_cmpk_eq_i32 s82, 0x54
	s_cselect_b32 s44, s8, s85
	s_cselect_b32 s45, s9, s86
	s_cselect_b32 s40, s28, s83
	s_cselect_b32 s41, s29, s84
	s_add_u32 s38, s44, 0x80
	s_addc_u32 s39, s45, 0
	ds_read_b128 v[180:183], v149
	ds_read_b128 v[184:187], v149 offset:1024
	ds_read_b128 v[188:191], v149 offset:2048
	ds_read_b128 v[192:195], v149 offset:3072
	ds_read_b128 v[196:199], v149 offset:4096
	ds_read_b128 v[200:203], v149 offset:5120
	ds_read_b128 v[204:207], v149 offset:6144
	ds_read_b128 v[208:211], v149 offset:7168
	s_mov_b32 m0, s72
	s_nop 0
	global_load_lds_dwordx4 v1, s[36:37] offset:0
	s_nop 0
	s_mov_b32 m0, s73
	s_nop 0
	global_load_lds_dwordx4 v143, s[36:37] offset:0
	s_waitcnt vmcnt(8)
	s_waitcnt lgkmcnt(0)
	s_barrier
	s_setprio 1
	s_waitcnt lgkmcnt(7)
	s_waitcnt lgkmcnt(5)
	s_waitcnt lgkmcnt(3)
	s_waitcnt lgkmcnt(1)
	s_waitcnt lgkmcnt(0)
	v_mfma_f32_16x16x32_bf16 v[130:133], v[138:141], v[180:183], v[130:133]
	v_mfma_f32_16x16x32_bf16 v[130:133], v[152:155], v[184:187], v[130:133]
	v_mfma_f32_16x16x32_bf16 v[126:129], v[156:159], v[180:183], v[126:129]
	v_mfma_f32_16x16x32_bf16 v[126:129], v[160:163], v[184:187], v[126:129]
	v_mfma_f32_16x16x32_bf16 v[114:117], v[138:141], v[188:191], v[114:117]
	v_mfma_f32_16x16x32_bf16 v[114:117], v[152:155], v[192:195], v[114:117]
	v_mfma_f32_16x16x32_bf16 v[110:113], v[156:159], v[188:191], v[110:113]
	v_mfma_f32_16x16x32_bf16 v[110:113], v[160:163], v[192:195], v[110:113]
	v_mfma_f32_16x16x32_bf16 v[98:101], v[138:141], v[196:199], v[98:101]
	v_mfma_f32_16x16x32_bf16 v[98:101], v[152:155], v[200:203], v[98:101]
	v_mfma_f32_16x16x32_bf16 v[94:97], v[156:159], v[196:199], v[94:97]
	v_mfma_f32_16x16x32_bf16 v[94:97], v[160:163], v[200:203], v[94:97]
	v_mfma_f32_16x16x32_bf16 v[82:85], v[138:141], v[204:207], v[82:85]
	v_mfma_f32_16x16x32_bf16 v[82:85], v[152:155], v[208:211], v[82:85]
	v_mfma_f32_16x16x32_bf16 v[78:81], v[156:159], v[204:207], v[78:81]
	v_mfma_f32_16x16x32_bf16 v[78:81], v[160:163], v[208:211], v[78:81]
	s_setprio 0
	s_setprio 1
	v_mfma_f32_16x16x32_bf16 v[122:125], v[164:167], v[180:183], v[122:125]
	v_mfma_f32_16x16x32_bf16 v[122:125], v[168:171], v[184:187], v[122:125]
	v_mfma_f32_16x16x32_bf16 v[118:121], v[172:175], v[180:183], v[118:121]
	v_mfma_f32_16x16x32_bf16 v[118:121], v[176:179], v[184:187], v[118:121]
	v_mfma_f32_16x16x32_bf16 v[106:109], v[164:167], v[188:191], v[106:109]
	v_mfma_f32_16x16x32_bf16 v[106:109], v[168:171], v[192:195], v[106:109]
	v_mfma_f32_16x16x32_bf16 v[102:105], v[172:175], v[188:191], v[102:105]
	v_mfma_f32_16x16x32_bf16 v[102:105], v[176:179], v[192:195], v[102:105]
	v_mfma_f32_16x16x32_bf16 v[90:93], v[164:167], v[196:199], v[90:93]
	v_mfma_f32_16x16x32_bf16 v[90:93], v[168:171], v[200:203], v[90:93]
	v_mfma_f32_16x16x32_bf16 v[86:89], v[172:175], v[196:199], v[86:89]
	v_mfma_f32_16x16x32_bf16 v[86:89], v[176:179], v[200:203], v[86:89]
	v_mfma_f32_16x16x32_bf16 v[74:77], v[164:167], v[204:207], v[74:77]
	v_mfma_f32_16x16x32_bf16 v[74:77], v[168:171], v[208:211], v[74:77]
	v_mfma_f32_16x16x32_bf16 v[70:73], v[172:175], v[204:207], v[70:73]
	v_mfma_f32_16x16x32_bf16 v[70:73], v[176:179], v[208:211], v[70:73]
	s_setprio 0
	s_barrier
	ds_read_b128 v[180:183], v149 offset:16384
	ds_read_b128 v[184:187], v149 offset:17408
	ds_read_b128 v[188:191], v149 offset:18432
	ds_read_b128 v[192:195], v149 offset:19456
	ds_read_b128 v[196:199], v149 offset:20480
	ds_read_b128 v[200:203], v149 offset:21504
	ds_read_b128 v[204:207], v149 offset:22528
	ds_read_b128 v[208:211], v149 offset:23552
	s_mov_b32 m0, s52
	s_nop 0
	global_load_lds_dwordx4 v142, s[40:41] offset:0
	s_add_u32 s30, s40, 0x160000
	s_mov_b32 m0, s53
	s_nop 0
	global_load_lds_dwordx4 v144, s[40:41] offset:0
	s_addc_u32 s31, s41, 0
	s_mov_b32 m0, s54
	s_nop 0
	global_load_lds_dwordx4 v142, s[30:31] offset:0
	s_nop 0
	s_mov_b32 m0, s55
	s_nop 0
	global_load_lds_dwordx4 v144, s[30:31] offset:0
	s_nop 0
	s_mov_b32 m0, s47
	s_nop 0
	global_load_lds_dwordx4 v1, s[44:45] offset:0
	s_nop 0
	s_mov_b32 m0, s56
	s_nop 0
	global_load_lds_dwordx4 v143, s[44:45] offset:0
	s_waitcnt vmcnt(8)
	s_waitcnt lgkmcnt(0)
	s_barrier
	s_setprio 1
	s_waitcnt lgkmcnt(7)
	s_waitcnt lgkmcnt(5)
	s_waitcnt lgkmcnt(3)
	s_waitcnt lgkmcnt(1)
	s_waitcnt lgkmcnt(0)
	v_mfma_f32_16x16x32_bf16 v[66:69], v[138:141], v[180:183], v[66:69]
	v_mfma_f32_16x16x32_bf16 v[66:69], v[152:155], v[184:187], v[66:69]
	v_mfma_f32_16x16x32_bf16 v[62:65], v[156:159], v[180:183], v[62:65]
	v_mfma_f32_16x16x32_bf16 v[62:65], v[160:163], v[184:187], v[62:65]
	v_mfma_f32_16x16x32_bf16 v[50:53], v[138:141], v[188:191], v[50:53]
	v_mfma_f32_16x16x32_bf16 v[50:53], v[152:155], v[192:195], v[50:53]
	v_mfma_f32_16x16x32_bf16 v[46:49], v[156:159], v[188:191], v[46:49]
	v_mfma_f32_16x16x32_bf16 v[46:49], v[160:163], v[192:195], v[46:49]
	v_mfma_f32_16x16x32_bf16 v[34:37], v[138:141], v[196:199], v[34:37]
	v_mfma_f32_16x16x32_bf16 v[34:37], v[152:155], v[200:203], v[34:37]
	v_mfma_f32_16x16x32_bf16 v[30:33], v[156:159], v[196:199], v[30:33]
	v_mfma_f32_16x16x32_bf16 v[30:33], v[160:163], v[200:203], v[30:33]
	v_mfma_f32_16x16x32_bf16 v[18:21], v[138:141], v[204:207], v[18:21]
	v_mfma_f32_16x16x32_bf16 v[18:21], v[152:155], v[208:211], v[18:21]
	v_mfma_f32_16x16x32_bf16 v[14:17], v[156:159], v[204:207], v[14:17]
	v_mfma_f32_16x16x32_bf16 v[14:17], v[160:163], v[208:211], v[14:17]
	s_setprio 0
	s_setprio 1
	v_mfma_f32_16x16x32_bf16 v[58:61], v[164:167], v[180:183], v[58:61]
	v_mfma_f32_16x16x32_bf16 v[54:57], v[172:175], v[180:183], v[54:57]
	v_mfma_f32_16x16x32_bf16 v[42:45], v[164:167], v[188:191], v[42:45]
	v_mfma_f32_16x16x32_bf16 v[38:41], v[172:175], v[188:191], v[38:41]
	v_mfma_f32_16x16x32_bf16 v[26:29], v[164:167], v[196:199], v[26:29]
	v_mfma_f32_16x16x32_bf16 v[22:25], v[172:175], v[196:199], v[22:25]
	v_mfma_f32_16x16x32_bf16 v[10:13], v[164:167], v[204:207], v[10:13]
	v_mfma_f32_16x16x32_bf16 v[4:7], v[172:175], v[204:207], v[6:9]
	v_mfma_f32_16x16x32_bf16 v[58:61], v[168:171], v[184:187], v[58:61]
	v_mfma_f32_16x16x32_bf16 v[54:57], v[176:179], v[184:187], v[54:57]
	v_mfma_f32_16x16x32_bf16 v[42:45], v[168:171], v[192:195], v[42:45]
	v_mfma_f32_16x16x32_bf16 v[38:41], v[176:179], v[192:195], v[38:41]
	v_mfma_f32_16x16x32_bf16 v[26:29], v[168:171], v[200:203], v[26:29]
	v_mfma_f32_16x16x32_bf16 v[22:25], v[176:179], v[200:203], v[22:25]
	v_mfma_f32_16x16x32_bf16 v[10:13], v[168:171], v[208:211], v[10:13]
	v_mfma_f32_16x16x32_bf16 v[4:7], v[176:179], v[208:211], v[4:7]
	s_setprio 0
	s_barrier
	ds_read_b128 v[138:141], v150
	ds_read_b128 v[152:155], v150 offset:1024
	ds_read_b128 v[156:159], v150 offset:2048
	ds_read_b128 v[160:163], v150 offset:3072
	ds_read_b128 v[164:167], v151
	ds_read_b128 v[168:171], v151 offset:1024
	ds_read_b128 v[172:175], v151 offset:2048
	ds_read_b128 v[176:179], v151 offset:3072
	ds_read_b128 v[180:183], v149 offset:32768
	ds_read_b128 v[184:187], v149 offset:33792
	ds_read_b128 v[188:191], v149 offset:34816
	ds_read_b128 v[192:195], v149 offset:35840
	ds_read_b128 v[196:199], v149 offset:36864
	ds_read_b128 v[200:203], v149 offset:37888
	ds_read_b128 v[204:207], v149 offset:38912
	ds_read_b128 v[208:211], v149 offset:39936
	s_add_u32 s30, s44, 0x160000
	s_addc_u32 s31, s45, 0
	s_mov_b32 m0, s57
	s_nop 0
	global_load_lds_dwordx4 v1, s[30:31] offset:0
	s_nop 0
	s_mov_b32 m0, s58
	s_nop 0
	global_load_lds_dwordx4 v143, s[30:31] offset:0
	s_waitcnt vmcnt(8)
	s_waitcnt lgkmcnt(0)
	s_barrier
	s_setprio 1
	s_waitcnt lgkmcnt(7)
	s_waitcnt lgkmcnt(5)
	s_waitcnt lgkmcnt(3)
	s_waitcnt lgkmcnt(1)
	s_waitcnt lgkmcnt(0)
	v_mfma_f32_16x16x32_bf16 v[130:133], v[138:141], v[180:183], v[130:133]
	v_mfma_f32_16x16x32_bf16 v[130:133], v[152:155], v[184:187], v[130:133]
	v_mfma_f32_16x16x32_bf16 v[126:129], v[156:159], v[180:183], v[126:129]
	v_mfma_f32_16x16x32_bf16 v[126:129], v[160:163], v[184:187], v[126:129]
	v_mfma_f32_16x16x32_bf16 v[114:117], v[138:141], v[188:191], v[114:117]
	v_mfma_f32_16x16x32_bf16 v[114:117], v[152:155], v[192:195], v[114:117]
	v_mfma_f32_16x16x32_bf16 v[110:113], v[156:159], v[188:191], v[110:113]
	v_mfma_f32_16x16x32_bf16 v[110:113], v[160:163], v[192:195], v[110:113]
	v_mfma_f32_16x16x32_bf16 v[98:101], v[138:141], v[196:199], v[98:101]
	v_mfma_f32_16x16x32_bf16 v[98:101], v[152:155], v[200:203], v[98:101]
	v_mfma_f32_16x16x32_bf16 v[94:97], v[156:159], v[196:199], v[94:97]
	v_mfma_f32_16x16x32_bf16 v[94:97], v[160:163], v[200:203], v[94:97]
	v_mfma_f32_16x16x32_bf16 v[82:85], v[138:141], v[204:207], v[82:85]
	v_mfma_f32_16x16x32_bf16 v[82:85], v[152:155], v[208:211], v[82:85]
	v_mfma_f32_16x16x32_bf16 v[78:81], v[156:159], v[204:207], v[78:81]
	v_mfma_f32_16x16x32_bf16 v[78:81], v[160:163], v[208:211], v[78:81]
	s_setprio 0
	s_setprio 1
	v_mfma_f32_16x16x32_bf16 v[122:125], v[164:167], v[180:183], v[122:125]
	v_mfma_f32_16x16x32_bf16 v[122:125], v[168:171], v[184:187], v[122:125]
	v_mfma_f32_16x16x32_bf16 v[118:121], v[172:175], v[180:183], v[118:121]
	v_mfma_f32_16x16x32_bf16 v[118:121], v[176:179], v[184:187], v[118:121]
	v_mfma_f32_16x16x32_bf16 v[106:109], v[164:167], v[188:191], v[106:109]
	v_mfma_f32_16x16x32_bf16 v[106:109], v[168:171], v[192:195], v[106:109]
	v_mfma_f32_16x16x32_bf16 v[102:105], v[172:175], v[188:191], v[102:105]
	v_mfma_f32_16x16x32_bf16 v[102:105], v[176:179], v[192:195], v[102:105]
	v_mfma_f32_16x16x32_bf16 v[90:93], v[164:167], v[196:199], v[90:93]
	v_mfma_f32_16x16x32_bf16 v[90:93], v[168:171], v[200:203], v[90:93]
	v_mfma_f32_16x16x32_bf16 v[86:89], v[172:175], v[196:199], v[86:89]
	v_mfma_f32_16x16x32_bf16 v[86:89], v[176:179], v[200:203], v[86:89]
	v_mfma_f32_16x16x32_bf16 v[74:77], v[164:167], v[204:207], v[74:77]
	v_mfma_f32_16x16x32_bf16 v[74:77], v[168:171], v[208:211], v[74:77]
	v_mfma_f32_16x16x32_bf16 v[70:73], v[172:175], v[204:207], v[70:73]
	v_mfma_f32_16x16x32_bf16 v[70:73], v[176:179], v[208:211], v[70:73]
	s_setprio 0
	s_barrier
; #define PG8_KSETUP() const bool last = (t == nt - 2); const char* a1 = cA + (size_t)(t + 1) * kstep; \
;             const char* a2 = last ? nA : cA + (size_t)(t + 2) * kstep; const char* b2 = last ? nB : cB + (size_t)(t + 2) * kstep; const char* a3 = a2 + kstep; const char* b3 = b2 + kstep; \
;             if (last && has_next) S.a_ready(nxt)
; template <class Epi, class Sched, bool ALIGN_EPI = false, bool SP2 = false>
; __device__ __forceinline__ void gemm_phase(PG8_LAS unsigned char* lds, const Gemm g, const Sched& S, const Epi& E) {
;     ...
;         int t0 = 0;
;         if constexpr (SP2 && Epi::NVM == 16) { if (ui > 0) { const int t = 0; PG8_KSETUP(); PG8_KITER_SP2(24, 24); t0 = 2; } }
;         if constexpr (SP2 && Epi::NVM == 8) { if (ui > 0) { const int t = 0; PG8_KSETUP(); PG8_KITER_SP2(16, 16); t0 = 2; } }
;         for (int t = t0; t < nt; t += 2) {
	ds_read_b128 v[180:183], v149 offset:49152
	ds_read_b128 v[184:187], v149 offset:50176
	ds_read_b128 v[188:191], v149 offset:51200
	ds_read_b128 v[192:195], v149 offset:52224
	ds_read_b128 v[196:199], v149 offset:53248
	ds_read_b128 v[200:203], v149 offset:54272
	ds_read_b128 v[204:207], v149 offset:55296
	ds_read_b128 v[208:211], v149 offset:56320
	s_add_u32 s30, s40, 0x80
	s_addc_u32 s31, s41, 0
	s_mov_b32 m0, s66
	s_nop 0
	global_load_lds_dwordx4 v142, s[30:31] offset:0
	s_nop 0
	s_mov_b32 m0, s67
	s_nop 0
	global_load_lds_dwordx4 v144, s[30:31] offset:0
	s_add_u32 s30, s40, 0x160080
	s_addc_u32 s31, s41, 0
	s_mov_b32 m0, s70
	s_nop 0
	global_load_lds_dwordx4 v142, s[30:31] offset:0
	s_nop 0
	s_mov_b32 m0, s71
	s_nop 0
	global_load_lds_dwordx4 v144, s[30:31] offset:0
	s_nop 0
	s_mov_b32 m0, s68
	s_nop 0
	global_load_lds_dwordx4 v1, s[38:39] offset:0
	s_nop 0
	s_mov_b32 m0, s69
	s_nop 0
	global_load_lds_dwordx4 v143, s[38:39] offset:0
	s_waitcnt vmcnt(8)
	s_waitcnt lgkmcnt(0)
	s_barrier
	s_setprio 1
	s_waitcnt lgkmcnt(7)
	s_waitcnt lgkmcnt(5)
	s_waitcnt lgkmcnt(3)
	s_waitcnt lgkmcnt(1)
	s_waitcnt lgkmcnt(0)
	v_mfma_f32_16x16x32_bf16 v[66:69], v[138:141], v[180:183], v[66:69]
	v_mfma_f32_16x16x32_bf16 v[66:69], v[152:155], v[184:187], v[66:69]
	v_mfma_f32_16x16x32_bf16 v[62:65], v[156:159], v[180:183], v[62:65]
	v_mfma_f32_16x16x32_bf16 v[62:65], v[160:163], v[184:187], v[62:65]
	v_mfma_f32_16x16x32_bf16 v[50:53], v[138:141], v[188:191], v[50:53]
	v_mfma_f32_16x16x32_bf16 v[50:53], v[152:155], v[192:195], v[50:53]
	v_mfma_f32_16x16x32_bf16 v[46:49], v[156:159], v[188:191], v[46:49]
	v_mfma_f32_16x16x32_bf16 v[46:49], v[160:163], v[192:195], v[46:49]
	v_mfma_f32_16x16x32_bf16 v[34:37], v[138:141], v[196:199], v[34:37]
	v_mfma_f32_16x16x32_bf16 v[34:37], v[152:155], v[200:203], v[34:37]
	v_mfma_f32_16x16x32_bf16 v[30:33], v[156:159], v[196:199], v[30:33]
	v_mfma_f32_16x16x32_bf16 v[30:33], v[160:163], v[200:203], v[30:33]
	v_mfma_f32_16x16x32_bf16 v[18:21], v[138:141], v[204:207], v[18:21]
	v_mfma_f32_16x16x32_bf16 v[18:21], v[152:155], v[208:211], v[18:21]
	v_mfma_f32_16x16x32_bf16 v[14:17], v[156:159], v[204:207], v[14:17]
	v_mfma_f32_16x16x32_bf16 v[14:17], v[160:163], v[208:211], v[14:17]
	s_setprio 0
	s_setprio 1
	v_mfma_f32_16x16x32_bf16 v[58:61], v[164:167], v[180:183], v[58:61]
	v_mfma_f32_16x16x32_bf16 v[54:57], v[172:175], v[180:183], v[54:57]
	v_mfma_f32_16x16x32_bf16 v[42:45], v[164:167], v[188:191], v[42:45]
	v_mfma_f32_16x16x32_bf16 v[38:41], v[172:175], v[188:191], v[38:41]
	v_mfma_f32_16x16x32_bf16 v[26:29], v[164:167], v[196:199], v[26:29]
	v_mfma_f32_16x16x32_bf16 v[22:25], v[172:175], v[196:199], v[22:25]
	v_mfma_f32_16x16x32_bf16 v[8:11], v[164:167], v[204:207], v[10:13]
	v_mfma_f32_16x16x32_bf16 v[4:7], v[172:175], v[204:207], v[4:7]
	v_mfma_f32_16x16x32_bf16 v[58:61], v[168:171], v[184:187], v[58:61]
	v_mfma_f32_16x16x32_bf16 v[54:57], v[176:179], v[184:187], v[54:57]
	v_mfma_f32_16x16x32_bf16 v[42:45], v[168:171], v[192:195], v[42:45]
	v_mfma_f32_16x16x32_bf16 v[38:41], v[176:179], v[192:195], v[38:41]
	v_mfma_f32_16x16x32_bf16 v[26:29], v[168:171], v[200:203], v[26:29]
	v_mfma_f32_16x16x32_bf16 v[22:25], v[176:179], v[200:203], v[22:25]
	v_mfma_f32_16x16x32_bf16 v[10:13], v[168:171], v[208:211], v[8:11]
	v_mfma_f32_16x16x32_bf16 v[6:9], v[176:179], v[208:211], v[4:7]
	s_setprio 0
	s_barrier
	s_add_i32 s82, s82, 2
	s_add_u32 s83, s83, 0x100
	s_addc_u32 s84, s84, 0
	s_add_u32 s85, s85, 0x100
	s_addc_u32 s86, s86, 0
	s_add_u32 s36, s36, 0x100
	s_addc_u32 s37, s37, 0
	s_cmpk_gt_u32 s82, 0x55
	s_cbranch_scc0 .LBB0_2378
	s_and_b64 vcc, exec, s[16:17]
	s_cbranch_vccz .LBB0_2381
	s_barrier

.LBB0_2536:
	ds_read_b128 v[160:163], v155
	ds_read_b128 v[168:171], v155 offset:1024
	ds_read_b128 v[172:175], v155 offset:2048
	ds_read_b128 v[176:179], v155 offset:3072
	ds_read_b128 v[180:183], v159
	ds_read_b128 v[184:187], v159 offset:1024
	ds_read_b128 v[188:191], v159 offset:2048
	ds_read_b128 v[192:195], v159 offset:3072
	s_cmp_eq_u32 s91, 28
	s_cselect_b32 s56, s45, s89
	s_cselect_b32 s57, s37, s90
	s_cselect_b32 s54, s86, s87
	s_cselect_b32 s55, s29, s88
	s_add_u32 s46, s56, 0x80
	s_addc_u32 s47, s57, 0
	ds_read_b128 v[196:199], v164
	ds_read_b128 v[200:203], v164 offset:1024
	ds_read_b128 v[204:207], v164 offset:2048
	ds_read_b128 v[208:211], v164 offset:3072
	ds_read_b128 v[212:215], v164 offset:4096
	ds_read_b128 v[216:219], v164 offset:5120
	ds_read_b128 v[220:223], v164 offset:6144
	ds_read_b128 v[224:227], v164 offset:7168
	s_add_u32 s30, s89, 0x7ff80
	s_addc_u32 s31, s90, 0
	s_mov_b32 m0, s78
	s_nop 0
	global_load_lds_dwordx4 v1, s[30:31] offset:0
	s_nop 0
	s_mov_b32 m0, s79
	s_nop 0
	global_load_lds_dwordx4 v139, s[30:31] offset:0
	s_waitcnt vmcnt(8)
	s_waitcnt lgkmcnt(0)
	s_barrier
	s_setprio 1
	s_waitcnt lgkmcnt(7)
	s_waitcnt lgkmcnt(5)
	s_waitcnt lgkmcnt(3)
	s_waitcnt lgkmcnt(1)
	s_waitcnt lgkmcnt(0)
	v_mfma_f32_16x16x32_bf16 v[126:129], v[160:163], v[196:199], v[126:129]
	v_mfma_f32_16x16x32_bf16 v[126:129], v[168:171], v[200:203], v[126:129]
	v_mfma_f32_16x16x32_bf16 v[122:125], v[172:175], v[196:199], v[122:125]
	v_mfma_f32_16x16x32_bf16 v[122:125], v[176:179], v[200:203], v[122:125]
	v_mfma_f32_16x16x32_bf16 v[114:117], v[160:163], v[204:207], v[114:117]
	v_mfma_f32_16x16x32_bf16 v[114:117], v[168:171], v[208:211], v[114:117]
	v_mfma_f32_16x16x32_bf16 v[106:109], v[172:175], v[204:207], v[106:109]
	v_mfma_f32_16x16x32_bf16 v[106:109], v[176:179], v[208:211], v[106:109]
	v_mfma_f32_16x16x32_bf16 v[98:101], v[160:163], v[212:215], v[98:101]
	v_mfma_f32_16x16x32_bf16 v[98:101], v[168:171], v[216:219], v[98:101]
	v_mfma_f32_16x16x32_bf16 v[90:93], v[172:175], v[212:215], v[90:93]
	v_mfma_f32_16x16x32_bf16 v[90:93], v[176:179], v[216:219], v[90:93]
	v_mfma_f32_16x16x32_bf16 v[82:85], v[160:163], v[220:223], v[82:85]
	v_mfma_f32_16x16x32_bf16 v[82:85], v[168:171], v[224:227], v[82:85]
	v_mfma_f32_16x16x32_bf16 v[74:77], v[172:175], v[220:223], v[74:77]
	v_mfma_f32_16x16x32_bf16 v[74:77], v[176:179], v[224:227], v[74:77]
	s_setprio 0
	s_setprio 1
	v_mfma_f32_16x16x32_bf16 v[118:121], v[180:183], v[196:199], v[118:121]
	v_mfma_f32_16x16x32_bf16 v[118:121], v[184:187], v[200:203], v[118:121]
	v_mfma_f32_16x16x32_bf16 v[110:113], v[188:191], v[196:199], v[110:113]
	v_mfma_f32_16x16x32_bf16 v[110:113], v[192:195], v[200:203], v[110:113]
	v_mfma_f32_16x16x32_bf16 v[102:105], v[180:183], v[204:207], v[102:105]
	v_mfma_f32_16x16x32_bf16 v[102:105], v[184:187], v[208:211], v[102:105]
	v_mfma_f32_16x16x32_bf16 v[94:97], v[188:191], v[204:207], v[94:97]
	v_mfma_f32_16x16x32_bf16 v[94:97], v[192:195], v[208:211], v[94:97]
	v_mfma_f32_16x16x32_bf16 v[86:89], v[180:183], v[212:215], v[86:89]
	v_mfma_f32_16x16x32_bf16 v[86:89], v[184:187], v[216:219], v[86:89]
	v_mfma_f32_16x16x32_bf16 v[78:81], v[188:191], v[212:215], v[78:81]
	v_mfma_f32_16x16x32_bf16 v[78:81], v[192:195], v[216:219], v[78:81]
	v_mfma_f32_16x16x32_bf16 v[70:73], v[180:183], v[220:223], v[70:73]
	v_mfma_f32_16x16x32_bf16 v[70:73], v[184:187], v[224:227], v[70:73]
	v_mfma_f32_16x16x32_bf16 v[66:69], v[188:191], v[220:223], v[66:69]
	v_mfma_f32_16x16x32_bf16 v[66:69], v[192:195], v[224:227], v[66:69]
	s_setprio 0
	s_barrier
	ds_read_b128 v[196:199], v164 offset:16384
	ds_read_b128 v[200:203], v164 offset:17408
	ds_read_b128 v[204:207], v164 offset:18432
	ds_read_b128 v[208:211], v164 offset:19456
	ds_read_b128 v[212:215], v164 offset:20480
	ds_read_b128 v[216:219], v164 offset:21504
	ds_read_b128 v[220:223], v164 offset:22528
	ds_read_b128 v[224:227], v164 offset:23552
	s_mov_b32 m0, s64
	s_nop 0
	global_load_lds_dwordx4 v137, s[54:55] offset:0
	s_add_u32 s30, s54, 0x80000
	s_mov_b32 m0, s65
	s_nop 0
	global_load_lds_dwordx4 v141, s[54:55] offset:0
	s_addc_u32 s31, s55, 0
	s_mov_b32 m0, s66
	s_nop 0
	global_load_lds_dwordx4 v137, s[30:31] offset:0
	s_nop 0
	s_mov_b32 m0, s67
	s_nop 0
	global_load_lds_dwordx4 v141, s[30:31] offset:0
	s_nop 0
	s_mov_b32 m0, s53
	s_nop 0
	global_load_lds_dwordx4 v1, s[56:57] offset:0
	s_nop 0
	s_mov_b32 m0, s68
	s_nop 0
	global_load_lds_dwordx4 v139, s[56:57] offset:0
	s_waitcnt vmcnt(8)
	s_waitcnt lgkmcnt(0)
	s_barrier
	s_setprio 1
	s_waitcnt lgkmcnt(7)
	s_waitcnt lgkmcnt(5)
	s_waitcnt lgkmcnt(3)
	s_waitcnt lgkmcnt(1)
	s_waitcnt lgkmcnt(0)
	v_mfma_f32_16x16x32_bf16 v[62:65], v[160:163], v[196:199], v[62:65]
	v_mfma_f32_16x16x32_bf16 v[62:65], v[168:171], v[200:203], v[62:65]
	v_mfma_f32_16x16x32_bf16 v[58:61], v[172:175], v[196:199], v[58:61]
	v_mfma_f32_16x16x32_bf16 v[58:61], v[176:179], v[200:203], v[58:61]
	v_mfma_f32_16x16x32_bf16 v[50:53], v[160:163], v[204:207], v[50:53]
	v_mfma_f32_16x16x32_bf16 v[50:53], v[168:171], v[208:211], v[50:53]
	v_mfma_f32_16x16x32_bf16 v[42:45], v[172:175], v[204:207], v[42:45]
	v_mfma_f32_16x16x32_bf16 v[42:45], v[176:179], v[208:211], v[42:45]
	v_mfma_f32_16x16x32_bf16 v[34:37], v[160:163], v[212:215], v[34:37]
	v_mfma_f32_16x16x32_bf16 v[34:37], v[168:171], v[216:219], v[34:37]
	v_mfma_f32_16x16x32_bf16 v[26:29], v[172:175], v[212:215], v[26:29]
	v_mfma_f32_16x16x32_bf16 v[26:29], v[176:179], v[216:219], v[26:29]
	v_mfma_f32_16x16x32_bf16 v[18:21], v[160:163], v[220:223], v[18:21]
	v_mfma_f32_16x16x32_bf16 v[18:21], v[168:171], v[224:227], v[18:21]
	v_mfma_f32_16x16x32_bf16 v[10:13], v[172:175], v[220:223], v[10:13]
	v_mfma_f32_16x16x32_bf16 v[10:13], v[176:179], v[224:227], v[10:13]
	s_setprio 0
	s_setprio 1
	v_mfma_f32_16x16x32_bf16 v[54:57], v[180:183], v[196:199], v[54:57]
	v_mfma_f32_16x16x32_bf16 v[54:57], v[184:187], v[200:203], v[54:57]
	v_mfma_f32_16x16x32_bf16 v[46:49], v[188:191], v[196:199], v[46:49]
	v_mfma_f32_16x16x32_bf16 v[46:49], v[192:195], v[200:203], v[46:49]
	v_mfma_f32_16x16x32_bf16 v[38:41], v[180:183], v[204:207], v[38:41]
	v_mfma_f32_16x16x32_bf16 v[38:41], v[184:187], v[208:211], v[38:41]
	v_mfma_f32_16x16x32_bf16 v[30:33], v[188:191], v[204:207], v[30:33]
	v_mfma_f32_16x16x32_bf16 v[30:33], v[192:195], v[208:211], v[30:33]
	v_mfma_f32_16x16x32_bf16 v[22:25], v[180:183], v[212:215], v[22:25]
	v_mfma_f32_16x16x32_bf16 v[22:25], v[184:187], v[216:219], v[22:25]
	v_mfma_f32_16x16x32_bf16 v[14:17], v[188:191], v[212:215], v[14:17]
	v_mfma_f32_16x16x32_bf16 v[14:17], v[192:195], v[216:219], v[14:17]
	v_mfma_f32_16x16x32_bf16 v[6:9], v[180:183], v[220:223], v[6:9]
	v_mfma_f32_16x16x32_bf16 v[6:9], v[184:187], v[224:227], v[6:9]
	v_mfma_f32_16x16x32_bf16 v[2:5], v[188:191], v[220:223], v[2:5]
	v_mfma_f32_16x16x32_bf16 v[2:5], v[192:195], v[224:227], v[2:5]
	s_setprio 0
	s_barrier
	ds_read_b128 v[160:163], v165
	ds_read_b128 v[168:171], v165 offset:1024
	ds_read_b128 v[172:175], v165 offset:2048
	ds_read_b128 v[176:179], v165 offset:3072
	ds_read_b128 v[180:183], v166
	ds_read_b128 v[184:187], v166 offset:1024
	ds_read_b128 v[188:191], v166 offset:2048
	ds_read_b128 v[192:195], v166 offset:3072
	ds_read_b128 v[196:199], v164 offset:32768
	ds_read_b128 v[200:203], v164 offset:33792
	ds_read_b128 v[204:207], v164 offset:34816
	ds_read_b128 v[208:211], v164 offset:35840
	ds_read_b128 v[212:215], v164 offset:36864
	ds_read_b128 v[216:219], v164 offset:37888
	ds_read_b128 v[220:223], v164 offset:38912
	ds_read_b128 v[224:227], v164 offset:39936
	s_add_u32 s30, s56, 0x80000
	s_addc_u32 s31, s57, 0
	s_mov_b32 m0, s69
	s_nop 0
	global_load_lds_dwordx4 v1, s[30:31] offset:0
	s_nop 0
	s_mov_b32 m0, s70
	s_nop 0
	global_load_lds_dwordx4 v139, s[30:31] offset:0
	s_waitcnt vmcnt(8)
	s_waitcnt lgkmcnt(0)
	s_barrier
	s_setprio 1
	s_waitcnt lgkmcnt(7)
	s_waitcnt lgkmcnt(5)
	s_waitcnt lgkmcnt(3)
	s_waitcnt lgkmcnt(1)
	s_waitcnt lgkmcnt(0)
	v_mfma_f32_16x16x32_bf16 v[126:129], v[160:163], v[196:199], v[126:129]
	v_mfma_f32_16x16x32_bf16 v[126:129], v[168:171], v[200:203], v[126:129]
	v_mfma_f32_16x16x32_bf16 v[122:125], v[172:175], v[196:199], v[122:125]
	v_mfma_f32_16x16x32_bf16 v[122:125], v[176:179], v[200:203], v[122:125]
	v_mfma_f32_16x16x32_bf16 v[114:117], v[160:163], v[204:207], v[114:117]
	v_mfma_f32_16x16x32_bf16 v[114:117], v[168:171], v[208:211], v[114:117]
	v_mfma_f32_16x16x32_bf16 v[106:109], v[172:175], v[204:207], v[106:109]
	v_mfma_f32_16x16x32_bf16 v[106:109], v[176:179], v[208:211], v[106:109]
	v_mfma_f32_16x16x32_bf16 v[98:101], v[160:163], v[212:215], v[98:101]
	v_mfma_f32_16x16x32_bf16 v[98:101], v[168:171], v[216:219], v[98:101]
	v_mfma_f32_16x16x32_bf16 v[90:93], v[172:175], v[212:215], v[90:93]
	v_mfma_f32_16x16x32_bf16 v[90:93], v[176:179], v[216:219], v[90:93]
	v_mfma_f32_16x16x32_bf16 v[82:85], v[160:163], v[220:223], v[82:85]
	v_mfma_f32_16x16x32_bf16 v[82:85], v[168:171], v[224:227], v[82:85]
	v_mfma_f32_16x16x32_bf16 v[74:77], v[172:175], v[220:223], v[74:77]
	v_mfma_f32_16x16x32_bf16 v[74:77], v[176:179], v[224:227], v[74:77]
	s_setprio 0
	s_setprio 1
	v_mfma_f32_16x16x32_bf16 v[118:121], v[180:183], v[196:199], v[118:121]
	v_mfma_f32_16x16x32_bf16 v[118:121], v[184:187], v[200:203], v[118:121]
	v_mfma_f32_16x16x32_bf16 v[110:113], v[188:191], v[196:199], v[110:113]
	v_mfma_f32_16x16x32_bf16 v[110:113], v[192:195], v[200:203], v[110:113]
	v_mfma_f32_16x16x32_bf16 v[102:105], v[180:183], v[204:207], v[102:105]
	v_mfma_f32_16x16x32_bf16 v[102:105], v[184:187], v[208:211], v[102:105]
	v_mfma_f32_16x16x32_bf16 v[94:97], v[188:191], v[204:207], v[94:97]
	v_mfma_f32_16x16x32_bf16 v[94:97], v[192:195], v[208:211], v[94:97]
	v_mfma_f32_16x16x32_bf16 v[86:89], v[180:183], v[212:215], v[86:89]
	v_mfma_f32_16x16x32_bf16 v[86:89], v[184:187], v[216:219], v[86:89]
	v_mfma_f32_16x16x32_bf16 v[78:81], v[188:191], v[212:215], v[78:81]
	v_mfma_f32_16x16x32_bf16 v[78:81], v[192:195], v[216:219], v[78:81]
	v_mfma_f32_16x16x32_bf16 v[70:73], v[180:183], v[220:223], v[70:73]
	v_mfma_f32_16x16x32_bf16 v[70:73], v[184:187], v[224:227], v[70:73]
	v_mfma_f32_16x16x32_bf16 v[66:69], v[188:191], v[220:223], v[66:69]
	v_mfma_f32_16x16x32_bf16 v[66:69], v[192:195], v[224:227], v[66:69]
	s_setprio 0
	s_barrier
; #define PG8_KSETUP() const bool last = (t == nt - 2); const char* a1 = cA + (size_t)(t + 1) * kstep; \
;             const char* a2 = last ? nA : cA + (size_t)(t + 2) * kstep; const char* b2 = last ? nB : cB + (size_t)(t + 2) * kstep; const char* a3 = a2 + kstep; const char* b3 = b2 + kstep; \
;             if (last && has_next) S.a_ready(nxt)
; template <class Epi, class Sched, bool ALIGN_EPI = false, bool SP2 = false>
; __device__ __forceinline__ void gemm_phase(PG8_LAS unsigned char* lds, const Gemm g, const Sched& S, const Epi& E) {
;     ...
;         int t0 = 0;
;         if constexpr (SP2 && Epi::NVM == 16) { if (ui > 0) { const int t = 0; PG8_KSETUP(); PG8_KITER_SP2(24, 24); t0 = 2; } }
;         if constexpr (SP2 && Epi::NVM == 8) { if (ui > 0) { const int t = 0; PG8_KSETUP(); PG8_KITER_SP2(16, 16); t0 = 2; } }
;         for (int t = t0; t < nt; t += 2) {
	ds_read_b128 v[196:199], v164 offset:49152
	ds_read_b128 v[200:203], v164 offset:50176
	ds_read_b128 v[204:207], v164 offset:51200
	ds_read_b128 v[208:211], v164 offset:52224
	ds_read_b128 v[212:215], v164 offset:53248
	ds_read_b128 v[216:219], v164 offset:54272
	ds_read_b128 v[220:223], v164 offset:55296
	ds_read_b128 v[224:227], v164 offset:56320
	s_add_u32 s30, s54, 0x80
	s_addc_u32 s31, s55, 0
	s_mov_b32 m0, s72
	s_nop 0
	global_load_lds_dwordx4 v137, s[30:31] offset:0
	s_nop 0
	s_mov_b32 m0, s73
	s_nop 0
	global_load_lds_dwordx4 v141, s[30:31] offset:0
	s_add_u32 s30, s54, 0x80080
	s_addc_u32 s31, s55, 0
	s_mov_b32 m0, s76
	s_nop 0
	global_load_lds_dwordx4 v137, s[30:31] offset:0
	s_nop 0
	s_mov_b32 m0, s77
	s_nop 0
	global_load_lds_dwordx4 v141, s[30:31] offset:0
	s_nop 0
	s_mov_b32 m0, s74
	s_nop 0
	global_load_lds_dwordx4 v1, s[46:47] offset:0
	s_nop 0
	s_mov_b32 m0, s75
	s_nop 0
	global_load_lds_dwordx4 v139, s[46:47] offset:0
	s_waitcnt vmcnt(8)
	s_waitcnt lgkmcnt(0)
	s_barrier
	s_setprio 1
	s_waitcnt lgkmcnt(7)
	s_waitcnt lgkmcnt(5)
	s_waitcnt lgkmcnt(3)
	s_waitcnt lgkmcnt(1)
	s_waitcnt lgkmcnt(0)
	v_mfma_f32_16x16x32_bf16 v[62:65], v[160:163], v[196:199], v[62:65]
	v_mfma_f32_16x16x32_bf16 v[62:65], v[168:171], v[200:203], v[62:65]
	v_mfma_f32_16x16x32_bf16 v[58:61], v[172:175], v[196:199], v[58:61]
	v_mfma_f32_16x16x32_bf16 v[58:61], v[176:179], v[200:203], v[58:61]
	v_mfma_f32_16x16x32_bf16 v[50:53], v[160:163], v[204:207], v[50:53]
	v_mfma_f32_16x16x32_bf16 v[50:53], v[168:171], v[208:211], v[50:53]
	v_mfma_f32_16x16x32_bf16 v[42:45], v[172:175], v[204:207], v[42:45]
	v_mfma_f32_16x16x32_bf16 v[42:45], v[176:179], v[208:211], v[42:45]
	v_mfma_f32_16x16x32_bf16 v[34:37], v[160:163], v[212:215], v[34:37]
	v_mfma_f32_16x16x32_bf16 v[34:37], v[168:171], v[216:219], v[34:37]
	v_mfma_f32_16x16x32_bf16 v[26:29], v[172:175], v[212:215], v[26:29]
	v_mfma_f32_16x16x32_bf16 v[26:29], v[176:179], v[216:219], v[26:29]
	v_mfma_f32_16x16x32_bf16 v[18:21], v[160:163], v[220:223], v[18:21]
	v_mfma_f32_16x16x32_bf16 v[18:21], v[168:171], v[224:227], v[18:21]
	v_mfma_f32_16x16x32_bf16 v[10:13], v[172:175], v[220:223], v[10:13]
	v_mfma_f32_16x16x32_bf16 v[10:13], v[176:179], v[224:227], v[10:13]
	s_setprio 0
	s_setprio 1
	v_mfma_f32_16x16x32_bf16 v[54:57], v[180:183], v[196:199], v[54:57]
	v_mfma_f32_16x16x32_bf16 v[54:57], v[184:187], v[200:203], v[54:57]
	v_mfma_f32_16x16x32_bf16 v[46:49], v[188:191], v[196:199], v[46:49]
	v_mfma_f32_16x16x32_bf16 v[46:49], v[192:195], v[200:203], v[46:49]
	v_mfma_f32_16x16x32_bf16 v[38:41], v[180:183], v[204:207], v[38:41]
	v_mfma_f32_16x16x32_bf16 v[38:41], v[184:187], v[208:211], v[38:41]
	v_mfma_f32_16x16x32_bf16 v[30:33], v[188:191], v[204:207], v[30:33]
	v_mfma_f32_16x16x32_bf16 v[30:33], v[192:195], v[208:211], v[30:33]
	v_mfma_f32_16x16x32_bf16 v[22:25], v[180:183], v[212:215], v[22:25]
	v_mfma_f32_16x16x32_bf16 v[22:25], v[184:187], v[216:219], v[22:25]
	v_mfma_f32_16x16x32_bf16 v[14:17], v[188:191], v[212:215], v[14:17]
	v_mfma_f32_16x16x32_bf16 v[14:17], v[192:195], v[216:219], v[14:17]
	v_mfma_f32_16x16x32_bf16 v[6:9], v[180:183], v[220:223], v[6:9]
	v_mfma_f32_16x16x32_bf16 v[6:9], v[184:187], v[224:227], v[6:9]
	v_mfma_f32_16x16x32_bf16 v[2:5], v[188:191], v[220:223], v[2:5]
	v_mfma_f32_16x16x32_bf16 v[2:5], v[192:195], v[224:227], v[2:5]
	s_setprio 0
	s_barrier
	s_add_i32 s91, s91, 2
	s_add_u32 s87, s87, 0x100
	s_addc_u32 s88, s88, 0
	s_add_u32 s89, s89, 0x100
	s_addc_u32 s90, s90, 0
	s_cmp_gt_u32 s91, 29
	s_cbranch_scc0 .LBB0_2536
	s_and_b64 vcc, exec, s[18:19]
	s_cbranch_vccz .LBB0_2539
	s_barrier

.LBB0_2714:
	ds_read_b128 v[138:141], v147
	ds_read_b128 v[152:155], v147 offset:1024
	ds_read_b128 v[156:159], v147 offset:2048
	ds_read_b128 v[160:163], v147 offset:3072
	ds_read_b128 v[164:167], v148
	ds_read_b128 v[168:171], v148 offset:1024
	ds_read_b128 v[172:175], v148 offset:2048
	ds_read_b128 v[176:179], v148 offset:3072
	s_cmp_eq_u32 s84, 28
	s_cselect_b32 s58, s43, s87
	s_cselect_b32 s59, s37, s88
	s_cselect_b32 s56, s83, s85
	s_cselect_b32 s57, s29, s86
	s_add_u32 s54, s58, 0x80
	s_addc_u32 s55, s59, 0
	ds_read_b128 v[180:183], v149
	ds_read_b128 v[184:187], v149 offset:1024
	ds_read_b128 v[188:191], v149 offset:2048
	ds_read_b128 v[192:195], v149 offset:3072
	ds_read_b128 v[196:199], v149 offset:4096
	ds_read_b128 v[200:203], v149 offset:5120
	ds_read_b128 v[204:207], v149 offset:6144
	ds_read_b128 v[208:211], v149 offset:7168
	s_mov_b32 m0, s77
	s_nop 0
	global_load_lds_dwordx4 v1, s[46:47] offset:0
	s_nop 0
	s_mov_b32 m0, s78
	s_nop 0
	global_load_lds_dwordx4 v143, s[46:47] offset:0
	s_waitcnt vmcnt(8)
	s_waitcnt lgkmcnt(0)
	s_barrier
	s_setprio 1
	s_waitcnt lgkmcnt(7)
	s_waitcnt lgkmcnt(5)
	s_waitcnt lgkmcnt(3)
	s_waitcnt lgkmcnt(1)
	s_waitcnt lgkmcnt(0)
	v_mfma_f32_16x16x32_bf16 v[130:133], v[138:141], v[180:183], v[130:133]
	v_mfma_f32_16x16x32_bf16 v[130:133], v[152:155], v[184:187], v[130:133]
	v_mfma_f32_16x16x32_bf16 v[126:129], v[156:159], v[180:183], v[126:129]
	v_mfma_f32_16x16x32_bf16 v[126:129], v[160:163], v[184:187], v[126:129]
	v_mfma_f32_16x16x32_bf16 v[114:117], v[138:141], v[188:191], v[114:117]
	v_mfma_f32_16x16x32_bf16 v[114:117], v[152:155], v[192:195], v[114:117]
	v_mfma_f32_16x16x32_bf16 v[110:113], v[156:159], v[188:191], v[110:113]
	v_mfma_f32_16x16x32_bf16 v[110:113], v[160:163], v[192:195], v[110:113]
	v_mfma_f32_16x16x32_bf16 v[98:101], v[138:141], v[196:199], v[98:101]
	v_mfma_f32_16x16x32_bf16 v[98:101], v[152:155], v[200:203], v[98:101]
	v_mfma_f32_16x16x32_bf16 v[94:97], v[156:159], v[196:199], v[94:97]
	v_mfma_f32_16x16x32_bf16 v[94:97], v[160:163], v[200:203], v[94:97]
	v_mfma_f32_16x16x32_bf16 v[82:85], v[138:141], v[204:207], v[82:85]
	v_mfma_f32_16x16x32_bf16 v[82:85], v[152:155], v[208:211], v[82:85]
	v_mfma_f32_16x16x32_bf16 v[78:81], v[156:159], v[204:207], v[78:81]
	v_mfma_f32_16x16x32_bf16 v[78:81], v[160:163], v[208:211], v[78:81]
	s_setprio 0
	s_setprio 1
	v_mfma_f32_16x16x32_bf16 v[122:125], v[164:167], v[180:183], v[122:125]
	v_mfma_f32_16x16x32_bf16 v[122:125], v[168:171], v[184:187], v[122:125]
	v_mfma_f32_16x16x32_bf16 v[118:121], v[172:175], v[180:183], v[118:121]
	v_mfma_f32_16x16x32_bf16 v[118:121], v[176:179], v[184:187], v[118:121]
	v_mfma_f32_16x16x32_bf16 v[106:109], v[164:167], v[188:191], v[106:109]
	v_mfma_f32_16x16x32_bf16 v[106:109], v[168:171], v[192:195], v[106:109]
	v_mfma_f32_16x16x32_bf16 v[102:105], v[172:175], v[188:191], v[102:105]
	v_mfma_f32_16x16x32_bf16 v[102:105], v[176:179], v[192:195], v[102:105]
	v_mfma_f32_16x16x32_bf16 v[90:93], v[164:167], v[196:199], v[90:93]
	v_mfma_f32_16x16x32_bf16 v[90:93], v[168:171], v[200:203], v[90:93]
	v_mfma_f32_16x16x32_bf16 v[86:89], v[172:175], v[196:199], v[86:89]
	v_mfma_f32_16x16x32_bf16 v[86:89], v[176:179], v[200:203], v[86:89]
	v_mfma_f32_16x16x32_bf16 v[74:77], v[164:167], v[204:207], v[74:77]
	v_mfma_f32_16x16x32_bf16 v[74:77], v[168:171], v[208:211], v[74:77]
	v_mfma_f32_16x16x32_bf16 v[70:73], v[172:175], v[204:207], v[70:73]
	v_mfma_f32_16x16x32_bf16 v[70:73], v[176:179], v[208:211], v[70:73]
	s_setprio 0
	s_barrier
	ds_read_b128 v[180:183], v149 offset:16384
	ds_read_b128 v[184:187], v149 offset:17408
	ds_read_b128 v[188:191], v149 offset:18432
	ds_read_b128 v[192:195], v149 offset:19456
	ds_read_b128 v[196:199], v149 offset:20480
	ds_read_b128 v[200:203], v149 offset:21504
	ds_read_b128 v[204:207], v149 offset:22528
	ds_read_b128 v[208:211], v149 offset:23552
	s_mov_b32 m0, s45
	s_nop 0
	global_load_lds_dwordx4 v142, s[56:57] offset:0
	s_add_u32 s30, s56, 0x80000
	s_mov_b32 m0, s52
	s_nop 0
	global_load_lds_dwordx4 v144, s[56:57] offset:0
	s_addc_u32 s31, s57, 0
	s_mov_b32 m0, s53
	s_nop 0
	global_load_lds_dwordx4 v142, s[30:31] offset:0
	s_nop 0
	s_mov_b32 m0, s64
	s_nop 0
	global_load_lds_dwordx4 v144, s[30:31] offset:0
	s_nop 0
	s_mov_b32 m0, s33
	s_nop 0
	global_load_lds_dwordx4 v1, s[58:59] offset:0
	s_nop 0
	s_mov_b32 m0, s65
	s_nop 0
	global_load_lds_dwordx4 v143, s[58:59] offset:0
	s_waitcnt vmcnt(8)
	s_waitcnt lgkmcnt(0)
	s_barrier
	s_setprio 1
	s_waitcnt lgkmcnt(7)
	s_waitcnt lgkmcnt(5)
	s_waitcnt lgkmcnt(3)
	s_waitcnt lgkmcnt(1)
	s_waitcnt lgkmcnt(0)
	v_mfma_f32_16x16x32_bf16 v[66:69], v[138:141], v[180:183], v[66:69]
	v_mfma_f32_16x16x32_bf16 v[66:69], v[152:155], v[184:187], v[66:69]
	v_mfma_f32_16x16x32_bf16 v[62:65], v[156:159], v[180:183], v[62:65]
	v_mfma_f32_16x16x32_bf16 v[62:65], v[160:163], v[184:187], v[62:65]
	v_mfma_f32_16x16x32_bf16 v[50:53], v[138:141], v[188:191], v[50:53]
	v_mfma_f32_16x16x32_bf16 v[50:53], v[152:155], v[192:195], v[50:53]
	v_mfma_f32_16x16x32_bf16 v[46:49], v[156:159], v[188:191], v[46:49]
	v_mfma_f32_16x16x32_bf16 v[46:49], v[160:163], v[192:195], v[46:49]
	v_mfma_f32_16x16x32_bf16 v[34:37], v[138:141], v[196:199], v[34:37]
	v_mfma_f32_16x16x32_bf16 v[34:37], v[152:155], v[200:203], v[34:37]
	v_mfma_f32_16x16x32_bf16 v[30:33], v[156:159], v[196:199], v[30:33]
	v_mfma_f32_16x16x32_bf16 v[30:33], v[160:163], v[200:203], v[30:33]
	v_mfma_f32_16x16x32_bf16 v[18:21], v[138:141], v[204:207], v[18:21]
	v_mfma_f32_16x16x32_bf16 v[18:21], v[152:155], v[208:211], v[18:21]
	v_mfma_f32_16x16x32_bf16 v[14:17], v[156:159], v[204:207], v[14:17]
	v_mfma_f32_16x16x32_bf16 v[14:17], v[160:163], v[208:211], v[14:17]
	s_setprio 0
	s_setprio 1
	v_mfma_f32_16x16x32_bf16 v[58:61], v[164:167], v[180:183], v[58:61]
	v_mfma_f32_16x16x32_bf16 v[54:57], v[172:175], v[180:183], v[54:57]
	v_mfma_f32_16x16x32_bf16 v[42:45], v[164:167], v[188:191], v[42:45]
	v_mfma_f32_16x16x32_bf16 v[38:41], v[172:175], v[188:191], v[38:41]
	v_mfma_f32_16x16x32_bf16 v[26:29], v[164:167], v[196:199], v[26:29]
	v_mfma_f32_16x16x32_bf16 v[22:25], v[172:175], v[196:199], v[22:25]
	v_mfma_f32_16x16x32_bf16 v[10:13], v[164:167], v[204:207], v[10:13]
	v_mfma_f32_16x16x32_bf16 v[4:7], v[172:175], v[204:207], v[6:9]
	v_mfma_f32_16x16x32_bf16 v[58:61], v[168:171], v[184:187], v[58:61]
	v_mfma_f32_16x16x32_bf16 v[54:57], v[176:179], v[184:187], v[54:57]
	v_mfma_f32_16x16x32_bf16 v[42:45], v[168:171], v[192:195], v[42:45]
	v_mfma_f32_16x16x32_bf16 v[38:41], v[176:179], v[192:195], v[38:41]
	v_mfma_f32_16x16x32_bf16 v[26:29], v[168:171], v[200:203], v[26:29]
	v_mfma_f32_16x16x32_bf16 v[22:25], v[176:179], v[200:203], v[22:25]
	v_mfma_f32_16x16x32_bf16 v[10:13], v[168:171], v[208:211], v[10:13]
	v_mfma_f32_16x16x32_bf16 v[4:7], v[176:179], v[208:211], v[4:7]
	s_setprio 0
	s_barrier
	ds_read_b128 v[138:141], v150
	ds_read_b128 v[152:155], v150 offset:1024
	ds_read_b128 v[156:159], v150 offset:2048
	ds_read_b128 v[160:163], v150 offset:3072
	ds_read_b128 v[164:167], v151
	ds_read_b128 v[168:171], v151 offset:1024
	ds_read_b128 v[172:175], v151 offset:2048
	ds_read_b128 v[176:179], v151 offset:3072
	ds_read_b128 v[180:183], v149 offset:32768
	ds_read_b128 v[184:187], v149 offset:33792
	ds_read_b128 v[188:191], v149 offset:34816
	ds_read_b128 v[192:195], v149 offset:35840
	ds_read_b128 v[196:199], v149 offset:36864
	ds_read_b128 v[200:203], v149 offset:37888
	ds_read_b128 v[204:207], v149 offset:38912
	ds_read_b128 v[208:211], v149 offset:39936
	s_add_u32 s30, s58, 0x80000
	s_addc_u32 s31, s59, 0
	s_mov_b32 m0, s66
	s_nop 0
	global_load_lds_dwordx4 v1, s[30:31] offset:0
	s_nop 0
	s_mov_b32 m0, s67
	s_nop 0
	global_load_lds_dwordx4 v143, s[30:31] offset:0
	s_waitcnt vmcnt(8)
	s_waitcnt lgkmcnt(0)
	s_barrier
	s_setprio 1
	s_waitcnt lgkmcnt(7)
	s_waitcnt lgkmcnt(5)
	s_waitcnt lgkmcnt(3)
	s_waitcnt lgkmcnt(1)
	s_waitcnt lgkmcnt(0)
	v_mfma_f32_16x16x32_bf16 v[130:133], v[138:141], v[180:183], v[130:133]
	v_mfma_f32_16x16x32_bf16 v[130:133], v[152:155], v[184:187], v[130:133]
	v_mfma_f32_16x16x32_bf16 v[126:129], v[156:159], v[180:183], v[126:129]
	v_mfma_f32_16x16x32_bf16 v[126:129], v[160:163], v[184:187], v[126:129]
	v_mfma_f32_16x16x32_bf16 v[114:117], v[138:141], v[188:191], v[114:117]
	v_mfma_f32_16x16x32_bf16 v[114:117], v[152:155], v[192:195], v[114:117]
	v_mfma_f32_16x16x32_bf16 v[110:113], v[156:159], v[188:191], v[110:113]
	v_mfma_f32_16x16x32_bf16 v[110:113], v[160:163], v[192:195], v[110:113]
	v_mfma_f32_16x16x32_bf16 v[98:101], v[138:141], v[196:199], v[98:101]
	v_mfma_f32_16x16x32_bf16 v[98:101], v[152:155], v[200:203], v[98:101]
	v_mfma_f32_16x16x32_bf16 v[94:97], v[156:159], v[196:199], v[94:97]
	v_mfma_f32_16x16x32_bf16 v[94:97], v[160:163], v[200:203], v[94:97]
	v_mfma_f32_16x16x32_bf16 v[82:85], v[138:141], v[204:207], v[82:85]
	v_mfma_f32_16x16x32_bf16 v[82:85], v[152:155], v[208:211], v[82:85]
	v_mfma_f32_16x16x32_bf16 v[78:81], v[156:159], v[204:207], v[78:81]
	v_mfma_f32_16x16x32_bf16 v[78:81], v[160:163], v[208:211], v[78:81]
	s_setprio 0
	s_setprio 1
	v_mfma_f32_16x16x32_bf16 v[122:125], v[164:167], v[180:183], v[122:125]
	v_mfma_f32_16x16x32_bf16 v[122:125], v[168:171], v[184:187], v[122:125]
	v_mfma_f32_16x16x32_bf16 v[118:121], v[172:175], v[180:183], v[118:121]
	v_mfma_f32_16x16x32_bf16 v[118:121], v[176:179], v[184:187], v[118:121]
	v_mfma_f32_16x16x32_bf16 v[106:109], v[164:167], v[188:191], v[106:109]
	v_mfma_f32_16x16x32_bf16 v[106:109], v[168:171], v[192:195], v[106:109]
	v_mfma_f32_16x16x32_bf16 v[102:105], v[172:175], v[188:191], v[102:105]
	v_mfma_f32_16x16x32_bf16 v[102:105], v[176:179], v[192:195], v[102:105]
	v_mfma_f32_16x16x32_bf16 v[90:93], v[164:167], v[196:199], v[90:93]
	v_mfma_f32_16x16x32_bf16 v[90:93], v[168:171], v[200:203], v[90:93]
	v_mfma_f32_16x16x32_bf16 v[86:89], v[172:175], v[196:199], v[86:89]
	v_mfma_f32_16x16x32_bf16 v[86:89], v[176:179], v[200:203], v[86:89]
	v_mfma_f32_16x16x32_bf16 v[74:77], v[164:167], v[204:207], v[74:77]
	v_mfma_f32_16x16x32_bf16 v[74:77], v[168:171], v[208:211], v[74:77]
	v_mfma_f32_16x16x32_bf16 v[70:73], v[172:175], v[204:207], v[70:73]
	v_mfma_f32_16x16x32_bf16 v[70:73], v[176:179], v[208:211], v[70:73]
	s_setprio 0
	s_barrier
; #define PG8_KSETUP() const bool last = (t == nt - 2); const char* a1 = cA + (size_t)(t + 1) * kstep; \
;             const char* a2 = last ? nA : cA + (size_t)(t + 2) * kstep; const char* b2 = last ? nB : cB + (size_t)(t + 2) * kstep; const char* a3 = a2 + kstep; const char* b3 = b2 + kstep; \
;             if (last && has_next) S.a_ready(nxt)
; template <class Epi, class Sched, bool ALIGN_EPI = false, bool SP2 = false>
; __device__ __forceinline__ void gemm_phase(PG8_LAS unsigned char* lds, const Gemm g, const Sched& S, const Epi& E) {
;     ...
;         int t0 = 0;
;         if constexpr (SP2 && Epi::NVM == 16) { if (ui > 0) { const int t = 0; PG8_KSETUP(); PG8_KITER_SP2(24, 24); t0 = 2; } }
;         if constexpr (SP2 && Epi::NVM == 8) { if (ui > 0) { const int t = 0; PG8_KSETUP(); PG8_KITER_SP2(16, 16); t0 = 2; } }
;         for (int t = t0; t < nt; t += 2) {
	ds_read_b128 v[180:183], v149 offset:49152
	ds_read_b128 v[184:187], v149 offset:50176
	ds_read_b128 v[188:191], v149 offset:51200
	ds_read_b128 v[192:195], v149 offset:52224
	ds_read_b128 v[196:199], v149 offset:53248
	ds_read_b128 v[200:203], v149 offset:54272
	ds_read_b128 v[204:207], v149 offset:55296
	ds_read_b128 v[208:211], v149 offset:56320
	s_add_u32 s30, s56, 0x80
	s_addc_u32 s31, s57, 0
	s_mov_b32 m0, s71
	s_nop 0
	global_load_lds_dwordx4 v142, s[30:31] offset:0
	s_nop 0
	s_mov_b32 m0, s72
	s_nop 0
	global_load_lds_dwordx4 v144, s[30:31] offset:0
	s_add_u32 s30, s56, 0x80080
	s_addc_u32 s31, s57, 0
	s_mov_b32 m0, s75
	s_nop 0
	global_load_lds_dwordx4 v142, s[30:31] offset:0
	s_nop 0
	s_mov_b32 m0, s76
	s_nop 0
	global_load_lds_dwordx4 v144, s[30:31] offset:0
	s_nop 0
	s_mov_b32 m0, s73
	s_nop 0
	global_load_lds_dwordx4 v1, s[54:55] offset:0
	s_nop 0
	s_mov_b32 m0, s74
	s_nop 0
	global_load_lds_dwordx4 v143, s[54:55] offset:0
	s_waitcnt vmcnt(8)
	s_waitcnt lgkmcnt(0)
	s_barrier
	s_setprio 1
	s_waitcnt lgkmcnt(7)
	s_waitcnt lgkmcnt(5)
	s_waitcnt lgkmcnt(3)
	s_waitcnt lgkmcnt(1)
	s_waitcnt lgkmcnt(0)
	v_mfma_f32_16x16x32_bf16 v[66:69], v[138:141], v[180:183], v[66:69]
	v_mfma_f32_16x16x32_bf16 v[66:69], v[152:155], v[184:187], v[66:69]
	v_mfma_f32_16x16x32_bf16 v[62:65], v[156:159], v[180:183], v[62:65]
	v_mfma_f32_16x16x32_bf16 v[62:65], v[160:163], v[184:187], v[62:65]
	v_mfma_f32_16x16x32_bf16 v[50:53], v[138:141], v[188:191], v[50:53]
	v_mfma_f32_16x16x32_bf16 v[50:53], v[152:155], v[192:195], v[50:53]
	v_mfma_f32_16x16x32_bf16 v[46:49], v[156:159], v[188:191], v[46:49]
	v_mfma_f32_16x16x32_bf16 v[46:49], v[160:163], v[192:195], v[46:49]
	v_mfma_f32_16x16x32_bf16 v[34:37], v[138:141], v[196:199], v[34:37]
	v_mfma_f32_16x16x32_bf16 v[34:37], v[152:155], v[200:203], v[34:37]
	v_mfma_f32_16x16x32_bf16 v[30:33], v[156:159], v[196:199], v[30:33]
	v_mfma_f32_16x16x32_bf16 v[30:33], v[160:163], v[200:203], v[30:33]
	v_mfma_f32_16x16x32_bf16 v[18:21], v[138:141], v[204:207], v[18:21]
	v_mfma_f32_16x16x32_bf16 v[18:21], v[152:155], v[208:211], v[18:21]
	v_mfma_f32_16x16x32_bf16 v[14:17], v[156:159], v[204:207], v[14:17]
	v_mfma_f32_16x16x32_bf16 v[14:17], v[160:163], v[208:211], v[14:17]
	s_setprio 0
	s_setprio 1
	v_mfma_f32_16x16x32_bf16 v[58:61], v[164:167], v[180:183], v[58:61]
	v_mfma_f32_16x16x32_bf16 v[54:57], v[172:175], v[180:183], v[54:57]
	v_mfma_f32_16x16x32_bf16 v[42:45], v[164:167], v[188:191], v[42:45]
	v_mfma_f32_16x16x32_bf16 v[38:41], v[172:175], v[188:191], v[38:41]
	v_mfma_f32_16x16x32_bf16 v[26:29], v[164:167], v[196:199], v[26:29]
	v_mfma_f32_16x16x32_bf16 v[22:25], v[172:175], v[196:199], v[22:25]
	v_mfma_f32_16x16x32_bf16 v[8:11], v[164:167], v[204:207], v[10:13]
	v_mfma_f32_16x16x32_bf16 v[4:7], v[172:175], v[204:207], v[4:7]
	v_mfma_f32_16x16x32_bf16 v[58:61], v[168:171], v[184:187], v[58:61]
	v_mfma_f32_16x16x32_bf16 v[54:57], v[176:179], v[184:187], v[54:57]
	v_mfma_f32_16x16x32_bf16 v[42:45], v[168:171], v[192:195], v[42:45]
	v_mfma_f32_16x16x32_bf16 v[38:41], v[176:179], v[192:195], v[38:41]
	v_mfma_f32_16x16x32_bf16 v[26:29], v[168:171], v[200:203], v[26:29]
	v_mfma_f32_16x16x32_bf16 v[22:25], v[176:179], v[200:203], v[22:25]
	v_mfma_f32_16x16x32_bf16 v[10:13], v[168:171], v[208:211], v[8:11]
	v_mfma_f32_16x16x32_bf16 v[6:9], v[176:179], v[208:211], v[4:7]
	s_setprio 0
	s_barrier
	s_add_i32 s84, s84, 2
	s_add_u32 s85, s85, 0x100
	s_addc_u32 s86, s86, 0
	s_add_u32 s87, s87, 0x100
	s_addc_u32 s88, s88, 0
	s_add_u32 s46, s46, 0x100
	s_addc_u32 s47, s47, 0
	s_cmp_gt_u32 s84, 29
	s_cbranch_scc0 .LBB0_2714
	s_and_b64 vcc, exec, s[18:19]
	s_cbranch_vccz .LBB0_2717
	s_barrier

.LBB0_2873:
	ds_read_b128 v[138:141], v152
	ds_read_b128 v[142:145], v152 offset:1024
	ds_read_b128 v[158:161], v152 offset:2048
	ds_read_b128 v[162:165], v152 offset:3072
	ds_read_b128 v[166:169], v153
	ds_read_b128 v[170:173], v153 offset:1024
	ds_read_b128 v[174:177], v153 offset:2048
	ds_read_b128 v[178:181], v153 offset:3072
	s_cmp_eq_u32 s76, 28
	s_cselect_b32 s40, s74, s79
	s_cselect_b32 s41, s19, s80
	s_cselect_b32 s38, s75, s77
	s_cselect_b32 s39, s17, s78
	s_add_u32 s36, s40, 0x80
	s_addc_u32 s37, s41, 0
	ds_read_b128 v[182:185], v154
	ds_read_b128 v[186:189], v154 offset:1024
	ds_read_b128 v[190:193], v154 offset:2048
	ds_read_b128 v[194:197], v154 offset:3072
	ds_read_b128 v[198:201], v154 offset:4096
	ds_read_b128 v[202:205], v154 offset:5120
	ds_read_b128 v[206:209], v154 offset:6144
	ds_read_b128 v[210:213], v154 offset:7168
	s_add_u32 s30, s79, 0x7ff80
	s_addc_u32 s31, s80, 0
	s_mov_b32 m0, s64
	s_nop 0
	global_load_lds_dwordx4 v1, s[30:31] offset:0
	s_nop 0
	s_mov_b32 m0, s65
	s_nop 0
	global_load_lds_dwordx4 v147, s[30:31] offset:0
	s_waitcnt vmcnt(8)
	s_waitcnt lgkmcnt(0)
	s_barrier
	s_setprio 1
	s_waitcnt lgkmcnt(0)
	v_mfma_f32_16x16x32_bf16 v[130:133], v[138:141], v[182:185], v[130:133]
	v_mfma_f32_16x16x32_bf16 v[130:133], v[142:145], v[186:189], v[130:133]
	v_mfma_f32_16x16x32_bf16 v[126:129], v[158:161], v[182:185], v[126:129]
	v_mfma_f32_16x16x32_bf16 v[126:129], v[162:165], v[186:189], v[126:129]
	v_mfma_f32_16x16x32_bf16 v[114:117], v[138:141], v[190:193], v[114:117]
	v_mfma_f32_16x16x32_bf16 v[114:117], v[142:145], v[194:197], v[114:117]
	v_mfma_f32_16x16x32_bf16 v[110:113], v[158:161], v[190:193], v[110:113]
	v_mfma_f32_16x16x32_bf16 v[110:113], v[162:165], v[194:197], v[110:113]
	v_mfma_f32_16x16x32_bf16 v[98:101], v[138:141], v[198:201], v[98:101]
	v_mfma_f32_16x16x32_bf16 v[98:101], v[142:145], v[202:205], v[98:101]
	v_mfma_f32_16x16x32_bf16 v[94:97], v[158:161], v[198:201], v[94:97]
	v_mfma_f32_16x16x32_bf16 v[94:97], v[162:165], v[202:205], v[94:97]
	v_mfma_f32_16x16x32_bf16 v[82:85], v[138:141], v[206:209], v[82:85]
	v_mfma_f32_16x16x32_bf16 v[82:85], v[142:145], v[210:213], v[82:85]
	v_mfma_f32_16x16x32_bf16 v[78:81], v[158:161], v[206:209], v[78:81]
	v_mfma_f32_16x16x32_bf16 v[78:81], v[162:165], v[210:213], v[78:81]
	s_setprio 0
	s_setprio 1
	v_mfma_f32_16x16x32_bf16 v[122:125], v[166:169], v[182:185], v[122:125]
	v_mfma_f32_16x16x32_bf16 v[122:125], v[170:173], v[186:189], v[122:125]
	v_mfma_f32_16x16x32_bf16 v[118:121], v[174:177], v[182:185], v[118:121]
	v_mfma_f32_16x16x32_bf16 v[118:121], v[178:181], v[186:189], v[118:121]
	v_mfma_f32_16x16x32_bf16 v[106:109], v[166:169], v[190:193], v[106:109]
	v_mfma_f32_16x16x32_bf16 v[106:109], v[170:173], v[194:197], v[106:109]
	v_mfma_f32_16x16x32_bf16 v[102:105], v[174:177], v[190:193], v[102:105]
	v_mfma_f32_16x16x32_bf16 v[102:105], v[178:181], v[194:197], v[102:105]
	v_mfma_f32_16x16x32_bf16 v[90:93], v[166:169], v[198:201], v[90:93]
	v_mfma_f32_16x16x32_bf16 v[90:93], v[170:173], v[202:205], v[90:93]
	v_mfma_f32_16x16x32_bf16 v[86:89], v[174:177], v[198:201], v[86:89]
	v_mfma_f32_16x16x32_bf16 v[86:89], v[178:181], v[202:205], v[86:89]
	v_mfma_f32_16x16x32_bf16 v[74:77], v[166:169], v[206:209], v[74:77]
	v_mfma_f32_16x16x32_bf16 v[74:77], v[170:173], v[210:213], v[74:77]
	v_mfma_f32_16x16x32_bf16 v[66:69], v[174:177], v[206:209], v[66:69]
	v_mfma_f32_16x16x32_bf16 v[66:69], v[178:181], v[210:213], v[66:69]
	s_setprio 0
	s_barrier
	ds_read_b128 v[182:185], v154 offset:16384
	ds_read_b128 v[186:189], v154 offset:17408
	ds_read_b128 v[190:193], v154 offset:18432
	ds_read_b128 v[194:197], v154 offset:19456
	ds_read_b128 v[198:201], v154 offset:20480
	ds_read_b128 v[202:205], v154 offset:21504
	ds_read_b128 v[206:209], v154 offset:22528
	ds_read_b128 v[210:213], v154 offset:23552
	s_mov_b32 m0, s29
	s_nop 0
	global_load_lds_dwordx4 v146, s[38:39] offset:0
	s_add_u32 s30, s38, 0x80000
	s_mov_b32 m0, s44
	s_nop 0
	global_load_lds_dwordx4 v148, s[38:39] offset:0
	s_addc_u32 s31, s39, 0
	s_mov_b32 m0, s45
	s_nop 0
	global_load_lds_dwordx4 v146, s[30:31] offset:0
	s_nop 0
	s_mov_b32 m0, s46
	s_nop 0
	global_load_lds_dwordx4 v148, s[30:31] offset:0
	s_nop 0
	s_mov_b32 m0, s21
	s_nop 0
	global_load_lds_dwordx4 v1, s[40:41] offset:0
	s_nop 0
	s_mov_b32 m0, s47
	s_nop 0
	global_load_lds_dwordx4 v147, s[40:41] offset:0
	s_waitcnt vmcnt(8)
	s_waitcnt lgkmcnt(0)
	s_barrier
	s_setprio 1
	s_waitcnt lgkmcnt(0)
	v_mfma_f32_16x16x32_bf16 v[70:73], v[138:141], v[182:185], v[70:73]
	v_mfma_f32_16x16x32_bf16 v[70:73], v[142:145], v[186:189], v[70:73]
	v_mfma_f32_16x16x32_bf16 v[62:65], v[158:161], v[182:185], v[62:65]
	v_mfma_f32_16x16x32_bf16 v[62:65], v[162:165], v[186:189], v[62:65]
	v_mfma_f32_16x16x32_bf16 v[50:53], v[138:141], v[190:193], v[50:53]
	v_mfma_f32_16x16x32_bf16 v[50:53], v[142:145], v[194:197], v[50:53]
	v_mfma_f32_16x16x32_bf16 v[46:49], v[158:161], v[190:193], v[46:49]
	v_mfma_f32_16x16x32_bf16 v[46:49], v[162:165], v[194:197], v[46:49]
	v_mfma_f32_16x16x32_bf16 v[34:37], v[138:141], v[198:201], v[34:37]
	v_mfma_f32_16x16x32_bf16 v[34:37], v[142:145], v[202:205], v[34:37]
	v_mfma_f32_16x16x32_bf16 v[30:33], v[158:161], v[198:201], v[30:33]
	v_mfma_f32_16x16x32_bf16 v[30:33], v[162:165], v[202:205], v[30:33]
	v_mfma_f32_16x16x32_bf16 v[18:21], v[138:141], v[206:209], v[18:21]
	v_mfma_f32_16x16x32_bf16 v[18:21], v[142:145], v[210:213], v[18:21]
	v_mfma_f32_16x16x32_bf16 v[14:17], v[158:161], v[206:209], v[14:17]
	v_mfma_f32_16x16x32_bf16 v[14:17], v[162:165], v[210:213], v[14:17]
	s_setprio 0
	s_setprio 1
	v_mfma_f32_16x16x32_bf16 v[58:61], v[166:169], v[182:185], v[58:61]
	v_mfma_f32_16x16x32_bf16 v[54:57], v[174:177], v[182:185], v[54:57]
	v_mfma_f32_16x16x32_bf16 v[42:45], v[166:169], v[190:193], v[42:45]
	v_mfma_f32_16x16x32_bf16 v[38:41], v[174:177], v[190:193], v[38:41]
	v_mfma_f32_16x16x32_bf16 v[26:29], v[166:169], v[198:201], v[26:29]
	v_mfma_f32_16x16x32_bf16 v[22:25], v[174:177], v[198:201], v[22:25]
	v_mfma_f32_16x16x32_bf16 v[10:13], v[166:169], v[206:209], v[10:13]
	v_mfma_f32_16x16x32_bf16 v[4:7], v[174:177], v[206:209], v[6:9]
	v_mfma_f32_16x16x32_bf16 v[58:61], v[170:173], v[186:189], v[58:61]
	v_mfma_f32_16x16x32_bf16 v[54:57], v[178:181], v[186:189], v[54:57]
	v_mfma_f32_16x16x32_bf16 v[42:45], v[170:173], v[194:197], v[42:45]
	v_mfma_f32_16x16x32_bf16 v[38:41], v[178:181], v[194:197], v[38:41]
	v_mfma_f32_16x16x32_bf16 v[26:29], v[170:173], v[202:205], v[26:29]
	v_mfma_f32_16x16x32_bf16 v[22:25], v[178:181], v[202:205], v[22:25]
	v_mfma_f32_16x16x32_bf16 v[10:13], v[170:173], v[210:213], v[10:13]
	v_mfma_f32_16x16x32_bf16 v[4:7], v[178:181], v[210:213], v[4:7]
	s_setprio 0
	s_barrier
; #define PG8_KSETUP() const bool last = (t == nt - 2); const char* a1 = cA + (size_t)(t + 1) * kstep; \
;             const char* a2 = last ? nA : cA + (size_t)(t + 2) * kstep; const char* b2 = last ? nB : cB + (size_t)(t + 2) * kstep; const char* a3 = a2 + kstep; const char* b3 = b2 + kstep; \
;             if (last && has_next) S.a_ready(nxt)
; template <class Epi, class Sched, bool ALIGN_EPI = false, bool SP2 = false>
; __device__ __forceinline__ void gemm_phase(PG8_LAS unsigned char* lds, const Gemm g, const Sched& S, const Epi& E) {
;     ...
;         int t0 = 0;
;         if constexpr (SP2 && Epi::NVM == 16) { if (ui > 0) { const int t = 0; PG8_KSETUP(); PG8_KITER_SP2(24, 24); t0 = 2; } }
;         if constexpr (SP2 && Epi::NVM == 8) { if (ui > 0) { const int t = 0; PG8_KSETUP(); PG8_KITER_SP2(16, 16); t0 = 2; } }
;         for (int t = t0; t < nt; t += 2) {
	ds_read_b128 v[138:141], v155
	ds_read_b128 v[142:145], v155 offset:1024
	ds_read_b128 v[158:161], v155 offset:2048
	ds_read_b128 v[162:165], v155 offset:3072
	ds_read_b128 v[166:169], v156
	ds_read_b128 v[170:173], v156 offset:1024
	ds_read_b128 v[174:177], v156 offset:2048
	ds_read_b128 v[178:181], v156 offset:3072
	ds_read_b128 v[182:185], v154 offset:32768
	ds_read_b128 v[186:189], v154 offset:33792
	ds_read_b128 v[190:193], v154 offset:34816
	ds_read_b128 v[194:197], v154 offset:35840
	ds_read_b128 v[198:201], v154 offset:36864
	ds_read_b128 v[202:205], v154 offset:37888
	ds_read_b128 v[206:209], v154 offset:38912
	ds_read_b128 v[210:213], v154 offset:39936
	s_add_u32 s30, s40, 0x80000
	s_addc_u32 s31, s41, 0
	s_mov_b32 m0, s52
	s_nop 0
	global_load_lds_dwordx4 v1, s[30:31] offset:0
	s_nop 0
	s_mov_b32 m0, s53
	s_nop 0
	global_load_lds_dwordx4 v147, s[30:31] offset:0
	s_waitcnt vmcnt(8)
	s_waitcnt lgkmcnt(0)
	s_barrier
	s_setprio 1
	s_waitcnt lgkmcnt(0)
	v_mfma_f32_16x16x32_bf16 v[130:133], v[138:141], v[182:185], v[130:133]
	v_mfma_f32_16x16x32_bf16 v[130:133], v[142:145], v[186:189], v[130:133]
	v_mfma_f32_16x16x32_bf16 v[126:129], v[158:161], v[182:185], v[126:129]
	v_mfma_f32_16x16x32_bf16 v[126:129], v[162:165], v[186:189], v[126:129]
	v_mfma_f32_16x16x32_bf16 v[114:117], v[138:141], v[190:193], v[114:117]
	v_mfma_f32_16x16x32_bf16 v[114:117], v[142:145], v[194:197], v[114:117]
	v_mfma_f32_16x16x32_bf16 v[110:113], v[158:161], v[190:193], v[110:113]
	v_mfma_f32_16x16x32_bf16 v[110:113], v[162:165], v[194:197], v[110:113]
	v_mfma_f32_16x16x32_bf16 v[98:101], v[138:141], v[198:201], v[98:101]
	v_mfma_f32_16x16x32_bf16 v[98:101], v[142:145], v[202:205], v[98:101]
	v_mfma_f32_16x16x32_bf16 v[94:97], v[158:161], v[198:201], v[94:97]
	v_mfma_f32_16x16x32_bf16 v[94:97], v[162:165], v[202:205], v[94:97]
	v_mfma_f32_16x16x32_bf16 v[82:85], v[138:141], v[206:209], v[82:85]
	v_mfma_f32_16x16x32_bf16 v[82:85], v[142:145], v[210:213], v[82:85]
	v_mfma_f32_16x16x32_bf16 v[78:81], v[158:161], v[206:209], v[78:81]
	v_mfma_f32_16x16x32_bf16 v[78:81], v[162:165], v[210:213], v[78:81]
	s_setprio 0
	s_setprio 1
	v_mfma_f32_16x16x32_bf16 v[122:125], v[166:169], v[182:185], v[122:125]
	v_mfma_f32_16x16x32_bf16 v[122:125], v[170:173], v[186:189], v[122:125]
	v_mfma_f32_16x16x32_bf16 v[118:121], v[174:177], v[182:185], v[118:121]
	v_mfma_f32_16x16x32_bf16 v[118:121], v[178:181], v[186:189], v[118:121]
	v_mfma_f32_16x16x32_bf16 v[106:109], v[166:169], v[190:193], v[106:109]
	v_mfma_f32_16x16x32_bf16 v[106:109], v[170:173], v[194:197], v[106:109]
	v_mfma_f32_16x16x32_bf16 v[102:105], v[174:177], v[190:193], v[102:105]
	v_mfma_f32_16x16x32_bf16 v[102:105], v[178:181], v[194:197], v[102:105]
	v_mfma_f32_16x16x32_bf16 v[90:93], v[166:169], v[198:201], v[90:93]
	v_mfma_f32_16x16x32_bf16 v[90:93], v[170:173], v[202:205], v[90:93]
	v_mfma_f32_16x16x32_bf16 v[86:89], v[174:177], v[198:201], v[86:89]
	v_mfma_f32_16x16x32_bf16 v[86:89], v[178:181], v[202:205], v[86:89]
	v_mfma_f32_16x16x32_bf16 v[74:77], v[166:169], v[206:209], v[74:77]
	v_mfma_f32_16x16x32_bf16 v[74:77], v[170:173], v[210:213], v[74:77]
	v_mfma_f32_16x16x32_bf16 v[66:69], v[174:177], v[206:209], v[66:69]
	v_mfma_f32_16x16x32_bf16 v[66:69], v[178:181], v[210:213], v[66:69]
	s_setprio 0
	s_barrier
	ds_read_b128 v[182:185], v154 offset:49152
	ds_read_b128 v[186:189], v154 offset:50176
	ds_read_b128 v[190:193], v154 offset:51200
	ds_read_b128 v[194:197], v154 offset:52224
	ds_read_b128 v[198:201], v154 offset:53248
	ds_read_b128 v[202:205], v154 offset:54272
	ds_read_b128 v[206:209], v154 offset:55296
	ds_read_b128 v[210:213], v154 offset:56320
	s_add_u32 s30, s38, 0x80
	s_addc_u32 s31, s39, 0
	s_mov_b32 m0, s54
	s_nop 0
	global_load_lds_dwordx4 v146, s[30:31] offset:0
	s_nop 0
	s_mov_b32 m0, s55
	s_nop 0
	global_load_lds_dwordx4 v148, s[30:31] offset:0
	s_add_u32 s30, s38, 0x80080
	s_addc_u32 s31, s39, 0
	s_mov_b32 m0, s58
	s_nop 0
	global_load_lds_dwordx4 v146, s[30:31] offset:0
	s_nop 0
	s_mov_b32 m0, s59
	s_nop 0
	global_load_lds_dwordx4 v148, s[30:31] offset:0
	s_nop 0
	s_mov_b32 m0, s56
	s_nop 0
	global_load_lds_dwordx4 v1, s[36:37] offset:0
	s_nop 0
	s_mov_b32 m0, s57
	s_nop 0
	global_load_lds_dwordx4 v147, s[36:37] offset:0
	s_waitcnt vmcnt(8)
	s_waitcnt lgkmcnt(0)
	s_barrier
	s_setprio 1
	s_waitcnt lgkmcnt(0)
	v_mfma_f32_16x16x32_bf16 v[70:73], v[138:141], v[182:185], v[70:73]
	v_mfma_f32_16x16x32_bf16 v[70:73], v[142:145], v[186:189], v[70:73]
	v_mfma_f32_16x16x32_bf16 v[62:65], v[158:161], v[182:185], v[62:65]
	v_mfma_f32_16x16x32_bf16 v[62:65], v[162:165], v[186:189], v[62:65]
	v_mfma_f32_16x16x32_bf16 v[50:53], v[138:141], v[190:193], v[50:53]
	v_mfma_f32_16x16x32_bf16 v[50:53], v[142:145], v[194:197], v[50:53]
	v_mfma_f32_16x16x32_bf16 v[46:49], v[158:161], v[190:193], v[46:49]
	v_mfma_f32_16x16x32_bf16 v[46:49], v[162:165], v[194:197], v[46:49]
	v_mfma_f32_16x16x32_bf16 v[34:37], v[138:141], v[198:201], v[34:37]
	v_mfma_f32_16x16x32_bf16 v[34:37], v[142:145], v[202:205], v[34:37]
	v_mfma_f32_16x16x32_bf16 v[30:33], v[158:161], v[198:201], v[30:33]
	v_mfma_f32_16x16x32_bf16 v[30:33], v[162:165], v[202:205], v[30:33]
	v_mfma_f32_16x16x32_bf16 v[18:21], v[138:141], v[206:209], v[18:21]
	v_mfma_f32_16x16x32_bf16 v[18:21], v[142:145], v[210:213], v[18:21]
	v_mfma_f32_16x16x32_bf16 v[14:17], v[158:161], v[206:209], v[14:17]
	v_mfma_f32_16x16x32_bf16 v[14:17], v[162:165], v[210:213], v[14:17]
	s_setprio 0
	s_setprio 1
	v_mfma_f32_16x16x32_bf16 v[58:61], v[166:169], v[182:185], v[58:61]
	v_mfma_f32_16x16x32_bf16 v[54:57], v[174:177], v[182:185], v[54:57]
	v_mfma_f32_16x16x32_bf16 v[42:45], v[166:169], v[190:193], v[42:45]
	v_mfma_f32_16x16x32_bf16 v[38:41], v[174:177], v[190:193], v[38:41]
	v_mfma_f32_16x16x32_bf16 v[26:29], v[166:169], v[198:201], v[26:29]
	v_mfma_f32_16x16x32_bf16 v[22:25], v[174:177], v[198:201], v[22:25]
	v_mfma_f32_16x16x32_bf16 v[8:11], v[166:169], v[206:209], v[10:13]
	v_mfma_f32_16x16x32_bf16 v[4:7], v[174:177], v[206:209], v[4:7]
	v_mfma_f32_16x16x32_bf16 v[58:61], v[170:173], v[186:189], v[58:61]
	v_mfma_f32_16x16x32_bf16 v[54:57], v[178:181], v[186:189], v[54:57]
	v_mfma_f32_16x16x32_bf16 v[42:45], v[170:173], v[194:197], v[42:45]
	v_mfma_f32_16x16x32_bf16 v[38:41], v[178:181], v[194:197], v[38:41]
	v_mfma_f32_16x16x32_bf16 v[26:29], v[170:173], v[202:205], v[26:29]
	v_mfma_f32_16x16x32_bf16 v[22:25], v[178:181], v[202:205], v[22:25]
	v_mfma_f32_16x16x32_bf16 v[10:13], v[170:173], v[210:213], v[8:11]
	v_mfma_f32_16x16x32_bf16 v[6:9], v[178:181], v[210:213], v[4:7]
	s_setprio 0
	s_barrier
	s_add_i32 s76, s76, 2
	s_add_u32 s77, s77, 0x100
	s_addc_u32 s78, s78, 0
	s_add_u32 s79, s79, 0x100
	s_addc_u32 s80, s80, 0
	s_cmp_gt_u32 s76, 29
	s_cbranch_scc0 .LBB0_2873
	s_and_b64 vcc, exec, s[14:15]
	s_cbranch_vccz .LBB0_2876
	s_barrier

.LBB0_2960:
	ds_read_b128 v[138:141], v147
	ds_read_b128 v[152:155], v147 offset:1024
	ds_read_b128 v[156:159], v147 offset:2048
	ds_read_b128 v[160:163], v147 offset:3072
	ds_read_b128 v[164:167], v148
	ds_read_b128 v[168:171], v148 offset:1024
	ds_read_b128 v[172:175], v148 offset:2048
	ds_read_b128 v[176:179], v148 offset:3072
	s_cmpk_eq_i32 s80, 0x54
	s_cselect_b32 s42, s8, s83
	s_cselect_b32 s43, s9, s84
	s_cselect_b32 s40, s28, s81
	s_cselect_b32 s41, s29, s82
	s_add_u32 s38, s42, 0x80
	s_addc_u32 s39, s43, 0
	ds_read_b128 v[180:183], v149
	ds_read_b128 v[184:187], v149 offset:1024
	ds_read_b128 v[188:191], v149 offset:2048
	ds_read_b128 v[192:195], v149 offset:3072
	ds_read_b128 v[196:199], v149 offset:4096
	ds_read_b128 v[200:203], v149 offset:5120
	ds_read_b128 v[204:207], v149 offset:6144
	ds_read_b128 v[208:211], v149 offset:7168
	s_mov_b32 m0, s70
	s_nop 0
	global_load_lds_dwordx4 v1, s[36:37] offset:0
	s_nop 0
	s_mov_b32 m0, s71
	s_nop 0
	global_load_lds_dwordx4 v143, s[36:37] offset:0
	s_waitcnt vmcnt(8)
	s_waitcnt lgkmcnt(0)
	s_barrier
	s_setprio 1
	s_waitcnt lgkmcnt(7)
	s_waitcnt lgkmcnt(5)
	s_waitcnt lgkmcnt(3)
	s_waitcnt lgkmcnt(1)
	s_waitcnt lgkmcnt(0)
	v_mfma_f32_16x16x32_bf16 v[130:133], v[138:141], v[180:183], v[130:133]
	v_mfma_f32_16x16x32_bf16 v[130:133], v[152:155], v[184:187], v[130:133]
	v_mfma_f32_16x16x32_bf16 v[126:129], v[156:159], v[180:183], v[126:129]
	v_mfma_f32_16x16x32_bf16 v[126:129], v[160:163], v[184:187], v[126:129]
	v_mfma_f32_16x16x32_bf16 v[114:117], v[138:141], v[188:191], v[114:117]
	v_mfma_f32_16x16x32_bf16 v[114:117], v[152:155], v[192:195], v[114:117]
	v_mfma_f32_16x16x32_bf16 v[110:113], v[156:159], v[188:191], v[110:113]
	v_mfma_f32_16x16x32_bf16 v[110:113], v[160:163], v[192:195], v[110:113]
	v_mfma_f32_16x16x32_bf16 v[98:101], v[138:141], v[196:199], v[98:101]
	v_mfma_f32_16x16x32_bf16 v[98:101], v[152:155], v[200:203], v[98:101]
	v_mfma_f32_16x16x32_bf16 v[94:97], v[156:159], v[196:199], v[94:97]
	v_mfma_f32_16x16x32_bf16 v[94:97], v[160:163], v[200:203], v[94:97]
	v_mfma_f32_16x16x32_bf16 v[82:85], v[138:141], v[204:207], v[82:85]
	v_mfma_f32_16x16x32_bf16 v[82:85], v[152:155], v[208:211], v[82:85]
	v_mfma_f32_16x16x32_bf16 v[78:81], v[156:159], v[204:207], v[78:81]
	v_mfma_f32_16x16x32_bf16 v[78:81], v[160:163], v[208:211], v[78:81]
	s_setprio 0
	s_setprio 1
	v_mfma_f32_16x16x32_bf16 v[122:125], v[164:167], v[180:183], v[122:125]
	v_mfma_f32_16x16x32_bf16 v[122:125], v[168:171], v[184:187], v[122:125]
	v_mfma_f32_16x16x32_bf16 v[118:121], v[172:175], v[180:183], v[118:121]
	v_mfma_f32_16x16x32_bf16 v[118:121], v[176:179], v[184:187], v[118:121]
	v_mfma_f32_16x16x32_bf16 v[106:109], v[164:167], v[188:191], v[106:109]
	v_mfma_f32_16x16x32_bf16 v[106:109], v[168:171], v[192:195], v[106:109]
	v_mfma_f32_16x16x32_bf16 v[102:105], v[172:175], v[188:191], v[102:105]
	v_mfma_f32_16x16x32_bf16 v[102:105], v[176:179], v[192:195], v[102:105]
	v_mfma_f32_16x16x32_bf16 v[90:93], v[164:167], v[196:199], v[90:93]
	v_mfma_f32_16x16x32_bf16 v[90:93], v[168:171], v[200:203], v[90:93]
	v_mfma_f32_16x16x32_bf16 v[86:89], v[172:175], v[196:199], v[86:89]
	v_mfma_f32_16x16x32_bf16 v[86:89], v[176:179], v[200:203], v[86:89]
	v_mfma_f32_16x16x32_bf16 v[74:77], v[164:167], v[204:207], v[74:77]
	v_mfma_f32_16x16x32_bf16 v[74:77], v[168:171], v[208:211], v[74:77]
	v_mfma_f32_16x16x32_bf16 v[70:73], v[172:175], v[204:207], v[70:73]
	v_mfma_f32_16x16x32_bf16 v[70:73], v[176:179], v[208:211], v[70:73]
	s_setprio 0
	s_barrier
	ds_read_b128 v[180:183], v149 offset:16384
	ds_read_b128 v[184:187], v149 offset:17408
	ds_read_b128 v[188:191], v149 offset:18432
	ds_read_b128 v[192:195], v149 offset:19456
	ds_read_b128 v[196:199], v149 offset:20480
	ds_read_b128 v[200:203], v149 offset:21504
	ds_read_b128 v[204:207], v149 offset:22528
	ds_read_b128 v[208:211], v149 offset:23552
	s_mov_b32 m0, s46
	s_nop 0
	global_load_lds_dwordx4 v142, s[40:41] offset:0
	s_add_u32 s30, s40, 0x160000
	s_mov_b32 m0, s47
	s_nop 0
	global_load_lds_dwordx4 v144, s[40:41] offset:0
	s_addc_u32 s31, s41, 0
	s_mov_b32 m0, s52
	s_nop 0
	global_load_lds_dwordx4 v142, s[30:31] offset:0
	s_nop 0
	s_mov_b32 m0, s53
	s_nop 0
	global_load_lds_dwordx4 v144, s[30:31] offset:0
	s_nop 0
	s_mov_b32 m0, s45
	s_nop 0
	global_load_lds_dwordx4 v1, s[42:43] offset:0
	s_nop 0
	s_mov_b32 m0, s54
	s_nop 0
	global_load_lds_dwordx4 v143, s[42:43] offset:0
	s_waitcnt vmcnt(8)
	s_waitcnt lgkmcnt(0)
	s_barrier
	s_setprio 1
	s_waitcnt lgkmcnt(7)
	s_waitcnt lgkmcnt(5)
	s_waitcnt lgkmcnt(3)
	s_waitcnt lgkmcnt(1)
	s_waitcnt lgkmcnt(0)
	v_mfma_f32_16x16x32_bf16 v[66:69], v[138:141], v[180:183], v[66:69]
	v_mfma_f32_16x16x32_bf16 v[66:69], v[152:155], v[184:187], v[66:69]
	v_mfma_f32_16x16x32_bf16 v[62:65], v[156:159], v[180:183], v[62:65]
	v_mfma_f32_16x16x32_bf16 v[62:65], v[160:163], v[184:187], v[62:65]
	v_mfma_f32_16x16x32_bf16 v[50:53], v[138:141], v[188:191], v[50:53]
	v_mfma_f32_16x16x32_bf16 v[50:53], v[152:155], v[192:195], v[50:53]
	v_mfma_f32_16x16x32_bf16 v[46:49], v[156:159], v[188:191], v[46:49]
	v_mfma_f32_16x16x32_bf16 v[46:49], v[160:163], v[192:195], v[46:49]
	v_mfma_f32_16x16x32_bf16 v[34:37], v[138:141], v[196:199], v[34:37]
	v_mfma_f32_16x16x32_bf16 v[34:37], v[152:155], v[200:203], v[34:37]
	v_mfma_f32_16x16x32_bf16 v[30:33], v[156:159], v[196:199], v[30:33]
	v_mfma_f32_16x16x32_bf16 v[30:33], v[160:163], v[200:203], v[30:33]
	v_mfma_f32_16x16x32_bf16 v[18:21], v[138:141], v[204:207], v[18:21]
	v_mfma_f32_16x16x32_bf16 v[18:21], v[152:155], v[208:211], v[18:21]
	v_mfma_f32_16x16x32_bf16 v[14:17], v[156:159], v[204:207], v[14:17]
	v_mfma_f32_16x16x32_bf16 v[14:17], v[160:163], v[208:211], v[14:17]
	s_setprio 0
	s_setprio 1
	v_mfma_f32_16x16x32_bf16 v[58:61], v[164:167], v[180:183], v[58:61]
	v_mfma_f32_16x16x32_bf16 v[54:57], v[172:175], v[180:183], v[54:57]
	v_mfma_f32_16x16x32_bf16 v[42:45], v[164:167], v[188:191], v[42:45]
	v_mfma_f32_16x16x32_bf16 v[38:41], v[172:175], v[188:191], v[38:41]
	v_mfma_f32_16x16x32_bf16 v[26:29], v[164:167], v[196:199], v[26:29]
	v_mfma_f32_16x16x32_bf16 v[22:25], v[172:175], v[196:199], v[22:25]
	v_mfma_f32_16x16x32_bf16 v[10:13], v[164:167], v[204:207], v[10:13]
	v_mfma_f32_16x16x32_bf16 v[4:7], v[172:175], v[204:207], v[6:9]
	v_mfma_f32_16x16x32_bf16 v[58:61], v[168:171], v[184:187], v[58:61]
	v_mfma_f32_16x16x32_bf16 v[54:57], v[176:179], v[184:187], v[54:57]
	v_mfma_f32_16x16x32_bf16 v[42:45], v[168:171], v[192:195], v[42:45]
	v_mfma_f32_16x16x32_bf16 v[38:41], v[176:179], v[192:195], v[38:41]
	v_mfma_f32_16x16x32_bf16 v[26:29], v[168:171], v[200:203], v[26:29]
	v_mfma_f32_16x16x32_bf16 v[22:25], v[176:179], v[200:203], v[22:25]
	v_mfma_f32_16x16x32_bf16 v[10:13], v[168:171], v[208:211], v[10:13]
	v_mfma_f32_16x16x32_bf16 v[4:7], v[176:179], v[208:211], v[4:7]
	s_setprio 0
	s_barrier
	ds_read_b128 v[138:141], v150
	ds_read_b128 v[152:155], v150 offset:1024
	ds_read_b128 v[156:159], v150 offset:2048
	ds_read_b128 v[160:163], v150 offset:3072
	ds_read_b128 v[164:167], v151
	ds_read_b128 v[168:171], v151 offset:1024
	ds_read_b128 v[172:175], v151 offset:2048
	ds_read_b128 v[176:179], v151 offset:3072
	ds_read_b128 v[180:183], v149 offset:32768
	ds_read_b128 v[184:187], v149 offset:33792
	ds_read_b128 v[188:191], v149 offset:34816
	ds_read_b128 v[192:195], v149 offset:35840
	ds_read_b128 v[196:199], v149 offset:36864
	ds_read_b128 v[200:203], v149 offset:37888
	ds_read_b128 v[204:207], v149 offset:38912
	ds_read_b128 v[208:211], v149 offset:39936
	s_add_u32 s30, s42, 0x160000
	s_addc_u32 s31, s43, 0
	s_mov_b32 m0, s55
	s_nop 0
	global_load_lds_dwordx4 v1, s[30:31] offset:0
	s_nop 0
	s_mov_b32 m0, s56
	s_nop 0
	global_load_lds_dwordx4 v143, s[30:31] offset:0
	s_waitcnt vmcnt(8)
	s_waitcnt lgkmcnt(0)
	s_barrier
	s_setprio 1
	s_waitcnt lgkmcnt(7)
	s_waitcnt lgkmcnt(5)
	s_waitcnt lgkmcnt(3)
	s_waitcnt lgkmcnt(1)
	s_waitcnt lgkmcnt(0)
	v_mfma_f32_16x16x32_bf16 v[130:133], v[138:141], v[180:183], v[130:133]
	v_mfma_f32_16x16x32_bf16 v[130:133], v[152:155], v[184:187], v[130:133]
	v_mfma_f32_16x16x32_bf16 v[126:129], v[156:159], v[180:183], v[126:129]
	v_mfma_f32_16x16x32_bf16 v[126:129], v[160:163], v[184:187], v[126:129]
	v_mfma_f32_16x16x32_bf16 v[114:117], v[138:141], v[188:191], v[114:117]
	v_mfma_f32_16x16x32_bf16 v[114:117], v[152:155], v[192:195], v[114:117]
	v_mfma_f32_16x16x32_bf16 v[110:113], v[156:159], v[188:191], v[110:113]
	v_mfma_f32_16x16x32_bf16 v[110:113], v[160:163], v[192:195], v[110:113]
	v_mfma_f32_16x16x32_bf16 v[98:101], v[138:141], v[196:199], v[98:101]
	v_mfma_f32_16x16x32_bf16 v[98:101], v[152:155], v[200:203], v[98:101]
	v_mfma_f32_16x16x32_bf16 v[94:97], v[156:159], v[196:199], v[94:97]
	v_mfma_f32_16x16x32_bf16 v[94:97], v[160:163], v[200:203], v[94:97]
	v_mfma_f32_16x16x32_bf16 v[82:85], v[138:141], v[204:207], v[82:85]
	v_mfma_f32_16x16x32_bf16 v[82:85], v[152:155], v[208:211], v[82:85]
	v_mfma_f32_16x16x32_bf16 v[78:81], v[156:159], v[204:207], v[78:81]
	v_mfma_f32_16x16x32_bf16 v[78:81], v[160:163], v[208:211], v[78:81]
	s_setprio 0
	s_setprio 1
	v_mfma_f32_16x16x32_bf16 v[122:125], v[164:167], v[180:183], v[122:125]
	v_mfma_f32_16x16x32_bf16 v[122:125], v[168:171], v[184:187], v[122:125]
	v_mfma_f32_16x16x32_bf16 v[118:121], v[172:175], v[180:183], v[118:121]
	v_mfma_f32_16x16x32_bf16 v[118:121], v[176:179], v[184:187], v[118:121]
	v_mfma_f32_16x16x32_bf16 v[106:109], v[164:167], v[188:191], v[106:109]
	v_mfma_f32_16x16x32_bf16 v[106:109], v[168:171], v[192:195], v[106:109]
	v_mfma_f32_16x16x32_bf16 v[102:105], v[172:175], v[188:191], v[102:105]
	v_mfma_f32_16x16x32_bf16 v[102:105], v[176:179], v[192:195], v[102:105]
	v_mfma_f32_16x16x32_bf16 v[90:93], v[164:167], v[196:199], v[90:93]
	v_mfma_f32_16x16x32_bf16 v[90:93], v[168:171], v[200:203], v[90:93]
	v_mfma_f32_16x16x32_bf16 v[86:89], v[172:175], v[196:199], v[86:89]
	v_mfma_f32_16x16x32_bf16 v[86:89], v[176:179], v[200:203], v[86:89]
	v_mfma_f32_16x16x32_bf16 v[74:77], v[164:167], v[204:207], v[74:77]
	v_mfma_f32_16x16x32_bf16 v[74:77], v[168:171], v[208:211], v[74:77]
	v_mfma_f32_16x16x32_bf16 v[70:73], v[172:175], v[204:207], v[70:73]
	v_mfma_f32_16x16x32_bf16 v[70:73], v[176:179], v[208:211], v[70:73]
	s_setprio 0
	s_barrier
; #define PG8_KSETUP() const bool last = (t == nt - 2); const char* a1 = cA + (size_t)(t + 1) * kstep; \
;             const char* a2 = last ? nA : cA + (size_t)(t + 2) * kstep; const char* b2 = last ? nB : cB + (size_t)(t + 2) * kstep; const char* a3 = a2 + kstep; const char* b3 = b2 + kstep; \
;             if (last && has_next) S.a_ready(nxt)
; template <class Epi, class Sched, bool ALIGN_EPI = false, bool SP2 = false>
; __device__ __forceinline__ void gemm_phase(PG8_LAS unsigned char* lds, const Gemm g, const Sched& S, const Epi& E) {
;     ...
;         int t0 = 0;
;         if constexpr (SP2 && Epi::NVM == 16) { if (ui > 0) { const int t = 0; PG8_KSETUP(); PG8_KITER_SP2(24, 24); t0 = 2; } }
;         if constexpr (SP2 && Epi::NVM == 8) { if (ui > 0) { const int t = 0; PG8_KSETUP(); PG8_KITER_SP2(16, 16); t0 = 2; } }
;         for (int t = t0; t < nt; t += 2) {
	ds_read_b128 v[180:183], v149 offset:49152
	ds_read_b128 v[184:187], v149 offset:50176
	ds_read_b128 v[188:191], v149 offset:51200
	ds_read_b128 v[192:195], v149 offset:52224
	ds_read_b128 v[196:199], v149 offset:53248
	ds_read_b128 v[200:203], v149 offset:54272
	ds_read_b128 v[204:207], v149 offset:55296
	ds_read_b128 v[208:211], v149 offset:56320
	s_add_u32 s30, s40, 0x80
	s_addc_u32 s31, s41, 0
	s_mov_b32 m0, s64
	s_nop 0
	global_load_lds_dwordx4 v142, s[30:31] offset:0
	s_nop 0
	s_mov_b32 m0, s65
	s_nop 0
	global_load_lds_dwordx4 v144, s[30:31] offset:0
	s_add_u32 s30, s40, 0x160080
	s_addc_u32 s31, s41, 0
	s_mov_b32 m0, s68
	s_nop 0
	global_load_lds_dwordx4 v142, s[30:31] offset:0
	s_nop 0
	s_mov_b32 m0, s69
	s_nop 0
	global_load_lds_dwordx4 v144, s[30:31] offset:0
	s_nop 0
	s_mov_b32 m0, s66
	s_nop 0
	global_load_lds_dwordx4 v1, s[38:39] offset:0
	s_nop 0
	s_mov_b32 m0, s67
	s_nop 0
	global_load_lds_dwordx4 v143, s[38:39] offset:0
	s_waitcnt vmcnt(8)
	s_waitcnt lgkmcnt(0)
	s_barrier
	s_setprio 1
	s_waitcnt lgkmcnt(7)
	s_waitcnt lgkmcnt(5)
	s_waitcnt lgkmcnt(3)
	s_waitcnt lgkmcnt(1)
	s_waitcnt lgkmcnt(0)
	v_mfma_f32_16x16x32_bf16 v[66:69], v[138:141], v[180:183], v[66:69]
	v_mfma_f32_16x16x32_bf16 v[66:69], v[152:155], v[184:187], v[66:69]
	v_mfma_f32_16x16x32_bf16 v[62:65], v[156:159], v[180:183], v[62:65]
	v_mfma_f32_16x16x32_bf16 v[62:65], v[160:163], v[184:187], v[62:65]
	v_mfma_f32_16x16x32_bf16 v[50:53], v[138:141], v[188:191], v[50:53]
	v_mfma_f32_16x16x32_bf16 v[50:53], v[152:155], v[192:195], v[50:53]
	v_mfma_f32_16x16x32_bf16 v[46:49], v[156:159], v[188:191], v[46:49]
	v_mfma_f32_16x16x32_bf16 v[46:49], v[160:163], v[192:195], v[46:49]
	v_mfma_f32_16x16x32_bf16 v[34:37], v[138:141], v[196:199], v[34:37]
	v_mfma_f32_16x16x32_bf16 v[34:37], v[152:155], v[200:203], v[34:37]
	v_mfma_f32_16x16x32_bf16 v[30:33], v[156:159], v[196:199], v[30:33]
	v_mfma_f32_16x16x32_bf16 v[30:33], v[160:163], v[200:203], v[30:33]
	v_mfma_f32_16x16x32_bf16 v[18:21], v[138:141], v[204:207], v[18:21]
	v_mfma_f32_16x16x32_bf16 v[18:21], v[152:155], v[208:211], v[18:21]
	v_mfma_f32_16x16x32_bf16 v[14:17], v[156:159], v[204:207], v[14:17]
	v_mfma_f32_16x16x32_bf16 v[14:17], v[160:163], v[208:211], v[14:17]
	s_setprio 0
	s_setprio 1
	v_mfma_f32_16x16x32_bf16 v[58:61], v[164:167], v[180:183], v[58:61]
	v_mfma_f32_16x16x32_bf16 v[54:57], v[172:175], v[180:183], v[54:57]
	v_mfma_f32_16x16x32_bf16 v[42:45], v[164:167], v[188:191], v[42:45]
	v_mfma_f32_16x16x32_bf16 v[38:41], v[172:175], v[188:191], v[38:41]
	v_mfma_f32_16x16x32_bf16 v[26:29], v[164:167], v[196:199], v[26:29]
	v_mfma_f32_16x16x32_bf16 v[22:25], v[172:175], v[196:199], v[22:25]
	v_mfma_f32_16x16x32_bf16 v[8:11], v[164:167], v[204:207], v[10:13]
	v_mfma_f32_16x16x32_bf16 v[4:7], v[172:175], v[204:207], v[4:7]
	v_mfma_f32_16x16x32_bf16 v[58:61], v[168:171], v[184:187], v[58:61]
	v_mfma_f32_16x16x32_bf16 v[54:57], v[176:179], v[184:187], v[54:57]
	v_mfma_f32_16x16x32_bf16 v[42:45], v[168:171], v[192:195], v[42:45]
	v_mfma_f32_16x16x32_bf16 v[38:41], v[176:179], v[192:195], v[38:41]
	v_mfma_f32_16x16x32_bf16 v[26:29], v[168:171], v[200:203], v[26:29]
	v_mfma_f32_16x16x32_bf16 v[22:25], v[176:179], v[200:203], v[22:25]
	v_mfma_f32_16x16x32_bf16 v[10:13], v[168:171], v[208:211], v[8:11]
	v_mfma_f32_16x16x32_bf16 v[6:9], v[176:179], v[208:211], v[4:7]
	s_setprio 0
	s_barrier
	s_add_i32 s80, s80, 2
	s_add_u32 s81, s81, 0x100
	s_addc_u32 s82, s82, 0
	s_add_u32 s83, s83, 0x100
	s_addc_u32 s84, s84, 0
	s_add_u32 s36, s36, 0x100
	s_addc_u32 s37, s37, 0
	s_cmpk_gt_u32 s80, 0x55
	s_cbranch_scc0 .LBB0_2960
	s_and_b64 vcc, exec, s[16:17]
	s_cbranch_vccz .LBB0_2963
	s_barrier

.LBB0_3114:
	ds_read_b128 v[136:139], v149
	ds_read_b128 v[154:157], v149 offset:1024
	ds_read_b128 v[158:161], v149 offset:2048
	ds_read_b128 v[162:165], v149 offset:3072
	ds_read_b128 v[166:169], v150
	ds_read_b128 v[170:173], v150 offset:1024
	ds_read_b128 v[174:177], v150 offset:2048
	ds_read_b128 v[178:181], v150 offset:3072
	s_cmp_eq_u32 s78, 28
	s_cselect_b32 s40, s72, s76
	s_cselect_b32 s41, s19, s77
	s_cselect_b32 s38, s73, s74
	s_cselect_b32 s39, s17, s75
	s_add_u32 s36, s40, 0x80
	s_addc_u32 s37, s41, 0
	ds_read_b128 v[182:185], v151
	ds_read_b128 v[186:189], v151 offset:1024
	ds_read_b128 v[190:193], v151 offset:2048
	ds_read_b128 v[194:197], v151 offset:3072
	ds_read_b128 v[198:201], v151 offset:4096
	ds_read_b128 v[202:205], v151 offset:5120
	ds_read_b128 v[206:209], v151 offset:6144
	ds_read_b128 v[210:213], v151 offset:7168
	s_mov_b32 m0, s67
	s_nop 0
	global_load_lds_dwordx4 v1, s[28:29] offset:0
	s_nop 0
	s_mov_b32 m0, s68
	s_nop 0
	global_load_lds_dwordx4 v143, s[28:29] offset:0
	s_waitcnt vmcnt(8)
	s_waitcnt lgkmcnt(0)
	s_barrier
	s_setprio 1
	s_waitcnt lgkmcnt(7)
	s_waitcnt lgkmcnt(5)
	s_waitcnt lgkmcnt(3)
	s_waitcnt lgkmcnt(1)
	s_waitcnt lgkmcnt(0)
	v_mfma_f32_16x16x32_bf16 v[126:129], v[136:139], v[182:185], v[126:129]
	v_mfma_f32_16x16x32_bf16 v[126:129], v[154:157], v[186:189], v[126:129]
	v_mfma_f32_16x16x32_bf16 v[122:125], v[158:161], v[182:185], v[122:125]
	v_mfma_f32_16x16x32_bf16 v[122:125], v[162:165], v[186:189], v[122:125]
	v_mfma_f32_16x16x32_bf16 v[114:117], v[136:139], v[190:193], v[114:117]
	v_mfma_f32_16x16x32_bf16 v[114:117], v[154:157], v[194:197], v[114:117]
	v_mfma_f32_16x16x32_bf16 v[106:109], v[158:161], v[190:193], v[106:109]
	v_mfma_f32_16x16x32_bf16 v[106:109], v[162:165], v[194:197], v[106:109]
	v_mfma_f32_16x16x32_bf16 v[98:101], v[136:139], v[198:201], v[98:101]
	v_mfma_f32_16x16x32_bf16 v[98:101], v[154:157], v[202:205], v[98:101]
	v_mfma_f32_16x16x32_bf16 v[90:93], v[158:161], v[198:201], v[90:93]
	v_mfma_f32_16x16x32_bf16 v[90:93], v[162:165], v[202:205], v[90:93]
	v_mfma_f32_16x16x32_bf16 v[82:85], v[136:139], v[206:209], v[82:85]
	v_mfma_f32_16x16x32_bf16 v[82:85], v[154:157], v[210:213], v[82:85]
	v_mfma_f32_16x16x32_bf16 v[74:77], v[158:161], v[206:209], v[74:77]
	v_mfma_f32_16x16x32_bf16 v[74:77], v[162:165], v[210:213], v[74:77]
	s_setprio 0
	s_setprio 1
	v_mfma_f32_16x16x32_bf16 v[118:121], v[166:169], v[182:185], v[118:121]
	v_mfma_f32_16x16x32_bf16 v[118:121], v[170:173], v[186:189], v[118:121]
	v_mfma_f32_16x16x32_bf16 v[110:113], v[174:177], v[182:185], v[110:113]
	v_mfma_f32_16x16x32_bf16 v[110:113], v[178:181], v[186:189], v[110:113]
	v_mfma_f32_16x16x32_bf16 v[102:105], v[166:169], v[190:193], v[102:105]
	v_mfma_f32_16x16x32_bf16 v[102:105], v[170:173], v[194:197], v[102:105]
	v_mfma_f32_16x16x32_bf16 v[94:97], v[174:177], v[190:193], v[94:97]
	v_mfma_f32_16x16x32_bf16 v[94:97], v[178:181], v[194:197], v[94:97]
	v_mfma_f32_16x16x32_bf16 v[86:89], v[166:169], v[198:201], v[86:89]
	v_mfma_f32_16x16x32_bf16 v[86:89], v[170:173], v[202:205], v[86:89]
	v_mfma_f32_16x16x32_bf16 v[78:81], v[174:177], v[198:201], v[78:81]
	v_mfma_f32_16x16x32_bf16 v[78:81], v[178:181], v[202:205], v[78:81]
	v_mfma_f32_16x16x32_bf16 v[70:73], v[166:169], v[206:209], v[70:73]
	v_mfma_f32_16x16x32_bf16 v[70:73], v[170:173], v[210:213], v[70:73]
	v_mfma_f32_16x16x32_bf16 v[66:69], v[174:177], v[206:209], v[66:69]
	v_mfma_f32_16x16x32_bf16 v[66:69], v[178:181], v[210:213], v[66:69]
	s_setprio 0
	s_barrier
	ds_read_b128 v[182:185], v151 offset:16384
	ds_read_b128 v[186:189], v151 offset:17408
	ds_read_b128 v[190:193], v151 offset:18432
	ds_read_b128 v[194:197], v151 offset:19456
	ds_read_b128 v[198:201], v151 offset:20480
	ds_read_b128 v[202:205], v151 offset:21504
	ds_read_b128 v[206:209], v151 offset:22528
	ds_read_b128 v[210:213], v151 offset:23552
	s_mov_b32 m0, s25
	s_nop 0
	global_load_lds_dwordx4 v135, s[38:39] offset:0
	s_add_u32 s30, s38, 0x80000
	s_mov_b32 m0, s46
	s_nop 0
	global_load_lds_dwordx4 v145, s[38:39] offset:0
	s_addc_u32 s31, s39, 0
	s_mov_b32 m0, s47
	s_nop 0
	global_load_lds_dwordx4 v135, s[30:31] offset:0
	s_nop 0
	s_mov_b32 m0, s52
	s_nop 0
	global_load_lds_dwordx4 v145, s[30:31] offset:0
	s_nop 0
	s_mov_b32 m0, s43
	s_nop 0
	global_load_lds_dwordx4 v1, s[40:41] offset:0
	s_nop 0
	s_mov_b32 m0, s53
	s_nop 0
	global_load_lds_dwordx4 v143, s[40:41] offset:0
	s_waitcnt vmcnt(8)
	s_waitcnt lgkmcnt(0)
	s_barrier
	s_setprio 1
	s_waitcnt lgkmcnt(7)
	s_waitcnt lgkmcnt(5)
	s_waitcnt lgkmcnt(3)
	s_waitcnt lgkmcnt(1)
	s_waitcnt lgkmcnt(0)
	v_mfma_f32_16x16x32_bf16 v[62:65], v[136:139], v[182:185], v[62:65]
	v_mfma_f32_16x16x32_bf16 v[62:65], v[154:157], v[186:189], v[62:65]
	v_mfma_f32_16x16x32_bf16 v[58:61], v[158:161], v[182:185], v[58:61]
	v_mfma_f32_16x16x32_bf16 v[58:61], v[162:165], v[186:189], v[58:61]
	v_mfma_f32_16x16x32_bf16 v[50:53], v[136:139], v[190:193], v[50:53]
	v_mfma_f32_16x16x32_bf16 v[50:53], v[154:157], v[194:197], v[50:53]
	v_mfma_f32_16x16x32_bf16 v[42:45], v[158:161], v[190:193], v[42:45]
	v_mfma_f32_16x16x32_bf16 v[42:45], v[162:165], v[194:197], v[42:45]
	v_mfma_f32_16x16x32_bf16 v[34:37], v[136:139], v[198:201], v[34:37]
	v_mfma_f32_16x16x32_bf16 v[34:37], v[154:157], v[202:205], v[34:37]
	v_mfma_f32_16x16x32_bf16 v[26:29], v[158:161], v[198:201], v[26:29]
	v_mfma_f32_16x16x32_bf16 v[26:29], v[162:165], v[202:205], v[26:29]
	v_mfma_f32_16x16x32_bf16 v[18:21], v[136:139], v[206:209], v[18:21]
	v_mfma_f32_16x16x32_bf16 v[18:21], v[154:157], v[210:213], v[18:21]
	v_mfma_f32_16x16x32_bf16 v[10:13], v[158:161], v[206:209], v[10:13]
	v_mfma_f32_16x16x32_bf16 v[10:13], v[162:165], v[210:213], v[10:13]
	s_setprio 0
	s_setprio 1
	v_mfma_f32_16x16x32_bf16 v[54:57], v[166:169], v[182:185], v[54:57]
	v_mfma_f32_16x16x32_bf16 v[54:57], v[170:173], v[186:189], v[54:57]
	v_mfma_f32_16x16x32_bf16 v[46:49], v[174:177], v[182:185], v[46:49]
	v_mfma_f32_16x16x32_bf16 v[46:49], v[178:181], v[186:189], v[46:49]
	v_mfma_f32_16x16x32_bf16 v[38:41], v[166:169], v[190:193], v[38:41]
	v_mfma_f32_16x16x32_bf16 v[38:41], v[170:173], v[194:197], v[38:41]
	v_mfma_f32_16x16x32_bf16 v[30:33], v[174:177], v[190:193], v[30:33]
	v_mfma_f32_16x16x32_bf16 v[30:33], v[178:181], v[194:197], v[30:33]
	v_mfma_f32_16x16x32_bf16 v[22:25], v[166:169], v[198:201], v[22:25]
	v_mfma_f32_16x16x32_bf16 v[22:25], v[170:173], v[202:205], v[22:25]
	v_mfma_f32_16x16x32_bf16 v[14:17], v[174:177], v[198:201], v[14:17]
	v_mfma_f32_16x16x32_bf16 v[14:17], v[178:181], v[202:205], v[14:17]
	v_mfma_f32_16x16x32_bf16 v[6:9], v[166:169], v[206:209], v[6:9]
	v_mfma_f32_16x16x32_bf16 v[6:9], v[170:173], v[210:213], v[6:9]
	v_mfma_f32_16x16x32_bf16 v[2:5], v[174:177], v[206:209], v[2:5]
	v_mfma_f32_16x16x32_bf16 v[2:5], v[178:181], v[210:213], v[2:5]
	s_setprio 0
	s_barrier
; #define PG8_KSETUP() const bool last = (t == nt - 2); const char* a1 = cA + (size_t)(t + 1) * kstep; \
;             const char* a2 = last ? nA : cA + (size_t)(t + 2) * kstep; const char* b2 = last ? nB : cB + (size_t)(t + 2) * kstep; const char* a3 = a2 + kstep; const char* b3 = b2 + kstep; \
;             if (last && has_next) S.a_ready(nxt)
; template <class Epi, class Sched, bool ALIGN_EPI = false, bool SP2 = false>
; __device__ __forceinline__ void gemm_phase(PG8_LAS unsigned char* lds, const Gemm g, const Sched& S, const Epi& E) {
;     ...
;         int t0 = 0;
;         if constexpr (SP2 && Epi::NVM == 16) { if (ui > 0) { const int t = 0; PG8_KSETUP(); PG8_KITER_SP2(24, 24); t0 = 2; } }
;         if constexpr (SP2 && Epi::NVM == 8) { if (ui > 0) { const int t = 0; PG8_KSETUP(); PG8_KITER_SP2(16, 16); t0 = 2; } }
;         for (int t = t0; t < nt; t += 2) {
	ds_read_b128 v[136:139], v152
	ds_read_b128 v[154:157], v152 offset:1024
	ds_read_b128 v[158:161], v152 offset:2048
	ds_read_b128 v[162:165], v152 offset:3072
	ds_read_b128 v[166:169], v153
	ds_read_b128 v[170:173], v153 offset:1024
	ds_read_b128 v[174:177], v153 offset:2048
	ds_read_b128 v[178:181], v153 offset:3072
	ds_read_b128 v[182:185], v151 offset:32768
	ds_read_b128 v[186:189], v151 offset:33792
	ds_read_b128 v[190:193], v151 offset:34816
	ds_read_b128 v[194:197], v151 offset:35840
	ds_read_b128 v[198:201], v151 offset:36864
	ds_read_b128 v[202:205], v151 offset:37888
	ds_read_b128 v[206:209], v151 offset:38912
	ds_read_b128 v[210:213], v151 offset:39936
	s_add_u32 s30, s40, 0x80000
	s_addc_u32 s31, s41, 0
	s_mov_b32 m0, s54
	s_nop 0
	global_load_lds_dwordx4 v1, s[30:31] offset:0
	s_nop 0
	s_mov_b32 m0, s55
	s_nop 0
	global_load_lds_dwordx4 v143, s[30:31] offset:0
	s_waitcnt vmcnt(8)
	s_waitcnt lgkmcnt(0)
	s_barrier
	s_setprio 1
	s_waitcnt lgkmcnt(7)
	s_waitcnt lgkmcnt(5)
	s_waitcnt lgkmcnt(3)
	s_waitcnt lgkmcnt(1)
	s_waitcnt lgkmcnt(0)
	v_mfma_f32_16x16x32_bf16 v[126:129], v[136:139], v[182:185], v[126:129]
	v_mfma_f32_16x16x32_bf16 v[126:129], v[154:157], v[186:189], v[126:129]
	v_mfma_f32_16x16x32_bf16 v[122:125], v[158:161], v[182:185], v[122:125]
	v_mfma_f32_16x16x32_bf16 v[122:125], v[162:165], v[186:189], v[122:125]
	v_mfma_f32_16x16x32_bf16 v[114:117], v[136:139], v[190:193], v[114:117]
	v_mfma_f32_16x16x32_bf16 v[114:117], v[154:157], v[194:197], v[114:117]
	v_mfma_f32_16x16x32_bf16 v[106:109], v[158:161], v[190:193], v[106:109]
	v_mfma_f32_16x16x32_bf16 v[106:109], v[162:165], v[194:197], v[106:109]
	v_mfma_f32_16x16x32_bf16 v[98:101], v[136:139], v[198:201], v[98:101]
	v_mfma_f32_16x16x32_bf16 v[98:101], v[154:157], v[202:205], v[98:101]
	v_mfma_f32_16x16x32_bf16 v[90:93], v[158:161], v[198:201], v[90:93]
	v_mfma_f32_16x16x32_bf16 v[90:93], v[162:165], v[202:205], v[90:93]
	v_mfma_f32_16x16x32_bf16 v[82:85], v[136:139], v[206:209], v[82:85]
	v_mfma_f32_16x16x32_bf16 v[82:85], v[154:157], v[210:213], v[82:85]
	v_mfma_f32_16x16x32_bf16 v[74:77], v[158:161], v[206:209], v[74:77]
	v_mfma_f32_16x16x32_bf16 v[74:77], v[162:165], v[210:213], v[74:77]
	s_setprio 0
	s_setprio 1
	v_mfma_f32_16x16x32_bf16 v[118:121], v[166:169], v[182:185], v[118:121]
	v_mfma_f32_16x16x32_bf16 v[118:121], v[170:173], v[186:189], v[118:121]
	v_mfma_f32_16x16x32_bf16 v[110:113], v[174:177], v[182:185], v[110:113]
	v_mfma_f32_16x16x32_bf16 v[110:113], v[178:181], v[186:189], v[110:113]
	v_mfma_f32_16x16x32_bf16 v[102:105], v[166:169], v[190:193], v[102:105]
	v_mfma_f32_16x16x32_bf16 v[102:105], v[170:173], v[194:197], v[102:105]
	v_mfma_f32_16x16x32_bf16 v[94:97], v[174:177], v[190:193], v[94:97]
	v_mfma_f32_16x16x32_bf16 v[94:97], v[178:181], v[194:197], v[94:97]
	v_mfma_f32_16x16x32_bf16 v[86:89], v[166:169], v[198:201], v[86:89]
	v_mfma_f32_16x16x32_bf16 v[86:89], v[170:173], v[202:205], v[86:89]
	v_mfma_f32_16x16x32_bf16 v[78:81], v[174:177], v[198:201], v[78:81]
	v_mfma_f32_16x16x32_bf16 v[78:81], v[178:181], v[202:205], v[78:81]
	v_mfma_f32_16x16x32_bf16 v[70:73], v[166:169], v[206:209], v[70:73]
	v_mfma_f32_16x16x32_bf16 v[70:73], v[170:173], v[210:213], v[70:73]
	v_mfma_f32_16x16x32_bf16 v[66:69], v[174:177], v[206:209], v[66:69]
	v_mfma_f32_16x16x32_bf16 v[66:69], v[178:181], v[210:213], v[66:69]
	s_setprio 0
	s_barrier
	ds_read_b128 v[182:185], v151 offset:49152
	ds_read_b128 v[186:189], v151 offset:50176
	ds_read_b128 v[190:193], v151 offset:51200
	ds_read_b128 v[194:197], v151 offset:52224
	ds_read_b128 v[198:201], v151 offset:53248
	ds_read_b128 v[202:205], v151 offset:54272
	ds_read_b128 v[206:209], v151 offset:55296
	ds_read_b128 v[210:213], v151 offset:56320
	s_add_u32 s30, s38, 0x80
	s_addc_u32 s31, s39, 0
	s_mov_b32 m0, s57
	s_nop 0
	global_load_lds_dwordx4 v135, s[30:31] offset:0
	s_nop 0
	s_mov_b32 m0, s58
	s_nop 0
	global_load_lds_dwordx4 v145, s[30:31] offset:0
	s_add_u32 s30, s38, 0x80080
	s_addc_u32 s31, s39, 0
	s_mov_b32 m0, s65
	s_nop 0
	global_load_lds_dwordx4 v135, s[30:31] offset:0
	s_nop 0
	s_mov_b32 m0, s66
	s_nop 0
	global_load_lds_dwordx4 v145, s[30:31] offset:0
	s_nop 0
	s_mov_b32 m0, s59
	s_nop 0
	global_load_lds_dwordx4 v1, s[36:37] offset:0
	s_nop 0
	s_mov_b32 m0, s64
	s_nop 0
	global_load_lds_dwordx4 v143, s[36:37] offset:0
	s_waitcnt vmcnt(8)
	s_waitcnt lgkmcnt(0)
	s_barrier
	s_setprio 1
	s_waitcnt lgkmcnt(7)
	s_waitcnt lgkmcnt(5)
	s_waitcnt lgkmcnt(3)
	s_waitcnt lgkmcnt(1)
	s_waitcnt lgkmcnt(0)
	v_mfma_f32_16x16x32_bf16 v[62:65], v[136:139], v[182:185], v[62:65]
	v_mfma_f32_16x16x32_bf16 v[62:65], v[154:157], v[186:189], v[62:65]
	v_mfma_f32_16x16x32_bf16 v[58:61], v[158:161], v[182:185], v[58:61]
	v_mfma_f32_16x16x32_bf16 v[58:61], v[162:165], v[186:189], v[58:61]
	v_mfma_f32_16x16x32_bf16 v[50:53], v[136:139], v[190:193], v[50:53]
	v_mfma_f32_16x16x32_bf16 v[50:53], v[154:157], v[194:197], v[50:53]
	v_mfma_f32_16x16x32_bf16 v[42:45], v[158:161], v[190:193], v[42:45]
	v_mfma_f32_16x16x32_bf16 v[42:45], v[162:165], v[194:197], v[42:45]
	v_mfma_f32_16x16x32_bf16 v[34:37], v[136:139], v[198:201], v[34:37]
	v_mfma_f32_16x16x32_bf16 v[34:37], v[154:157], v[202:205], v[34:37]
	v_mfma_f32_16x16x32_bf16 v[26:29], v[158:161], v[198:201], v[26:29]
	v_mfma_f32_16x16x32_bf16 v[26:29], v[162:165], v[202:205], v[26:29]
	v_mfma_f32_16x16x32_bf16 v[18:21], v[136:139], v[206:209], v[18:21]
	v_mfma_f32_16x16x32_bf16 v[18:21], v[154:157], v[210:213], v[18:21]
	v_mfma_f32_16x16x32_bf16 v[10:13], v[158:161], v[206:209], v[10:13]
	v_mfma_f32_16x16x32_bf16 v[10:13], v[162:165], v[210:213], v[10:13]
	s_setprio 0
	s_setprio 1
	v_mfma_f32_16x16x32_bf16 v[54:57], v[166:169], v[182:185], v[54:57]
	v_mfma_f32_16x16x32_bf16 v[54:57], v[170:173], v[186:189], v[54:57]
	v_mfma_f32_16x16x32_bf16 v[46:49], v[174:177], v[182:185], v[46:49]
	v_mfma_f32_16x16x32_bf16 v[46:49], v[178:181], v[186:189], v[46:49]
	v_mfma_f32_16x16x32_bf16 v[38:41], v[166:169], v[190:193], v[38:41]
	v_mfma_f32_16x16x32_bf16 v[38:41], v[170:173], v[194:197], v[38:41]
	v_mfma_f32_16x16x32_bf16 v[30:33], v[174:177], v[190:193], v[30:33]
	v_mfma_f32_16x16x32_bf16 v[30:33], v[178:181], v[194:197], v[30:33]
	v_mfma_f32_16x16x32_bf16 v[22:25], v[166:169], v[198:201], v[22:25]
	v_mfma_f32_16x16x32_bf16 v[22:25], v[170:173], v[202:205], v[22:25]
	v_mfma_f32_16x16x32_bf16 v[14:17], v[174:177], v[198:201], v[14:17]
	v_mfma_f32_16x16x32_bf16 v[14:17], v[178:181], v[202:205], v[14:17]
	v_mfma_f32_16x16x32_bf16 v[6:9], v[166:169], v[206:209], v[6:9]
	v_mfma_f32_16x16x32_bf16 v[6:9], v[170:173], v[210:213], v[6:9]
	v_mfma_f32_16x16x32_bf16 v[2:5], v[174:177], v[206:209], v[2:5]
	v_mfma_f32_16x16x32_bf16 v[2:5], v[178:181], v[210:213], v[2:5]
	s_setprio 0
	s_barrier
	s_add_i32 s78, s78, 2
	s_add_u32 s74, s74, 0x100
	s_addc_u32 s75, s75, 0
	s_add_u32 s76, s76, 0x100
	s_addc_u32 s77, s77, 0
	s_add_u32 s28, s28, 0x100
	s_addc_u32 s29, s29, 0
	s_cmp_gt_u32 s78, 29
	s_cbranch_scc0 .LBB0_3114
	s_and_b64 vcc, exec, s[14:15]
	s_cbranch_vccz .LBB0_3117
	s_barrier

.LBB0_3468:
	ds_read_b128 v[138:141], v147
	ds_read_b128 v[152:155], v147 offset:1024
	ds_read_b128 v[156:159], v147 offset:2048
	ds_read_b128 v[160:163], v147 offset:3072
	ds_read_b128 v[164:167], v148
	ds_read_b128 v[168:171], v148 offset:1024
	ds_read_b128 v[172:175], v148 offset:2048
	ds_read_b128 v[176:179], v148 offset:3072
	s_cmp_eq_u32 s80, 28
	s_cselect_b32 s52, s43, s83
	s_cselect_b32 s53, s37, s84
	s_cselect_b32 s50, s79, s81
	s_cselect_b32 s51, s29, s82
	s_add_u32 s48, s52, 0x80
	s_addc_u32 s49, s53, 0
	ds_read_b128 v[180:183], v149
	ds_read_b128 v[184:187], v149 offset:1024
	ds_read_b128 v[188:191], v149 offset:2048
	ds_read_b128 v[192:195], v149 offset:3072
	ds_read_b128 v[196:199], v149 offset:4096
	ds_read_b128 v[200:203], v149 offset:5120
	ds_read_b128 v[204:207], v149 offset:6144
	ds_read_b128 v[208:211], v149 offset:7168
	s_mov_b32 m0, s73
	s_nop 0
	global_load_lds_dwordx4 v1, s[46:47] offset:0
	s_nop 0
	s_mov_b32 m0, s74
	s_nop 0
	global_load_lds_dwordx4 v143, s[46:47] offset:0
	s_waitcnt vmcnt(8)
	s_waitcnt lgkmcnt(0)
	s_barrier
	s_setprio 1
	s_waitcnt lgkmcnt(7)
	s_waitcnt lgkmcnt(5)
	s_waitcnt lgkmcnt(3)
	s_waitcnt lgkmcnt(1)
	s_waitcnt lgkmcnt(0)
	v_mfma_f32_16x16x32_bf16 v[130:133], v[138:141], v[180:183], v[130:133]
	v_mfma_f32_16x16x32_bf16 v[130:133], v[152:155], v[184:187], v[130:133]
	v_mfma_f32_16x16x32_bf16 v[126:129], v[156:159], v[180:183], v[126:129]
	v_mfma_f32_16x16x32_bf16 v[126:129], v[160:163], v[184:187], v[126:129]
	v_mfma_f32_16x16x32_bf16 v[114:117], v[138:141], v[188:191], v[114:117]
	v_mfma_f32_16x16x32_bf16 v[114:117], v[152:155], v[192:195], v[114:117]
	v_mfma_f32_16x16x32_bf16 v[110:113], v[156:159], v[188:191], v[110:113]
	v_mfma_f32_16x16x32_bf16 v[110:113], v[160:163], v[192:195], v[110:113]
	v_mfma_f32_16x16x32_bf16 v[98:101], v[138:141], v[196:199], v[98:101]
	v_mfma_f32_16x16x32_bf16 v[98:101], v[152:155], v[200:203], v[98:101]
	v_mfma_f32_16x16x32_bf16 v[94:97], v[156:159], v[196:199], v[94:97]
	v_mfma_f32_16x16x32_bf16 v[94:97], v[160:163], v[200:203], v[94:97]
	v_mfma_f32_16x16x32_bf16 v[82:85], v[138:141], v[204:207], v[82:85]
	v_mfma_f32_16x16x32_bf16 v[82:85], v[152:155], v[208:211], v[82:85]
	v_mfma_f32_16x16x32_bf16 v[78:81], v[156:159], v[204:207], v[78:81]
	v_mfma_f32_16x16x32_bf16 v[78:81], v[160:163], v[208:211], v[78:81]
	s_setprio 0
	s_setprio 1
	v_mfma_f32_16x16x32_bf16 v[122:125], v[164:167], v[180:183], v[122:125]
	v_mfma_f32_16x16x32_bf16 v[122:125], v[168:171], v[184:187], v[122:125]
	v_mfma_f32_16x16x32_bf16 v[118:121], v[172:175], v[180:183], v[118:121]
	v_mfma_f32_16x16x32_bf16 v[118:121], v[176:179], v[184:187], v[118:121]
	v_mfma_f32_16x16x32_bf16 v[106:109], v[164:167], v[188:191], v[106:109]
	v_mfma_f32_16x16x32_bf16 v[106:109], v[168:171], v[192:195], v[106:109]
	v_mfma_f32_16x16x32_bf16 v[102:105], v[172:175], v[188:191], v[102:105]
	v_mfma_f32_16x16x32_bf16 v[102:105], v[176:179], v[192:195], v[102:105]
	v_mfma_f32_16x16x32_bf16 v[90:93], v[164:167], v[196:199], v[90:93]
	v_mfma_f32_16x16x32_bf16 v[90:93], v[168:171], v[200:203], v[90:93]
	v_mfma_f32_16x16x32_bf16 v[86:89], v[172:175], v[196:199], v[86:89]
	v_mfma_f32_16x16x32_bf16 v[86:89], v[176:179], v[200:203], v[86:89]
	v_mfma_f32_16x16x32_bf16 v[74:77], v[164:167], v[204:207], v[74:77]
	v_mfma_f32_16x16x32_bf16 v[74:77], v[168:171], v[208:211], v[74:77]
	v_mfma_f32_16x16x32_bf16 v[70:73], v[172:175], v[204:207], v[70:73]
	v_mfma_f32_16x16x32_bf16 v[70:73], v[176:179], v[208:211], v[70:73]
	s_setprio 0
	s_barrier
	ds_read_b128 v[180:183], v149 offset:16384
	ds_read_b128 v[184:187], v149 offset:17408
	ds_read_b128 v[188:191], v149 offset:18432
	ds_read_b128 v[192:195], v149 offset:19456
	ds_read_b128 v[196:199], v149 offset:20480
	ds_read_b128 v[200:203], v149 offset:21504
	ds_read_b128 v[204:207], v149 offset:22528
	ds_read_b128 v[208:211], v149 offset:23552
	s_mov_b32 m0, s45
	s_nop 0
	global_load_lds_dwordx4 v142, s[50:51] offset:0
	s_add_u32 s30, s50, 0x80000
	s_mov_b32 m0, s54
	s_nop 0
	global_load_lds_dwordx4 v144, s[50:51] offset:0
	s_addc_u32 s31, s51, 0
	s_mov_b32 m0, s55
	s_nop 0
	global_load_lds_dwordx4 v142, s[30:31] offset:0
	s_nop 0
	s_mov_b32 m0, s56
	s_nop 0
	global_load_lds_dwordx4 v144, s[30:31] offset:0
	s_nop 0
	s_mov_b32 m0, s33
	s_nop 0
	global_load_lds_dwordx4 v1, s[52:53] offset:0
	s_nop 0
	s_mov_b32 m0, s57
	s_nop 0
	global_load_lds_dwordx4 v143, s[52:53] offset:0
	s_waitcnt vmcnt(8)
	s_waitcnt lgkmcnt(0)
	s_barrier
	s_setprio 1
	s_waitcnt lgkmcnt(7)
	s_waitcnt lgkmcnt(5)
	s_waitcnt lgkmcnt(3)
	s_waitcnt lgkmcnt(1)
	s_waitcnt lgkmcnt(0)
	v_mfma_f32_16x16x32_bf16 v[66:69], v[138:141], v[180:183], v[66:69]
	v_mfma_f32_16x16x32_bf16 v[66:69], v[152:155], v[184:187], v[66:69]
	v_mfma_f32_16x16x32_bf16 v[62:65], v[156:159], v[180:183], v[62:65]
	v_mfma_f32_16x16x32_bf16 v[62:65], v[160:163], v[184:187], v[62:65]
	v_mfma_f32_16x16x32_bf16 v[50:53], v[138:141], v[188:191], v[50:53]
	v_mfma_f32_16x16x32_bf16 v[50:53], v[152:155], v[192:195], v[50:53]
	v_mfma_f32_16x16x32_bf16 v[46:49], v[156:159], v[188:191], v[46:49]
	v_mfma_f32_16x16x32_bf16 v[46:49], v[160:163], v[192:195], v[46:49]
	v_mfma_f32_16x16x32_bf16 v[34:37], v[138:141], v[196:199], v[34:37]
	v_mfma_f32_16x16x32_bf16 v[34:37], v[152:155], v[200:203], v[34:37]
	v_mfma_f32_16x16x32_bf16 v[30:33], v[156:159], v[196:199], v[30:33]
	v_mfma_f32_16x16x32_bf16 v[30:33], v[160:163], v[200:203], v[30:33]
	v_mfma_f32_16x16x32_bf16 v[18:21], v[138:141], v[204:207], v[18:21]
	v_mfma_f32_16x16x32_bf16 v[18:21], v[152:155], v[208:211], v[18:21]
	v_mfma_f32_16x16x32_bf16 v[14:17], v[156:159], v[204:207], v[14:17]
	v_mfma_f32_16x16x32_bf16 v[14:17], v[160:163], v[208:211], v[14:17]
	s_setprio 0
	s_setprio 1
	v_mfma_f32_16x16x32_bf16 v[58:61], v[164:167], v[180:183], v[58:61]
	v_mfma_f32_16x16x32_bf16 v[54:57], v[172:175], v[180:183], v[54:57]
	v_mfma_f32_16x16x32_bf16 v[42:45], v[164:167], v[188:191], v[42:45]
	v_mfma_f32_16x16x32_bf16 v[38:41], v[172:175], v[188:191], v[38:41]
	v_mfma_f32_16x16x32_bf16 v[26:29], v[164:167], v[196:199], v[26:29]
	v_mfma_f32_16x16x32_bf16 v[22:25], v[172:175], v[196:199], v[22:25]
	v_mfma_f32_16x16x32_bf16 v[10:13], v[164:167], v[204:207], v[10:13]
	v_mfma_f32_16x16x32_bf16 v[4:7], v[172:175], v[204:207], v[6:9]
	v_mfma_f32_16x16x32_bf16 v[58:61], v[168:171], v[184:187], v[58:61]
	v_mfma_f32_16x16x32_bf16 v[54:57], v[176:179], v[184:187], v[54:57]
	v_mfma_f32_16x16x32_bf16 v[42:45], v[168:171], v[192:195], v[42:45]
	v_mfma_f32_16x16x32_bf16 v[38:41], v[176:179], v[192:195], v[38:41]
	v_mfma_f32_16x16x32_bf16 v[26:29], v[168:171], v[200:203], v[26:29]
	v_mfma_f32_16x16x32_bf16 v[22:25], v[176:179], v[200:203], v[22:25]
	v_mfma_f32_16x16x32_bf16 v[10:13], v[168:171], v[208:211], v[10:13]
	v_mfma_f32_16x16x32_bf16 v[4:7], v[176:179], v[208:211], v[4:7]
	s_setprio 0
	s_barrier
	ds_read_b128 v[138:141], v150
	ds_read_b128 v[152:155], v150 offset:1024
	ds_read_b128 v[156:159], v150 offset:2048
	ds_read_b128 v[160:163], v150 offset:3072
	ds_read_b128 v[164:167], v151
	ds_read_b128 v[168:171], v151 offset:1024
	ds_read_b128 v[172:175], v151 offset:2048
	ds_read_b128 v[176:179], v151 offset:3072
	ds_read_b128 v[180:183], v149 offset:32768
	ds_read_b128 v[184:187], v149 offset:33792
	ds_read_b128 v[188:191], v149 offset:34816
	ds_read_b128 v[192:195], v149 offset:35840
	ds_read_b128 v[196:199], v149 offset:36864
	ds_read_b128 v[200:203], v149 offset:37888
	ds_read_b128 v[204:207], v149 offset:38912
	ds_read_b128 v[208:211], v149 offset:39936
	s_add_u32 s30, s52, 0x80000
	s_addc_u32 s31, s53, 0
	s_mov_b32 m0, s58
	s_nop 0
	global_load_lds_dwordx4 v1, s[30:31] offset:0
	s_nop 0
	s_mov_b32 m0, s59
	s_nop 0
	global_load_lds_dwordx4 v143, s[30:31] offset:0
	s_waitcnt vmcnt(8)
	s_waitcnt lgkmcnt(0)
	s_barrier
	s_setprio 1
	s_waitcnt lgkmcnt(7)
	s_waitcnt lgkmcnt(5)
	s_waitcnt lgkmcnt(3)
	s_waitcnt lgkmcnt(1)
	s_waitcnt lgkmcnt(0)
	v_mfma_f32_16x16x32_bf16 v[130:133], v[138:141], v[180:183], v[130:133]
	v_mfma_f32_16x16x32_bf16 v[130:133], v[152:155], v[184:187], v[130:133]
	v_mfma_f32_16x16x32_bf16 v[126:129], v[156:159], v[180:183], v[126:129]
	v_mfma_f32_16x16x32_bf16 v[126:129], v[160:163], v[184:187], v[126:129]
	v_mfma_f32_16x16x32_bf16 v[114:117], v[138:141], v[188:191], v[114:117]
	v_mfma_f32_16x16x32_bf16 v[114:117], v[152:155], v[192:195], v[114:117]
	v_mfma_f32_16x16x32_bf16 v[110:113], v[156:159], v[188:191], v[110:113]
	v_mfma_f32_16x16x32_bf16 v[110:113], v[160:163], v[192:195], v[110:113]
	v_mfma_f32_16x16x32_bf16 v[98:101], v[138:141], v[196:199], v[98:101]
	v_mfma_f32_16x16x32_bf16 v[98:101], v[152:155], v[200:203], v[98:101]
	v_mfma_f32_16x16x32_bf16 v[94:97], v[156:159], v[196:199], v[94:97]
	v_mfma_f32_16x16x32_bf16 v[94:97], v[160:163], v[200:203], v[94:97]
	v_mfma_f32_16x16x32_bf16 v[82:85], v[138:141], v[204:207], v[82:85]
	v_mfma_f32_16x16x32_bf16 v[82:85], v[152:155], v[208:211], v[82:85]
	v_mfma_f32_16x16x32_bf16 v[78:81], v[156:159], v[204:207], v[78:81]
	v_mfma_f32_16x16x32_bf16 v[78:81], v[160:163], v[208:211], v[78:81]
	s_setprio 0
	s_setprio 1
	v_mfma_f32_16x16x32_bf16 v[122:125], v[164:167], v[180:183], v[122:125]
	v_mfma_f32_16x16x32_bf16 v[122:125], v[168:171], v[184:187], v[122:125]
	v_mfma_f32_16x16x32_bf16 v[118:121], v[172:175], v[180:183], v[118:121]
	v_mfma_f32_16x16x32_bf16 v[118:121], v[176:179], v[184:187], v[118:121]
	v_mfma_f32_16x16x32_bf16 v[106:109], v[164:167], v[188:191], v[106:109]
	v_mfma_f32_16x16x32_bf16 v[106:109], v[168:171], v[192:195], v[106:109]
	v_mfma_f32_16x16x32_bf16 v[102:105], v[172:175], v[188:191], v[102:105]
	v_mfma_f32_16x16x32_bf16 v[102:105], v[176:179], v[192:195], v[102:105]
	v_mfma_f32_16x16x32_bf16 v[90:93], v[164:167], v[196:199], v[90:93]
	v_mfma_f32_16x16x32_bf16 v[90:93], v[168:171], v[200:203], v[90:93]
	v_mfma_f32_16x16x32_bf16 v[86:89], v[172:175], v[196:199], v[86:89]
	v_mfma_f32_16x16x32_bf16 v[86:89], v[176:179], v[200:203], v[86:89]
	v_mfma_f32_16x16x32_bf16 v[74:77], v[164:167], v[204:207], v[74:77]
	v_mfma_f32_16x16x32_bf16 v[74:77], v[168:171], v[208:211], v[74:77]
	v_mfma_f32_16x16x32_bf16 v[70:73], v[172:175], v[204:207], v[70:73]
	v_mfma_f32_16x16x32_bf16 v[70:73], v[176:179], v[208:211], v[70:73]
	s_setprio 0
	s_barrier
; #define PG8_KSETUP() const bool last = (t == nt - 2); const char* a1 = cA + (size_t)(t + 1) * kstep; \
;             const char* a2 = last ? nA : cA + (size_t)(t + 2) * kstep; const char* b2 = last ? nB : cB + (size_t)(t + 2) * kstep; const char* a3 = a2 + kstep; const char* b3 = b2 + kstep; \
;             if (last && has_next) S.a_ready(nxt)
; template <class Epi, class Sched, bool ALIGN_EPI = false, bool SP2 = false>
; __device__ __forceinline__ void gemm_phase(PG8_LAS unsigned char* lds, const Gemm g, const Sched& S, const Epi& E) {
;     ...
;         int t0 = 0;
;         if constexpr (SP2 && Epi::NVM == 16) { if (ui > 0) { const int t = 0; PG8_KSETUP(); PG8_KITER_SP2(24, 24); t0 = 2; } }
;         if constexpr (SP2 && Epi::NVM == 8) { if (ui > 0) { const int t = 0; PG8_KSETUP(); PG8_KITER_SP2(16, 16); t0 = 2; } }
;         for (int t = t0; t < nt; t += 2) {
	ds_read_b128 v[180:183], v149 offset:49152
	ds_read_b128 v[184:187], v149 offset:50176
	ds_read_b128 v[188:191], v149 offset:51200
	ds_read_b128 v[192:195], v149 offset:52224
	ds_read_b128 v[196:199], v149 offset:53248
	ds_read_b128 v[200:203], v149 offset:54272
	ds_read_b128 v[204:207], v149 offset:55296
	ds_read_b128 v[208:211], v149 offset:56320
	s_add_u32 s30, s50, 0x80
	s_addc_u32 s31, s51, 0
	s_mov_b32 m0, s67
	s_nop 0
	global_load_lds_dwordx4 v142, s[30:31] offset:0
	s_nop 0
	s_mov_b32 m0, s68
	s_nop 0
	global_load_lds_dwordx4 v144, s[30:31] offset:0
	s_add_u32 s30, s50, 0x80080
	s_addc_u32 s31, s51, 0
	s_mov_b32 m0, s71
	s_nop 0
	global_load_lds_dwordx4 v142, s[30:31] offset:0
	s_nop 0
	s_mov_b32 m0, s72
	s_nop 0
	global_load_lds_dwordx4 v144, s[30:31] offset:0
	s_nop 0
	s_mov_b32 m0, s69
	s_nop 0
	global_load_lds_dwordx4 v1, s[48:49] offset:0
	s_nop 0
	s_mov_b32 m0, s70
	s_nop 0
	global_load_lds_dwordx4 v143, s[48:49] offset:0
	s_waitcnt vmcnt(8)
	s_waitcnt lgkmcnt(0)
	s_barrier
	s_setprio 1
	s_waitcnt lgkmcnt(7)
	s_waitcnt lgkmcnt(5)
	s_waitcnt lgkmcnt(3)
	s_waitcnt lgkmcnt(1)
	s_waitcnt lgkmcnt(0)
	v_mfma_f32_16x16x32_bf16 v[66:69], v[138:141], v[180:183], v[66:69]
	v_mfma_f32_16x16x32_bf16 v[66:69], v[152:155], v[184:187], v[66:69]
	v_mfma_f32_16x16x32_bf16 v[62:65], v[156:159], v[180:183], v[62:65]
	v_mfma_f32_16x16x32_bf16 v[62:65], v[160:163], v[184:187], v[62:65]
	v_mfma_f32_16x16x32_bf16 v[50:53], v[138:141], v[188:191], v[50:53]
	v_mfma_f32_16x16x32_bf16 v[50:53], v[152:155], v[192:195], v[50:53]
	v_mfma_f32_16x16x32_bf16 v[46:49], v[156:159], v[188:191], v[46:49]
	v_mfma_f32_16x16x32_bf16 v[46:49], v[160:163], v[192:195], v[46:49]
	v_mfma_f32_16x16x32_bf16 v[34:37], v[138:141], v[196:199], v[34:37]
	v_mfma_f32_16x16x32_bf16 v[34:37], v[152:155], v[200:203], v[34:37]
	v_mfma_f32_16x16x32_bf16 v[30:33], v[156:159], v[196:199], v[30:33]
	v_mfma_f32_16x16x32_bf16 v[30:33], v[160:163], v[200:203], v[30:33]
	v_mfma_f32_16x16x32_bf16 v[18:21], v[138:141], v[204:207], v[18:21]
	v_mfma_f32_16x16x32_bf16 v[18:21], v[152:155], v[208:211], v[18:21]
	v_mfma_f32_16x16x32_bf16 v[14:17], v[156:159], v[204:207], v[14:17]
	v_mfma_f32_16x16x32_bf16 v[14:17], v[160:163], v[208:211], v[14:17]
	s_setprio 0
	s_setprio 1
	v_mfma_f32_16x16x32_bf16 v[58:61], v[164:167], v[180:183], v[58:61]
	v_mfma_f32_16x16x32_bf16 v[54:57], v[172:175], v[180:183], v[54:57]
	v_mfma_f32_16x16x32_bf16 v[42:45], v[164:167], v[188:191], v[42:45]
	v_mfma_f32_16x16x32_bf16 v[38:41], v[172:175], v[188:191], v[38:41]
	v_mfma_f32_16x16x32_bf16 v[26:29], v[164:167], v[196:199], v[26:29]
	v_mfma_f32_16x16x32_bf16 v[22:25], v[172:175], v[196:199], v[22:25]
	v_mfma_f32_16x16x32_bf16 v[8:11], v[164:167], v[204:207], v[10:13]
	v_mfma_f32_16x16x32_bf16 v[4:7], v[172:175], v[204:207], v[4:7]
	v_mfma_f32_16x16x32_bf16 v[58:61], v[168:171], v[184:187], v[58:61]
	v_mfma_f32_16x16x32_bf16 v[54:57], v[176:179], v[184:187], v[54:57]
	v_mfma_f32_16x16x32_bf16 v[42:45], v[168:171], v[192:195], v[42:45]
	v_mfma_f32_16x16x32_bf16 v[38:41], v[176:179], v[192:195], v[38:41]
	v_mfma_f32_16x16x32_bf16 v[26:29], v[168:171], v[200:203], v[26:29]
	v_mfma_f32_16x16x32_bf16 v[22:25], v[176:179], v[200:203], v[22:25]
	v_mfma_f32_16x16x32_bf16 v[10:13], v[168:171], v[208:211], v[8:11]
	v_mfma_f32_16x16x32_bf16 v[6:9], v[176:179], v[208:211], v[4:7]
	s_setprio 0
	s_barrier
	s_add_i32 s80, s80, 2
	s_add_u32 s81, s81, 0x100
	s_addc_u32 s82, s82, 0
	s_add_u32 s83, s83, 0x100
	s_addc_u32 s84, s84, 0
	s_add_u32 s46, s46, 0x100
	s_addc_u32 s47, s47, 0
	s_cmp_gt_u32 s80, 29
	s_cbranch_scc0 .LBB0_3468
	s_and_b64 vcc, exec, s[18:19]
	s_cbranch_vccz .LBB0_3471
	s_barrier

.LBB0_3621:
	ds_read_b128 v[138:141], v152
	ds_read_b128 v[142:145], v152 offset:1024
	ds_read_b128 v[158:161], v152 offset:2048
	ds_read_b128 v[162:165], v152 offset:3072
	ds_read_b128 v[166:169], v153
	ds_read_b128 v[170:173], v153 offset:1024
	ds_read_b128 v[174:177], v153 offset:2048
	ds_read_b128 v[178:181], v153 offset:3072
	s_cmp_eq_u32 s72, 28
	s_cselect_b32 s40, s70, s75
	s_cselect_b32 s41, s19, s76
	s_cselect_b32 s38, s71, s73
	s_cselect_b32 s39, s17, s74
	s_add_u32 s36, s40, 0x80
	s_addc_u32 s37, s41, 0
	ds_read_b128 v[182:185], v154
	ds_read_b128 v[186:189], v154 offset:1024
	ds_read_b128 v[190:193], v154 offset:2048
	ds_read_b128 v[194:197], v154 offset:3072
	ds_read_b128 v[198:201], v154 offset:4096
	ds_read_b128 v[202:205], v154 offset:5120
	ds_read_b128 v[206:209], v154 offset:6144
	ds_read_b128 v[210:213], v154 offset:7168
	s_add_u32 s30, s75, 0x7ff80
	s_addc_u32 s31, s76, 0
	s_mov_b32 m0, s56
	s_nop 0
	global_load_lds_dwordx4 v1, s[30:31] offset:0
	s_nop 0
	s_mov_b32 m0, s57
	s_nop 0
	global_load_lds_dwordx4 v147, s[30:31] offset:0
	s_waitcnt vmcnt(8)
	s_waitcnt lgkmcnt(0)
	s_barrier
	s_setprio 1
	s_waitcnt lgkmcnt(0)
	v_mfma_f32_16x16x32_bf16 v[130:133], v[138:141], v[182:185], v[130:133]
	v_mfma_f32_16x16x32_bf16 v[130:133], v[142:145], v[186:189], v[130:133]
	v_mfma_f32_16x16x32_bf16 v[126:129], v[158:161], v[182:185], v[126:129]
	v_mfma_f32_16x16x32_bf16 v[126:129], v[162:165], v[186:189], v[126:129]
	v_mfma_f32_16x16x32_bf16 v[114:117], v[138:141], v[190:193], v[114:117]
	v_mfma_f32_16x16x32_bf16 v[114:117], v[142:145], v[194:197], v[114:117]
	v_mfma_f32_16x16x32_bf16 v[110:113], v[158:161], v[190:193], v[110:113]
	v_mfma_f32_16x16x32_bf16 v[110:113], v[162:165], v[194:197], v[110:113]
	v_mfma_f32_16x16x32_bf16 v[98:101], v[138:141], v[198:201], v[98:101]
	v_mfma_f32_16x16x32_bf16 v[98:101], v[142:145], v[202:205], v[98:101]
	v_mfma_f32_16x16x32_bf16 v[94:97], v[158:161], v[198:201], v[94:97]
	v_mfma_f32_16x16x32_bf16 v[94:97], v[162:165], v[202:205], v[94:97]
	v_mfma_f32_16x16x32_bf16 v[82:85], v[138:141], v[206:209], v[82:85]
	v_mfma_f32_16x16x32_bf16 v[82:85], v[142:145], v[210:213], v[82:85]
	v_mfma_f32_16x16x32_bf16 v[78:81], v[158:161], v[206:209], v[78:81]
	v_mfma_f32_16x16x32_bf16 v[78:81], v[162:165], v[210:213], v[78:81]
	s_setprio 0
	s_setprio 1
	v_mfma_f32_16x16x32_bf16 v[122:125], v[166:169], v[182:185], v[122:125]
	v_mfma_f32_16x16x32_bf16 v[122:125], v[170:173], v[186:189], v[122:125]
	v_mfma_f32_16x16x32_bf16 v[118:121], v[174:177], v[182:185], v[118:121]
	v_mfma_f32_16x16x32_bf16 v[118:121], v[178:181], v[186:189], v[118:121]
	v_mfma_f32_16x16x32_bf16 v[106:109], v[166:169], v[190:193], v[106:109]
	v_mfma_f32_16x16x32_bf16 v[106:109], v[170:173], v[194:197], v[106:109]
	v_mfma_f32_16x16x32_bf16 v[102:105], v[174:177], v[190:193], v[102:105]
	v_mfma_f32_16x16x32_bf16 v[102:105], v[178:181], v[194:197], v[102:105]
	v_mfma_f32_16x16x32_bf16 v[90:93], v[166:169], v[198:201], v[90:93]
	v_mfma_f32_16x16x32_bf16 v[90:93], v[170:173], v[202:205], v[90:93]
	v_mfma_f32_16x16x32_bf16 v[86:89], v[174:177], v[198:201], v[86:89]
	v_mfma_f32_16x16x32_bf16 v[86:89], v[178:181], v[202:205], v[86:89]
	v_mfma_f32_16x16x32_bf16 v[74:77], v[166:169], v[206:209], v[74:77]
	v_mfma_f32_16x16x32_bf16 v[74:77], v[170:173], v[210:213], v[74:77]
	v_mfma_f32_16x16x32_bf16 v[66:69], v[174:177], v[206:209], v[66:69]
	v_mfma_f32_16x16x32_bf16 v[66:69], v[178:181], v[210:213], v[66:69]
	s_setprio 0
	s_barrier
	ds_read_b128 v[182:185], v154 offset:16384
	ds_read_b128 v[186:189], v154 offset:17408
	ds_read_b128 v[190:193], v154 offset:18432
	ds_read_b128 v[194:197], v154 offset:19456
	ds_read_b128 v[198:201], v154 offset:20480
	ds_read_b128 v[202:205], v154 offset:21504
	ds_read_b128 v[206:209], v154 offset:22528
	ds_read_b128 v[210:213], v154 offset:23552
	s_mov_b32 m0, s29
	s_nop 0
	global_load_lds_dwordx4 v146, s[38:39] offset:0
	s_add_u32 s30, s38, 0x80000
	s_mov_b32 m0, s44
	s_nop 0
	global_load_lds_dwordx4 v148, s[38:39] offset:0
	s_addc_u32 s31, s39, 0
	s_mov_b32 m0, s45
	s_nop 0
	global_load_lds_dwordx4 v146, s[30:31] offset:0
	s_nop 0
	s_mov_b32 m0, s46
	s_nop 0
	global_load_lds_dwordx4 v148, s[30:31] offset:0
	s_nop 0
	s_mov_b32 m0, s21
	s_nop 0
	global_load_lds_dwordx4 v1, s[40:41] offset:0
	s_nop 0
	s_mov_b32 m0, s47
	s_nop 0
	global_load_lds_dwordx4 v147, s[40:41] offset:0
	s_waitcnt vmcnt(8)
	s_waitcnt lgkmcnt(0)
	s_barrier
	s_setprio 1
	s_waitcnt lgkmcnt(0)
	v_mfma_f32_16x16x32_bf16 v[70:73], v[138:141], v[182:185], v[70:73]
	v_mfma_f32_16x16x32_bf16 v[70:73], v[142:145], v[186:189], v[70:73]
	v_mfma_f32_16x16x32_bf16 v[62:65], v[158:161], v[182:185], v[62:65]
	v_mfma_f32_16x16x32_bf16 v[62:65], v[162:165], v[186:189], v[62:65]
	v_mfma_f32_16x16x32_bf16 v[50:53], v[138:141], v[190:193], v[50:53]
	v_mfma_f32_16x16x32_bf16 v[50:53], v[142:145], v[194:197], v[50:53]
	v_mfma_f32_16x16x32_bf16 v[46:49], v[158:161], v[190:193], v[46:49]
	v_mfma_f32_16x16x32_bf16 v[46:49], v[162:165], v[194:197], v[46:49]
	v_mfma_f32_16x16x32_bf16 v[34:37], v[138:141], v[198:201], v[34:37]
	v_mfma_f32_16x16x32_bf16 v[34:37], v[142:145], v[202:205], v[34:37]
	v_mfma_f32_16x16x32_bf16 v[30:33], v[158:161], v[198:201], v[30:33]
	v_mfma_f32_16x16x32_bf16 v[30:33], v[162:165], v[202:205], v[30:33]
	v_mfma_f32_16x16x32_bf16 v[18:21], v[138:141], v[206:209], v[18:21]
	v_mfma_f32_16x16x32_bf16 v[18:21], v[142:145], v[210:213], v[18:21]
	v_mfma_f32_16x16x32_bf16 v[14:17], v[158:161], v[206:209], v[14:17]
	v_mfma_f32_16x16x32_bf16 v[14:17], v[162:165], v[210:213], v[14:17]
	s_setprio 0
	s_setprio 1
	v_mfma_f32_16x16x32_bf16 v[58:61], v[166:169], v[182:185], v[58:61]
	v_mfma_f32_16x16x32_bf16 v[54:57], v[174:177], v[182:185], v[54:57]
	v_mfma_f32_16x16x32_bf16 v[42:45], v[166:169], v[190:193], v[42:45]
	v_mfma_f32_16x16x32_bf16 v[38:41], v[174:177], v[190:193], v[38:41]
	v_mfma_f32_16x16x32_bf16 v[26:29], v[166:169], v[198:201], v[26:29]
	v_mfma_f32_16x16x32_bf16 v[22:25], v[174:177], v[198:201], v[22:25]
	v_mfma_f32_16x16x32_bf16 v[10:13], v[166:169], v[206:209], v[10:13]
	v_mfma_f32_16x16x32_bf16 v[4:7], v[174:177], v[206:209], v[6:9]
	v_mfma_f32_16x16x32_bf16 v[58:61], v[170:173], v[186:189], v[58:61]
	v_mfma_f32_16x16x32_bf16 v[54:57], v[178:181], v[186:189], v[54:57]
	v_mfma_f32_16x16x32_bf16 v[42:45], v[170:173], v[194:197], v[42:45]
	v_mfma_f32_16x16x32_bf16 v[38:41], v[178:181], v[194:197], v[38:41]
	v_mfma_f32_16x16x32_bf16 v[26:29], v[170:173], v[202:205], v[26:29]
	v_mfma_f32_16x16x32_bf16 v[22:25], v[178:181], v[202:205], v[22:25]
	v_mfma_f32_16x16x32_bf16 v[10:13], v[170:173], v[210:213], v[10:13]
	v_mfma_f32_16x16x32_bf16 v[4:7], v[178:181], v[210:213], v[4:7]
	s_setprio 0
	s_barrier
; #define PG8_KSETUP() const bool last = (t == nt - 2); const char* a1 = cA + (size_t)(t + 1) * kstep; \
;             const char* a2 = last ? nA : cA + (size_t)(t + 2) * kstep; const char* b2 = last ? nB : cB + (size_t)(t + 2) * kstep; const char* a3 = a2 + kstep; const char* b3 = b2 + kstep; \
;             if (last && has_next) S.a_ready(nxt)
; template <class Epi, class Sched, bool ALIGN_EPI = false, bool SP2 = false>
; __device__ __forceinline__ void gemm_phase(PG8_LAS unsigned char* lds, const Gemm g, const Sched& S, const Epi& E) {
;     ...
;         int t0 = 0;
;         if constexpr (SP2 && Epi::NVM == 16) { if (ui > 0) { const int t = 0; PG8_KSETUP(); PG8_KITER_SP2(24, 24); t0 = 2; } }
;         if constexpr (SP2 && Epi::NVM == 8) { if (ui > 0) { const int t = 0; PG8_KSETUP(); PG8_KITER_SP2(16, 16); t0 = 2; } }
;         for (int t = t0; t < nt; t += 2) {
	ds_read_b128 v[138:141], v155
	ds_read_b128 v[142:145], v155 offset:1024
	ds_read_b128 v[158:161], v155 offset:2048
	ds_read_b128 v[162:165], v155 offset:3072
	ds_read_b128 v[166:169], v156
	ds_read_b128 v[170:173], v156 offset:1024
	ds_read_b128 v[174:177], v156 offset:2048
	ds_read_b128 v[178:181], v156 offset:3072
	ds_read_b128 v[182:185], v154 offset:32768
	ds_read_b128 v[186:189], v154 offset:33792
	ds_read_b128 v[190:193], v154 offset:34816
	ds_read_b128 v[194:197], v154 offset:35840
	ds_read_b128 v[198:201], v154 offset:36864
	ds_read_b128 v[202:205], v154 offset:37888
	ds_read_b128 v[206:209], v154 offset:38912
	ds_read_b128 v[210:213], v154 offset:39936
	s_add_u32 s30, s40, 0x80000
	s_addc_u32 s31, s41, 0
	s_mov_b32 m0, s48
	s_nop 0
	global_load_lds_dwordx4 v1, s[30:31] offset:0
	s_nop 0
	s_mov_b32 m0, s49
	s_nop 0
	global_load_lds_dwordx4 v147, s[30:31] offset:0
	s_waitcnt vmcnt(8)
	s_waitcnt lgkmcnt(0)
	s_barrier
	s_setprio 1
	s_waitcnt lgkmcnt(0)
	v_mfma_f32_16x16x32_bf16 v[130:133], v[138:141], v[182:185], v[130:133]
	v_mfma_f32_16x16x32_bf16 v[130:133], v[142:145], v[186:189], v[130:133]
	v_mfma_f32_16x16x32_bf16 v[126:129], v[158:161], v[182:185], v[126:129]
	v_mfma_f32_16x16x32_bf16 v[126:129], v[162:165], v[186:189], v[126:129]
	v_mfma_f32_16x16x32_bf16 v[114:117], v[138:141], v[190:193], v[114:117]
	v_mfma_f32_16x16x32_bf16 v[114:117], v[142:145], v[194:197], v[114:117]
	v_mfma_f32_16x16x32_bf16 v[110:113], v[158:161], v[190:193], v[110:113]
	v_mfma_f32_16x16x32_bf16 v[110:113], v[162:165], v[194:197], v[110:113]
	v_mfma_f32_16x16x32_bf16 v[98:101], v[138:141], v[198:201], v[98:101]
	v_mfma_f32_16x16x32_bf16 v[98:101], v[142:145], v[202:205], v[98:101]
	v_mfma_f32_16x16x32_bf16 v[94:97], v[158:161], v[198:201], v[94:97]
	v_mfma_f32_16x16x32_bf16 v[94:97], v[162:165], v[202:205], v[94:97]
	v_mfma_f32_16x16x32_bf16 v[82:85], v[138:141], v[206:209], v[82:85]
	v_mfma_f32_16x16x32_bf16 v[82:85], v[142:145], v[210:213], v[82:85]
	v_mfma_f32_16x16x32_bf16 v[78:81], v[158:161], v[206:209], v[78:81]
	v_mfma_f32_16x16x32_bf16 v[78:81], v[162:165], v[210:213], v[78:81]
	s_setprio 0
	s_setprio 1
	v_mfma_f32_16x16x32_bf16 v[122:125], v[166:169], v[182:185], v[122:125]
	v_mfma_f32_16x16x32_bf16 v[122:125], v[170:173], v[186:189], v[122:125]
	v_mfma_f32_16x16x32_bf16 v[118:121], v[174:177], v[182:185], v[118:121]
	v_mfma_f32_16x16x32_bf16 v[118:121], v[178:181], v[186:189], v[118:121]
	v_mfma_f32_16x16x32_bf16 v[106:109], v[166:169], v[190:193], v[106:109]
	v_mfma_f32_16x16x32_bf16 v[106:109], v[170:173], v[194:197], v[106:109]
	v_mfma_f32_16x16x32_bf16 v[102:105], v[174:177], v[190:193], v[102:105]
	v_mfma_f32_16x16x32_bf16 v[102:105], v[178:181], v[194:197], v[102:105]
	v_mfma_f32_16x16x32_bf16 v[90:93], v[166:169], v[198:201], v[90:93]
	v_mfma_f32_16x16x32_bf16 v[90:93], v[170:173], v[202:205], v[90:93]
	v_mfma_f32_16x16x32_bf16 v[86:89], v[174:177], v[198:201], v[86:89]
	v_mfma_f32_16x16x32_bf16 v[86:89], v[178:181], v[202:205], v[86:89]
	v_mfma_f32_16x16x32_bf16 v[74:77], v[166:169], v[206:209], v[74:77]
	v_mfma_f32_16x16x32_bf16 v[74:77], v[170:173], v[210:213], v[74:77]
	v_mfma_f32_16x16x32_bf16 v[66:69], v[174:177], v[206:209], v[66:69]
	v_mfma_f32_16x16x32_bf16 v[66:69], v[178:181], v[210:213], v[66:69]
	s_setprio 0
	s_barrier
	ds_read_b128 v[182:185], v154 offset:49152
	ds_read_b128 v[186:189], v154 offset:50176
	ds_read_b128 v[190:193], v154 offset:51200
	ds_read_b128 v[194:197], v154 offset:52224
	ds_read_b128 v[198:201], v154 offset:53248
	ds_read_b128 v[202:205], v154 offset:54272
	ds_read_b128 v[206:209], v154 offset:55296
	ds_read_b128 v[210:213], v154 offset:56320
	s_add_u32 s30, s38, 0x80
	s_addc_u32 s31, s39, 0
	s_mov_b32 m0, s50
	s_nop 0
	global_load_lds_dwordx4 v146, s[30:31] offset:0
	s_nop 0
	s_mov_b32 m0, s51
	s_nop 0
	global_load_lds_dwordx4 v148, s[30:31] offset:0
	s_add_u32 s30, s38, 0x80080
	s_addc_u32 s31, s39, 0
	s_mov_b32 m0, s54
	s_nop 0
	global_load_lds_dwordx4 v146, s[30:31] offset:0
	s_nop 0
	s_mov_b32 m0, s55
	s_nop 0
	global_load_lds_dwordx4 v148, s[30:31] offset:0
	s_nop 0
	s_mov_b32 m0, s52
	s_nop 0
	global_load_lds_dwordx4 v1, s[36:37] offset:0
	s_nop 0
	s_mov_b32 m0, s53
	s_nop 0
	global_load_lds_dwordx4 v147, s[36:37] offset:0
	s_waitcnt vmcnt(8)
	s_waitcnt lgkmcnt(0)
	s_barrier
	s_setprio 1
	s_waitcnt lgkmcnt(0)
	v_mfma_f32_16x16x32_bf16 v[70:73], v[138:141], v[182:185], v[70:73]
	v_mfma_f32_16x16x32_bf16 v[70:73], v[142:145], v[186:189], v[70:73]
	v_mfma_f32_16x16x32_bf16 v[62:65], v[158:161], v[182:185], v[62:65]
	v_mfma_f32_16x16x32_bf16 v[62:65], v[162:165], v[186:189], v[62:65]
	v_mfma_f32_16x16x32_bf16 v[50:53], v[138:141], v[190:193], v[50:53]
	v_mfma_f32_16x16x32_bf16 v[50:53], v[142:145], v[194:197], v[50:53]
	v_mfma_f32_16x16x32_bf16 v[46:49], v[158:161], v[190:193], v[46:49]
	v_mfma_f32_16x16x32_bf16 v[46:49], v[162:165], v[194:197], v[46:49]
	v_mfma_f32_16x16x32_bf16 v[34:37], v[138:141], v[198:201], v[34:37]
	v_mfma_f32_16x16x32_bf16 v[34:37], v[142:145], v[202:205], v[34:37]
	v_mfma_f32_16x16x32_bf16 v[30:33], v[158:161], v[198:201], v[30:33]
	v_mfma_f32_16x16x32_bf16 v[30:33], v[162:165], v[202:205], v[30:33]
	v_mfma_f32_16x16x32_bf16 v[18:21], v[138:141], v[206:209], v[18:21]
	v_mfma_f32_16x16x32_bf16 v[18:21], v[142:145], v[210:213], v[18:21]
	v_mfma_f32_16x16x32_bf16 v[14:17], v[158:161], v[206:209], v[14:17]
	v_mfma_f32_16x16x32_bf16 v[14:17], v[162:165], v[210:213], v[14:17]
	s_setprio 0
	s_setprio 1
	v_mfma_f32_16x16x32_bf16 v[58:61], v[166:169], v[182:185], v[58:61]
	v_mfma_f32_16x16x32_bf16 v[54:57], v[174:177], v[182:185], v[54:57]
	v_mfma_f32_16x16x32_bf16 v[42:45], v[166:169], v[190:193], v[42:45]
	v_mfma_f32_16x16x32_bf16 v[38:41], v[174:177], v[190:193], v[38:41]
	v_mfma_f32_16x16x32_bf16 v[26:29], v[166:169], v[198:201], v[26:29]
	v_mfma_f32_16x16x32_bf16 v[22:25], v[174:177], v[198:201], v[22:25]
	v_mfma_f32_16x16x32_bf16 v[8:11], v[166:169], v[206:209], v[10:13]
	v_mfma_f32_16x16x32_bf16 v[4:7], v[174:177], v[206:209], v[4:7]
	v_mfma_f32_16x16x32_bf16 v[58:61], v[170:173], v[186:189], v[58:61]
	v_mfma_f32_16x16x32_bf16 v[54:57], v[178:181], v[186:189], v[54:57]
	v_mfma_f32_16x16x32_bf16 v[42:45], v[170:173], v[194:197], v[42:45]
	v_mfma_f32_16x16x32_bf16 v[38:41], v[178:181], v[194:197], v[38:41]
	v_mfma_f32_16x16x32_bf16 v[26:29], v[170:173], v[202:205], v[26:29]
	v_mfma_f32_16x16x32_bf16 v[22:25], v[178:181], v[202:205], v[22:25]
	v_mfma_f32_16x16x32_bf16 v[10:13], v[170:173], v[210:213], v[8:11]
	v_mfma_f32_16x16x32_bf16 v[6:9], v[178:181], v[210:213], v[4:7]
	s_setprio 0
	s_barrier
	s_add_i32 s72, s72, 2
	s_add_u32 s73, s73, 0x100
	s_addc_u32 s74, s74, 0
	s_add_u32 s75, s75, 0x100
	s_addc_u32 s76, s76, 0
	s_cmp_gt_u32 s72, 29
	s_cbranch_scc0 .LBB0_3621
	s_and_b64 vcc, exec, s[14:15]
	s_cbranch_vccz .LBB0_3624
	s_barrier

.LBB0_3701:
	ds_read_b128 v[132:135], v150
	ds_read_b128 v[140:143], v150 offset:1024
	ds_read_b128 v[156:159], v150 offset:2048
	ds_read_b128 v[160:163], v150 offset:3072
	ds_read_b128 v[164:167], v151
	ds_read_b128 v[168:171], v151 offset:1024
	ds_read_b128 v[172:175], v151 offset:2048
	ds_read_b128 v[176:179], v151 offset:3072
	s_cmpk_eq_i32 s22, 0x54
	s_cselect_b32 s20, s4, s57
	s_cselect_b32 s21, s5, s58
	s_cselect_b32 s18, s14, s23
	s_cselect_b32 s19, s15, s56
	s_add_u32 s16, s20, 0x80
	s_addc_u32 s17, s21, 0
	ds_read_b128 v[180:183], v152
	ds_read_b128 v[184:187], v152 offset:1024
	ds_read_b128 v[188:191], v152 offset:2048
	ds_read_b128 v[192:195], v152 offset:3072
	ds_read_b128 v[196:199], v152 offset:4096
	ds_read_b128 v[200:203], v152 offset:5120
	ds_read_b128 v[204:207], v152 offset:6144
	ds_read_b128 v[208:211], v152 offset:7168
	s_add_u32 s30, s57, 0x15ff80
	s_addc_u32 s31, s58, 0
	s_mov_b32 m0, s48
	s_nop 0
	global_load_lds_dwordx4 v144, s[30:31] offset:0
	s_nop 0
	s_mov_b32 m0, s49
	s_nop 0
	global_load_lds_dwordx4 v146, s[30:31] offset:0
	s_waitcnt vmcnt(8)
	s_waitcnt lgkmcnt(0)
	s_barrier
	s_setprio 1
	s_waitcnt lgkmcnt(7)
	s_waitcnt lgkmcnt(5)
	s_waitcnt lgkmcnt(3)
	s_waitcnt lgkmcnt(1)
	s_waitcnt lgkmcnt(0)
	v_mfma_f32_16x16x32_bf16 v[128:131], v[132:135], v[180:183], v[128:131]
	v_mfma_f32_16x16x32_bf16 v[128:131], v[140:143], v[184:187], v[128:131]
	v_mfma_f32_16x16x32_bf16 v[124:127], v[156:159], v[180:183], v[124:127]
	v_mfma_f32_16x16x32_bf16 v[124:127], v[160:163], v[184:187], v[124:127]
	v_mfma_f32_16x16x32_bf16 v[112:115], v[132:135], v[188:191], v[112:115]
	v_mfma_f32_16x16x32_bf16 v[112:115], v[140:143], v[192:195], v[112:115]
	v_mfma_f32_16x16x32_bf16 v[108:111], v[156:159], v[188:191], v[108:111]
	v_mfma_f32_16x16x32_bf16 v[108:111], v[160:163], v[192:195], v[108:111]
	v_mfma_f32_16x16x32_bf16 v[96:99], v[132:135], v[196:199], v[96:99]
	v_mfma_f32_16x16x32_bf16 v[96:99], v[140:143], v[200:203], v[96:99]
	v_mfma_f32_16x16x32_bf16 v[92:95], v[156:159], v[196:199], v[92:95]
	v_mfma_f32_16x16x32_bf16 v[92:95], v[160:163], v[200:203], v[92:95]
	v_mfma_f32_16x16x32_bf16 v[80:83], v[132:135], v[204:207], v[80:83]
	v_mfma_f32_16x16x32_bf16 v[80:83], v[140:143], v[208:211], v[80:83]
	v_mfma_f32_16x16x32_bf16 v[76:79], v[156:159], v[204:207], v[76:79]
	v_mfma_f32_16x16x32_bf16 v[76:79], v[160:163], v[208:211], v[76:79]
	s_setprio 0
	s_setprio 1
	v_mfma_f32_16x16x32_bf16 v[120:123], v[164:167], v[180:183], v[120:123]
	v_mfma_f32_16x16x32_bf16 v[120:123], v[168:171], v[184:187], v[120:123]
	v_mfma_f32_16x16x32_bf16 v[116:119], v[172:175], v[180:183], v[116:119]
	v_mfma_f32_16x16x32_bf16 v[116:119], v[176:179], v[184:187], v[116:119]
	v_mfma_f32_16x16x32_bf16 v[104:107], v[164:167], v[188:191], v[104:107]
	v_mfma_f32_16x16x32_bf16 v[104:107], v[168:171], v[192:195], v[104:107]
	v_mfma_f32_16x16x32_bf16 v[100:103], v[172:175], v[188:191], v[100:103]
	v_mfma_f32_16x16x32_bf16 v[100:103], v[176:179], v[192:195], v[100:103]
	v_mfma_f32_16x16x32_bf16 v[88:91], v[164:167], v[196:199], v[88:91]
	v_mfma_f32_16x16x32_bf16 v[88:91], v[168:171], v[200:203], v[88:91]
	v_mfma_f32_16x16x32_bf16 v[84:87], v[172:175], v[196:199], v[84:87]
	v_mfma_f32_16x16x32_bf16 v[84:87], v[176:179], v[200:203], v[84:87]
	v_mfma_f32_16x16x32_bf16 v[72:75], v[164:167], v[204:207], v[72:75]
	v_mfma_f32_16x16x32_bf16 v[72:75], v[168:171], v[208:211], v[72:75]
	v_mfma_f32_16x16x32_bf16 v[68:71], v[172:175], v[204:207], v[68:71]
	v_mfma_f32_16x16x32_bf16 v[68:71], v[176:179], v[208:211], v[68:71]
	s_setprio 0
	s_barrier
	ds_read_b128 v[180:183], v152 offset:16384
	ds_read_b128 v[184:187], v152 offset:17408
	ds_read_b128 v[188:191], v152 offset:18432
	ds_read_b128 v[192:195], v152 offset:19456
	ds_read_b128 v[196:199], v152 offset:20480
	ds_read_b128 v[200:203], v152 offset:21504
	ds_read_b128 v[204:207], v152 offset:22528
	ds_read_b128 v[208:211], v152 offset:23552
	s_mov_b32 m0, s34
	s_nop 0
	global_load_lds_dwordx4 v145, s[18:19] offset:0
	s_add_u32 s30, s18, 0x160000
	s_mov_b32 m0, s36
	s_nop 0
	global_load_lds_dwordx4 v147, s[18:19] offset:0
	s_addc_u32 s31, s19, 0
	s_mov_b32 m0, s37
	s_nop 0
	global_load_lds_dwordx4 v145, s[30:31] offset:0
	s_nop 0
	s_mov_b32 m0, s38
	s_nop 0
	global_load_lds_dwordx4 v147, s[30:31] offset:0
	s_nop 0
	s_mov_b32 m0, s28
	s_nop 0
	global_load_lds_dwordx4 v144, s[20:21] offset:0
	s_nop 0
	s_mov_b32 m0, s39
	s_nop 0
	global_load_lds_dwordx4 v146, s[20:21] offset:0
	s_waitcnt vmcnt(8)
	s_waitcnt lgkmcnt(0)
	s_barrier
	s_setprio 1
	s_waitcnt lgkmcnt(7)
	s_waitcnt lgkmcnt(5)
	s_waitcnt lgkmcnt(3)
	s_waitcnt lgkmcnt(1)
	s_waitcnt lgkmcnt(0)
	v_mfma_f32_16x16x32_bf16 v[64:67], v[132:135], v[180:183], v[64:67]
	v_mfma_f32_16x16x32_bf16 v[64:67], v[140:143], v[184:187], v[64:67]
	v_mfma_f32_16x16x32_bf16 v[60:63], v[156:159], v[180:183], v[60:63]
	v_mfma_f32_16x16x32_bf16 v[60:63], v[160:163], v[184:187], v[60:63]
	v_mfma_f32_16x16x32_bf16 v[48:51], v[132:135], v[188:191], v[48:51]
	v_mfma_f32_16x16x32_bf16 v[48:51], v[140:143], v[192:195], v[48:51]
	v_mfma_f32_16x16x32_bf16 v[44:47], v[156:159], v[188:191], v[44:47]
	v_mfma_f32_16x16x32_bf16 v[44:47], v[160:163], v[192:195], v[44:47]
	v_mfma_f32_16x16x32_bf16 v[32:35], v[132:135], v[196:199], v[32:35]
	v_mfma_f32_16x16x32_bf16 v[32:35], v[140:143], v[200:203], v[32:35]
	v_mfma_f32_16x16x32_bf16 v[28:31], v[156:159], v[196:199], v[28:31]
	v_mfma_f32_16x16x32_bf16 v[28:31], v[160:163], v[200:203], v[28:31]
	v_mfma_f32_16x16x32_bf16 v[16:19], v[132:135], v[204:207], v[16:19]
	v_mfma_f32_16x16x32_bf16 v[16:19], v[140:143], v[208:211], v[16:19]
	v_mfma_f32_16x16x32_bf16 v[12:15], v[156:159], v[204:207], v[12:15]
	v_mfma_f32_16x16x32_bf16 v[12:15], v[160:163], v[208:211], v[12:15]
	s_setprio 0
	s_setprio 1
	v_mfma_f32_16x16x32_bf16 v[56:59], v[164:167], v[180:183], v[56:59]
	v_mfma_f32_16x16x32_bf16 v[52:55], v[172:175], v[180:183], v[52:55]
	v_mfma_f32_16x16x32_bf16 v[40:43], v[164:167], v[188:191], v[40:43]
	v_mfma_f32_16x16x32_bf16 v[36:39], v[172:175], v[188:191], v[36:39]
	v_mfma_f32_16x16x32_bf16 v[24:27], v[164:167], v[196:199], v[24:27]
	v_mfma_f32_16x16x32_bf16 v[20:23], v[172:175], v[196:199], v[20:23]
	v_mfma_f32_16x16x32_bf16 v[8:11], v[164:167], v[204:207], v[8:11]
	v_mfma_f32_16x16x32_bf16 v[2:5], v[172:175], v[204:207], v[4:7]
	v_mfma_f32_16x16x32_bf16 v[56:59], v[168:171], v[184:187], v[56:59]
	v_mfma_f32_16x16x32_bf16 v[52:55], v[176:179], v[184:187], v[52:55]
	v_mfma_f32_16x16x32_bf16 v[40:43], v[168:171], v[192:195], v[40:43]
	v_mfma_f32_16x16x32_bf16 v[36:39], v[176:179], v[192:195], v[36:39]
	v_mfma_f32_16x16x32_bf16 v[24:27], v[168:171], v[200:203], v[24:27]
	v_mfma_f32_16x16x32_bf16 v[20:23], v[176:179], v[200:203], v[20:23]
	v_mfma_f32_16x16x32_bf16 v[8:11], v[168:171], v[208:211], v[8:11]
	v_mfma_f32_16x16x32_bf16 v[2:5], v[176:179], v[208:211], v[2:5]
	s_setprio 0
	s_barrier
	ds_read_b128 v[132:135], v153
	ds_read_b128 v[140:143], v153 offset:1024
	ds_read_b128 v[156:159], v153 offset:2048
	ds_read_b128 v[160:163], v153 offset:3072
	ds_read_b128 v[164:167], v154
	ds_read_b128 v[168:171], v154 offset:1024
	ds_read_b128 v[172:175], v154 offset:2048
	ds_read_b128 v[176:179], v154 offset:3072
	ds_read_b128 v[180:183], v152 offset:32768
	ds_read_b128 v[184:187], v152 offset:33792
	ds_read_b128 v[188:191], v152 offset:34816
	ds_read_b128 v[192:195], v152 offset:35840
	ds_read_b128 v[196:199], v152 offset:36864
	ds_read_b128 v[200:203], v152 offset:37888
	ds_read_b128 v[204:207], v152 offset:38912
	ds_read_b128 v[208:211], v152 offset:39936
	s_add_u32 s20, s20, 0x160000
	s_addc_u32 s21, s21, 0
	s_mov_b32 m0, s40
	s_nop 0
	global_load_lds_dwordx4 v144, s[20:21] offset:0
	s_nop 0
	s_mov_b32 m0, s41
	s_nop 0
	global_load_lds_dwordx4 v146, s[20:21] offset:0
	s_waitcnt vmcnt(8)
	s_waitcnt lgkmcnt(0)
	s_barrier
	s_setprio 1
	s_waitcnt lgkmcnt(7)
	s_waitcnt lgkmcnt(5)
	s_waitcnt lgkmcnt(3)
	s_waitcnt lgkmcnt(1)
	s_waitcnt lgkmcnt(0)
	v_mfma_f32_16x16x32_bf16 v[128:131], v[132:135], v[180:183], v[128:131]
	v_mfma_f32_16x16x32_bf16 v[128:131], v[140:143], v[184:187], v[128:131]
	v_mfma_f32_16x16x32_bf16 v[124:127], v[156:159], v[180:183], v[124:127]
	v_mfma_f32_16x16x32_bf16 v[124:127], v[160:163], v[184:187], v[124:127]
	v_mfma_f32_16x16x32_bf16 v[112:115], v[132:135], v[188:191], v[112:115]
	v_mfma_f32_16x16x32_bf16 v[112:115], v[140:143], v[192:195], v[112:115]
	v_mfma_f32_16x16x32_bf16 v[108:111], v[156:159], v[188:191], v[108:111]
	v_mfma_f32_16x16x32_bf16 v[108:111], v[160:163], v[192:195], v[108:111]
	v_mfma_f32_16x16x32_bf16 v[96:99], v[132:135], v[196:199], v[96:99]
	v_mfma_f32_16x16x32_bf16 v[96:99], v[140:143], v[200:203], v[96:99]
	v_mfma_f32_16x16x32_bf16 v[92:95], v[156:159], v[196:199], v[92:95]
	v_mfma_f32_16x16x32_bf16 v[92:95], v[160:163], v[200:203], v[92:95]
	v_mfma_f32_16x16x32_bf16 v[80:83], v[132:135], v[204:207], v[80:83]
	v_mfma_f32_16x16x32_bf16 v[80:83], v[140:143], v[208:211], v[80:83]
	v_mfma_f32_16x16x32_bf16 v[76:79], v[156:159], v[204:207], v[76:79]
	v_mfma_f32_16x16x32_bf16 v[76:79], v[160:163], v[208:211], v[76:79]
	s_setprio 0
	s_setprio 1
	v_mfma_f32_16x16x32_bf16 v[120:123], v[164:167], v[180:183], v[120:123]
	v_mfma_f32_16x16x32_bf16 v[120:123], v[168:171], v[184:187], v[120:123]
	v_mfma_f32_16x16x32_bf16 v[116:119], v[172:175], v[180:183], v[116:119]
	v_mfma_f32_16x16x32_bf16 v[116:119], v[176:179], v[184:187], v[116:119]
	v_mfma_f32_16x16x32_bf16 v[104:107], v[164:167], v[188:191], v[104:107]
	v_mfma_f32_16x16x32_bf16 v[104:107], v[168:171], v[192:195], v[104:107]
	v_mfma_f32_16x16x32_bf16 v[100:103], v[172:175], v[188:191], v[100:103]
	v_mfma_f32_16x16x32_bf16 v[100:103], v[176:179], v[192:195], v[100:103]
	v_mfma_f32_16x16x32_bf16 v[88:91], v[164:167], v[196:199], v[88:91]
	v_mfma_f32_16x16x32_bf16 v[88:91], v[168:171], v[200:203], v[88:91]
	v_mfma_f32_16x16x32_bf16 v[84:87], v[172:175], v[196:199], v[84:87]
	v_mfma_f32_16x16x32_bf16 v[84:87], v[176:179], v[200:203], v[84:87]
	v_mfma_f32_16x16x32_bf16 v[72:75], v[164:167], v[204:207], v[72:75]
	v_mfma_f32_16x16x32_bf16 v[72:75], v[168:171], v[208:211], v[72:75]
	v_mfma_f32_16x16x32_bf16 v[68:71], v[172:175], v[204:207], v[68:71]
	v_mfma_f32_16x16x32_bf16 v[68:71], v[176:179], v[208:211], v[68:71]
	s_setprio 0
	s_barrier
; #define PG8_KSETUP() const bool last = (t == nt - 2); const char* a1 = cA + (size_t)(t + 1) * kstep; \
;             const char* a2 = last ? nA : cA + (size_t)(t + 2) * kstep; const char* b2 = last ? nB : cB + (size_t)(t + 2) * kstep; const char* a3 = a2 + kstep; const char* b3 = b2 + kstep; \
;             if (last && has_next) S.a_ready(nxt)
; template <class Epi, class Sched, bool ALIGN_EPI = false, bool SP2 = false>
; __device__ __forceinline__ void gemm_phase(PG8_LAS unsigned char* lds, const Gemm g, const Sched& S, const Epi& E) {
;     ...
;         int t0 = 0;
;         if constexpr (SP2 && Epi::NVM == 16) { if (ui > 0) { const int t = 0; PG8_KSETUP(); PG8_KITER_SP2(24, 24); t0 = 2; } }
;         if constexpr (SP2 && Epi::NVM == 8) { if (ui > 0) { const int t = 0; PG8_KSETUP(); PG8_KITER_SP2(16, 16); t0 = 2; } }
;         for (int t = t0; t < nt; t += 2) {
	ds_read_b128 v[180:183], v152 offset:49152
	ds_read_b128 v[184:187], v152 offset:50176
	ds_read_b128 v[188:191], v152 offset:51200
	ds_read_b128 v[192:195], v152 offset:52224
	ds_read_b128 v[196:199], v152 offset:53248
	ds_read_b128 v[200:203], v152 offset:54272
	ds_read_b128 v[204:207], v152 offset:55296
	ds_read_b128 v[208:211], v152 offset:56320
	s_add_u32 s20, s18, 0x80
	s_addc_u32 s21, s19, 0
	s_mov_b32 m0, s42
	s_nop 0
	global_load_lds_dwordx4 v145, s[20:21] offset:0
	s_add_u32 s18, s18, 0x160080
	s_mov_b32 m0, s43
	s_nop 0
	global_load_lds_dwordx4 v147, s[20:21] offset:0
	s_addc_u32 s19, s19, 0
	s_mov_b32 m0, s46
	s_nop 0
	global_load_lds_dwordx4 v145, s[18:19] offset:0
	s_nop 0
	s_mov_b32 m0, s47
	s_nop 0
	global_load_lds_dwordx4 v147, s[18:19] offset:0
	s_nop 0
	s_mov_b32 m0, s44
	s_nop 0
	global_load_lds_dwordx4 v144, s[16:17] offset:0
	s_nop 0
	s_mov_b32 m0, s45
	s_nop 0
	global_load_lds_dwordx4 v146, s[16:17] offset:0
	s_waitcnt vmcnt(8)
	s_waitcnt lgkmcnt(0)
	s_barrier
	s_setprio 1
	s_waitcnt lgkmcnt(7)
	s_waitcnt lgkmcnt(5)
	s_waitcnt lgkmcnt(3)
	s_waitcnt lgkmcnt(1)
	s_waitcnt lgkmcnt(0)
	v_mfma_f32_16x16x32_bf16 v[64:67], v[132:135], v[180:183], v[64:67]
	v_mfma_f32_16x16x32_bf16 v[64:67], v[140:143], v[184:187], v[64:67]
	v_mfma_f32_16x16x32_bf16 v[60:63], v[156:159], v[180:183], v[60:63]
	v_mfma_f32_16x16x32_bf16 v[60:63], v[160:163], v[184:187], v[60:63]
	v_mfma_f32_16x16x32_bf16 v[48:51], v[132:135], v[188:191], v[48:51]
	v_mfma_f32_16x16x32_bf16 v[48:51], v[140:143], v[192:195], v[48:51]
	v_mfma_f32_16x16x32_bf16 v[44:47], v[156:159], v[188:191], v[44:47]
	v_mfma_f32_16x16x32_bf16 v[44:47], v[160:163], v[192:195], v[44:47]
	v_mfma_f32_16x16x32_bf16 v[32:35], v[132:135], v[196:199], v[32:35]
	v_mfma_f32_16x16x32_bf16 v[32:35], v[140:143], v[200:203], v[32:35]
	v_mfma_f32_16x16x32_bf16 v[28:31], v[156:159], v[196:199], v[28:31]
	v_mfma_f32_16x16x32_bf16 v[28:31], v[160:163], v[200:203], v[28:31]
	v_mfma_f32_16x16x32_bf16 v[16:19], v[132:135], v[204:207], v[16:19]
	v_mfma_f32_16x16x32_bf16 v[16:19], v[140:143], v[208:211], v[16:19]
	v_mfma_f32_16x16x32_bf16 v[12:15], v[156:159], v[204:207], v[12:15]
	v_mfma_f32_16x16x32_bf16 v[12:15], v[160:163], v[208:211], v[12:15]
	s_setprio 0
	s_setprio 1
	v_mfma_f32_16x16x32_bf16 v[56:59], v[164:167], v[180:183], v[56:59]
	v_mfma_f32_16x16x32_bf16 v[52:55], v[172:175], v[180:183], v[52:55]
	v_mfma_f32_16x16x32_bf16 v[40:43], v[164:167], v[188:191], v[40:43]
	v_mfma_f32_16x16x32_bf16 v[36:39], v[172:175], v[188:191], v[36:39]
	v_mfma_f32_16x16x32_bf16 v[24:27], v[164:167], v[196:199], v[24:27]
	v_mfma_f32_16x16x32_bf16 v[20:23], v[172:175], v[196:199], v[20:23]
	v_mfma_f32_16x16x32_bf16 v[6:9], v[164:167], v[204:207], v[8:11]
	v_mfma_f32_16x16x32_bf16 v[2:5], v[172:175], v[204:207], v[2:5]
	v_mfma_f32_16x16x32_bf16 v[56:59], v[168:171], v[184:187], v[56:59]
	v_mfma_f32_16x16x32_bf16 v[52:55], v[176:179], v[184:187], v[52:55]
	v_mfma_f32_16x16x32_bf16 v[40:43], v[168:171], v[192:195], v[40:43]
	v_mfma_f32_16x16x32_bf16 v[36:39], v[176:179], v[192:195], v[36:39]
	v_mfma_f32_16x16x32_bf16 v[24:27], v[168:171], v[200:203], v[24:27]
	v_mfma_f32_16x16x32_bf16 v[20:23], v[176:179], v[200:203], v[20:23]
	v_mfma_f32_16x16x32_bf16 v[8:11], v[168:171], v[208:211], v[6:9]
	v_mfma_f32_16x16x32_bf16 v[4:7], v[176:179], v[208:211], v[2:5]
	s_setprio 0
	s_barrier
	s_add_i32 s22, s22, 2
	s_add_u32 s23, s23, 0x100
	s_addc_u32 s56, s56, 0
	s_add_u32 s57, s57, 0x100
	s_addc_u32 s58, s58, 0
	s_cmpk_gt_u32 s22, 0x55
	s_cbranch_scc0 .LBB0_3701
	s_and_b64 vcc, exec, s[12:13]
	s_cbranch_vccz .LBB0_3704
	s_barrier
